# GEMM mainloops and prologues: LDS-DMA addressed by SGPR base + 32-bit lane offset (82 sites, no immediate offsets), on top of A DMA restructure
# speedup vs baseline: 1.0040x; 1.0040x over previous
; #define PG8_STAGE(bufoff, gbase, voff) do { _Pragma("unroll") for (int _i = 0; _i < 2; ++_i) \
;         __builtin_amdgcn_global_load_lds((const unsigned*)((const char*)(gbase) + (voff)[_i]), (PG8_LAS unsigned*)(lds + (bufoff) + ldsw + _i * 8192), 16, 0, 0); } while (0)
; #define PG8_WAIT_V(n) asm volatile("s_waitcnt vmcnt(" #n ")" ::: "memory")
; #define PG8_BAR __builtin_amdgcn_s_barrier()
; template <class Epi, class Sched, bool ALIGN_EPI = false, bool SP2 = false>
; __device__ __forceinline__ void gemm_phase(PG8_LAS unsigned char* lds, const Gemm g, const Sched& S, const Epi& E) {
;     int tid_ = threadIdx.x; asm volatile("" : "+v"(tid_)); const int tid = tid_, wid = __builtin_amdgcn_readfirstlane(tid >> 6), lane = tid & 63, wr = wid >> 2, wc = wid & 3, fr = lane & 15, fq = lane >> 4;
;     const int K = g.K, nt = K / BK;
;     unsigned voffA[2], voffB[2];
; #pragma unroll
;     for (int i = 0; i < 2; ++i) { int R, C; stage_rc(tid * 16 + i * 8192, R, C); const int Rb = Epi::PERM ? ((R & ~31) + perm32(R & 31)) : R;
;         voffA[i] = (unsigned)(R * g.lda + C) * 2u; voffB[i] = (unsigned)(Rb * g.ldb + C) * 2u; }
;     const size_t kstep = (size_t)(BK * 2);
;     const size_t hA = (size_t)HALF * g.lda * 2, hB = (size_t)HALF * g.ldb * 2;
;     const size_t tA = 2 * hA, tB = 2 * hB;
;     const unsigned ldsw = (unsigned)wid * 1024u;
;     const int aoff = lds_byte(wr * 64 + fr, fq * 8), boff = lds_byte(wc * 32 + fr, fq * 8);
;     ...
;     if constexpr (SP2) {
;         PG8_STAGE(PG8_SB(0, 0), cB, voffB); PG8_STAGE(PG8_SB(0, 1), cB + hB, voffB); PG8_STAGE(PG8_SA(0, 0), cA, voffA); PG8_STAGE(PG8_SA(0, 1), cA + hA, voffA);
;         if (wr == 1) PG8_BAR;
;         PG8_WAIT_V(2); PG8_BAR;
;         PG8_STAGE(PG8_SB(1, 0), cB + kstep, voffB); PG8_STAGE(PG8_SA(1, 0), cA + kstep, voffA); PG8_STAGE(PG8_SB(1, 1), cB + hB + kstep, voffB);
;         PG8_WAIT_V(6); PG8_BAR;
.LBB0_187:
	v_readlane_b32 s18, v254, 9
	v_mov_b32_e32 v133, v173
	v_readlane_b32 s19, v254, 10
	v_mov_b32_e32 v129, v173
	v_readlane_b32 s14, v254, 5
	v_lshl_add_u64 v[8:9], s[18:19], 0, v[132:133]
	v_lshl_add_u64 v[10:11], s[18:19], 0, v[128:129]
	v_mov_b32_e32 v135, v173
	v_readlane_b32 s15, v254, 6
	s_add_i32 m0, s47, 0x18000
	v_lshl_add_u64 v[8:9], v[8:9], 0, s[76:77]
	v_lshl_add_u64 v[12:13], s[14:15], 0, v[134:135]
	v_mov_b32_e32 v131, v173
	s_waitcnt vmcnt(2)
	s_barrier
	global_load_lds_dwordx4 v[8:9], off
	v_lshl_add_u64 v[8:9], v[10:11], 0, s[76:77]
	s_add_i32 m0, s47, 0x1a000
	s_add_i32 s97, s47, 0x8000
	v_lshl_add_u64 v[14:15], s[14:15], 0, v[130:131]
	global_load_lds_dwordx4 v[8:9], off
	v_lshl_add_u64 v[8:9], v[12:13], 0, s[76:77]
	s_mov_b32 m0, s97
	s_add_i32 s90, s47, 0xa000
	v_readlane_b32 s6, v254, 11
	global_load_lds_dwordx4 v[8:9], off
	v_lshl_add_u64 v[8:9], v[14:15], 0, s[76:77]
	s_mov_b32 m0, s90
	v_readlane_b32 s7, v254, 12
	global_load_lds_dwordx4 v[8:9], off
	s_add_i32 m0, s47, 0x1c000
	s_nop 0
	s_nop 1
	global_load_lds_dwordx4 v132, s[6:7]
	s_add_i32 m0, s47, 0x1e000
	v_and_b32_e32 v7, 15, v2
	global_load_lds_dwordx4 v128, s[6:7]
	v_bfe_u32 v8, v2, 4, 2
	v_lshlrev_b32_e32 v9, 4, v8
	v_lshlrev_b32_e32 v2, 2, v2
	s_lshl_b32 s1, s1, 5
	v_lshl_or_b32 v9, v7, 6, v9
	s_lshl_b32 s6, s8, 13
	v_and_b32_e32 v2, 32, v2
	s_and_b32 s1, s1, 0x60
	v_bitop3_b32 v10, v9, s6, v2 bitop3:0xde
	s_lshl_b32 s6, s1, 7
	v_bitop3_b32 v148, v9, s6, v2 bitop3:0xde
	v_lshlrev_b32_e32 v2, 14, v5
	v_and_b32_e32 v2, 0xffff8000, v2
	v_lshl_add_u32 v2, v4, 11, v2
	v_and_b32_e32 v4, 1, v5
	v_lshl_or_b32 v2, v4, 6, v2
	v_lshl_add_u32 v138, v6, 1, v2
	v_lshlrev_b32_e32 v2, 14, v0
	v_and_b32_e32 v2, 0xffff8000, v2
	s_waitcnt vmcnt(6)
	s_cmpk_lt_u32 s0, 0x100
	v_lshl_or_b32 v149, v8, 3, s1
	v_lshl_add_u32 v1, v1, 11, v2
	v_and_b32_e32 v0, 1, v0
	v_readlane_b32 s0, v254, 1
	v_lshl_or_b32 v137, s8, 6, v7
	s_cselect_b64 s[6:7], -1, 0
	s_lshl_b32 s8, s8, 2
	v_lshl_or_b32 v0, v0, 6, v1
	v_readlane_b32 s1, v254, 2
	s_mov_b32 s91, 0
	v_cmp_eq_u32_e64 s[40:41], 0, v8
	v_lshlrev_b32_e32 v136, 10, v7
	s_ashr_i32 s9, s8, 31
	v_or_b32_e32 v150, 16, v137
	v_or_b32_e32 v151, 32, v137
	v_or_b32_e32 v152, 48, v137
	v_add_u32_e32 v153, 0x80, v137
	v_add_u32_e32 v154, 0x90, v137
	v_add_u32_e32 v155, 0xa0, v137
	v_add_u32_e32 v156, 0xb0, v137
	v_mov_b32_e32 v139, v173
	v_lshl_add_u32 v140, v3, 1, v0
	v_mov_b32_e32 v141, v173
	v_add_u32_e32 v157, 0, v10
	v_readlane_b32 s44, v253, 22
	s_mov_b32 s95, s0
	s_mov_b64 s[0:1], s[14:15]
	s_movk_i32 s53, 0x121
	s_mov_b32 s54, 0x30000
	s_mov_b32 s55, 0x20000
	s_mov_b32 s56, 0x10000
	s_mov_b32 s57, 0x18000
	s_mov_b32 s60, 0x8000
	s_barrier
	s_branch .LBB0_190

; #define PG8_STAGE(bufoff, gbase, voff) do { _Pragma("unroll") for (int _i = 0; _i < 2; ++_i) \
;         __builtin_amdgcn_global_load_lds((const unsigned*)((const char*)(gbase) + (voff)[_i]), (PG8_LAS unsigned*)(lds + (bufoff) + ldsw + _i * 8192), 16, 0, 0); } while (0)
; #define PG8_LDA(dst, b, h) do { _Pragma("unroll") for (int m = 0; m < 4; ++m) _Pragma("unroll") for (int k = 0; k < 2; ++k) dst[m][k] = *(const PG8_LAS bf16x8*)(lds + PG8_SA(b, h) + aoff + m * 2048 + k * 1024); } while (0)
; #define PG8_LDB(dst, b, h) do { _Pragma("unroll") for (int n = 0; n < 2; ++n) _Pragma("unroll") for (int k = 0; k < 2; ++k) dst[n][k] = *(const PG8_LAS bf16x8*)(lds + PG8_SB(b, h) + boff + n * 2048 + k * 1024); } while (0)
; #define PG8_MMA(ai, bj, At, Bt) do { __builtin_amdgcn_s_setprio(1); _Pragma("unroll") for (int m = 0; m < 4; ++m) _Pragma("unroll") for (int n = 0; n < 2; ++n) _Pragma("unroll") for (int k = 0; k < 2; ++k) \
;         acc[ai][bj][m][n] = __builtin_amdgcn_mfma_f32_16x16x32_bf16(Bt[n][k], At[m][k], acc[ai][bj][m][n], 0, 0, 0); __builtin_amdgcn_s_setprio(0); } while (0)
; #define PG8_WAIT_V(n) asm volatile("s_waitcnt vmcnt(" #n ")" ::: "memory")
; #define PG8_WAIT_L(n) asm volatile("s_waitcnt lgkmcnt(" #n ")" ::: "memory")
; template <class Epi, class Sched, bool ALIGN_EPI = false, bool SP2 = false>
; __device__ __forceinline__ void gemm_phase(PG8_LAS unsigned char* lds, const Gemm g, const Sched& S, const Epi& E) {
;     ...
;         for (int t = 0; t < nt; t += 2) {
;             const bool last = (t == nt - 2);
;             const char* a1 = cA + (size_t)(t + 1) * kstep;
;             const char* a2 = last ? nA : cA + (size_t)(t + 2) * kstep; const char* b2 = last ? nB : cB + (size_t)(t + 2) * kstep;
;             const char* a3 = a2 + kstep; const char* b3 = b2 + kstep;
;             if (last && has_next) S.a_ready(nxt);
;             if constexpr (SP2) {
;             PG8_LDB(B0, 0, 0); PG8_LDB(B1, 0, 1); PG8_SCHED; PG8_LDA(At, 0, 0); PG8_STAGE(PG8_SA(1, 1), a1 + hA, voffA);
;             PG8_WAIT_V(8); PG8_WAIT_L(0); PG8_BAR; PG8_MMA(0, 0, At, B0); PG8_MMA(0, 1, At, B1); PG8_BAR; PG8_SCHED;
;             PG8_LDA(At, 0, 1); PG8_STAGE(PG8_SB(0, 0), b2, voffB); PG8_STAGE(PG8_SB(0, 1), b2 + hB, voffB); PG8_STAGE(PG8_SA(0, 0), a2, voffA);
;             PG8_WAIT_V(8); PG8_WAIT_L(0); PG8_BAR; PG8_MMA(1, 0, At, B0); PG8_MMA(1, 1, At, B1); PG8_BAR; PG8_SCHED;
.LBB0_193:
	s_add_u32 s18, s0, 0xfffc0080
	s_addc_u32 s19, s1, -1
	s_add_i32 s34, 0, 0x10000
	s_cmp_eq_u32 s75, 12
	s_cselect_b32 s31, s13, s19
	s_cselect_b32 s30, s45, s18
	v_add_u32_e32 v146, s34, v148
	s_cselect_b32 s19, s11, s74
	s_cselect_b32 s18, s50, s51
	s_add_i32 s52, 0, 0x14000
	ds_read_b128 v[142:145], v146
	ds_read_b128 v[158:161], v146 offset:1024
	ds_read_b128 v[162:165], v146 offset:2048
	ds_read_b128 v[166:169], v146 offset:3072
	v_add_u32_e32 v146, s52, v148
	ds_read_b128 v[184:187], v146
	ds_read_b128 v[188:191], v146 offset:1024
	ds_read_b128 v[200:203], v146 offset:2048
	ds_read_b128 v[204:207], v146 offset:3072
	s_add_i32 m0, s47, 0xc000
	ds_read_b128 v[208:211], v157
	ds_read_b128 v[212:215], v157 offset:1024
	ds_read_b128 v[216:219], v157 offset:2048
	ds_read_b128 v[220:223], v157 offset:3072
	ds_read_b128 v[224:227], v157 offset:4096
	ds_read_b128 v[228:231], v157 offset:5120
	ds_read_b128 v[232:235], v157 offset:6144
	ds_read_b128 v[236:239], v157 offset:7168
	global_load_lds_dwordx4 v138, s[0:1]
	s_add_i32 m0, s47, 0xe000
	s_nop 0
	global_load_lds_dwordx4 v140, s[0:1]
	s_waitcnt vmcnt(8)
	s_waitcnt lgkmcnt(0)
	s_barrier
	s_setprio 1
	s_waitcnt lgkmcnt(0)
	v_mfma_f32_16x16x32_bf16 v[124:127], v[142:145], v[208:211], v[124:127]
	v_mfma_f32_16x16x32_bf16 v[108:111], v[162:165], v[208:211], v[108:111]
	v_mfma_f32_16x16x32_bf16 v[120:123], v[142:145], v[216:219], v[120:123]
	v_mfma_f32_16x16x32_bf16 v[104:107], v[162:165], v[216:219], v[104:107]
	v_mfma_f32_16x16x32_bf16 v[116:119], v[142:145], v[224:227], v[116:119]
	v_mfma_f32_16x16x32_bf16 v[100:103], v[162:165], v[224:227], v[100:103]
	v_mfma_f32_16x16x32_bf16 v[112:115], v[142:145], v[232:235], v[112:115]
	v_mfma_f32_16x16x32_bf16 v[96:99], v[162:165], v[232:235], v[96:99]
	v_mfma_f32_16x16x32_bf16 v[124:127], v[158:161], v[212:215], v[124:127]
	v_mfma_f32_16x16x32_bf16 v[108:111], v[166:169], v[212:215], v[108:111]
	v_mfma_f32_16x16x32_bf16 v[120:123], v[158:161], v[220:223], v[120:123]
	v_mfma_f32_16x16x32_bf16 v[104:107], v[166:169], v[220:223], v[104:107]
	v_mfma_f32_16x16x32_bf16 v[116:119], v[158:161], v[228:231], v[116:119]
	v_mfma_f32_16x16x32_bf16 v[100:103], v[166:169], v[228:231], v[100:103]
	v_mfma_f32_16x16x32_bf16 v[112:115], v[158:161], v[236:239], v[112:115]
	v_mfma_f32_16x16x32_bf16 v[96:99], v[166:169], v[236:239], v[96:99]
	s_setprio 0
	s_setprio 1
	v_mfma_f32_16x16x32_bf16 v[60:63], v[184:187], v[208:211], v[60:63]
	v_mfma_f32_16x16x32_bf16 v[44:47], v[200:203], v[208:211], v[44:47]
	v_mfma_f32_16x16x32_bf16 v[56:59], v[184:187], v[216:219], v[56:59]
	v_mfma_f32_16x16x32_bf16 v[40:43], v[200:203], v[216:219], v[40:43]
	v_mfma_f32_16x16x32_bf16 v[52:55], v[184:187], v[224:227], v[52:55]
	v_mfma_f32_16x16x32_bf16 v[36:39], v[200:203], v[224:227], v[36:39]
	v_mfma_f32_16x16x32_bf16 v[48:51], v[184:187], v[232:235], v[48:51]
	v_mfma_f32_16x16x32_bf16 v[32:35], v[200:203], v[232:235], v[32:35]
	v_mfma_f32_16x16x32_bf16 v[60:63], v[188:191], v[212:215], v[60:63]
	v_mfma_f32_16x16x32_bf16 v[44:47], v[204:207], v[212:215], v[44:47]
	v_mfma_f32_16x16x32_bf16 v[56:59], v[188:191], v[220:223], v[56:59]
	v_mfma_f32_16x16x32_bf16 v[40:43], v[204:207], v[220:223], v[40:43]
	v_mfma_f32_16x16x32_bf16 v[52:55], v[188:191], v[228:231], v[52:55]
	v_mfma_f32_16x16x32_bf16 v[36:39], v[204:207], v[228:231], v[36:39]
	v_mfma_f32_16x16x32_bf16 v[48:51], v[188:191], v[236:239], v[48:51]
	v_mfma_f32_16x16x32_bf16 v[32:35], v[204:207], v[236:239], v[32:35]
	s_setprio 0
	s_barrier
	s_add_i32 s34, s34, s46
	v_lshl_add_u64 v[146:147], s[18:19], 0, v[132:133]
	s_mov_b32 m0, s34
	ds_read_b128 v[208:211], v157 offset:16384
	ds_read_b128 v[212:215], v157 offset:17408
	ds_read_b128 v[216:219], v157 offset:18432
	ds_read_b128 v[220:223], v157 offset:19456
	ds_read_b128 v[224:227], v157 offset:20480
	ds_read_b128 v[228:231], v157 offset:21504
	ds_read_b128 v[232:235], v157 offset:22528
	ds_read_b128 v[236:239], v157 offset:23552
	global_load_lds_dwordx4 v132, s[18:19]
	s_add_i32 m0, s34, 0x2000
	s_add_u32 s34, s18, 0x40000
	v_lshl_add_u64 v[170:171], s[18:19], 0, v[128:129]
	s_addc_u32 s35, s19, 0
	s_add_i32 s52, s52, s46
	global_load_lds_dwordx4 v128, s[18:19]
	s_mov_b32 m0, s52
	v_lshl_add_u64 v[176:177], s[30:31], 0, v[130:131]
	global_load_lds_dwordx4 v132, s[34:35]
	s_add_i32 m0, s52, 0x2000
	s_nop 0
	global_load_lds_dwordx4 v128, s[34:35]
	v_lshl_add_u64 v[174:175], s[30:31], 0, v[134:135]
	s_mov_b32 m0, s47
	s_nop 0
	global_load_lds_dwordx4 v134, s[30:31]
	s_mov_b32 m0, s68
	s_nop 0
	global_load_lds_dwordx4 v130, s[30:31]
	s_waitcnt vmcnt(8)
	s_waitcnt lgkmcnt(0)
	s_barrier
; #define PG8_STAGE(bufoff, gbase, voff) do { _Pragma("unroll") for (int _i = 0; _i < 2; ++_i) \
;         __builtin_amdgcn_global_load_lds((const unsigned*)((const char*)(gbase) + (voff)[_i]), (PG8_LAS unsigned*)(lds + (bufoff) + ldsw + _i * 8192), 16, 0, 0); } while (0)
; #define PG8_LDA(dst, b, h) do { _Pragma("unroll") for (int m = 0; m < 4; ++m) _Pragma("unroll") for (int k = 0; k < 2; ++k) dst[m][k] = *(const PG8_LAS bf16x8*)(lds + PG8_SA(b, h) + aoff + m * 2048 + k * 1024); } while (0)
; #define PG8_LDB(dst, b, h) do { _Pragma("unroll") for (int n = 0; n < 2; ++n) _Pragma("unroll") for (int k = 0; k < 2; ++k) dst[n][k] = *(const PG8_LAS bf16x8*)(lds + PG8_SB(b, h) + boff + n * 2048 + k * 1024); } while (0)
; #define PG8_MMA(ai, bj, At, Bt) do { __builtin_amdgcn_s_setprio(1); _Pragma("unroll") for (int m = 0; m < 4; ++m) _Pragma("unroll") for (int n = 0; n < 2; ++n) _Pragma("unroll") for (int k = 0; k < 2; ++k) \
;         acc[ai][bj][m][n] = __builtin_amdgcn_mfma_f32_16x16x32_bf16(Bt[n][k], At[m][k], acc[ai][bj][m][n], 0, 0, 0); __builtin_amdgcn_s_setprio(0); } while (0)
; #define PG8_WAIT_V(n) asm volatile("s_waitcnt vmcnt(" #n ")" ::: "memory")
; #define PG8_WAIT_L(n) asm volatile("s_waitcnt lgkmcnt(" #n ")" ::: "memory")
; #define PG8_BAR __builtin_amdgcn_s_barrier()
; #define PG8_SCHED __builtin_amdgcn_sched_barrier(0)
; template <class Epi, class Sched, bool ALIGN_EPI = false, bool SP2 = false>
; __device__ __forceinline__ void gemm_phase(PG8_LAS unsigned char* lds, const Gemm g, const Sched& S, const Epi& E) {
;     ...
;             PG8_WAIT_V(8); PG8_WAIT_L(0); PG8_BAR; PG8_MMA(1, 0, At, B0); PG8_MMA(1, 1, At, B1); PG8_BAR; PG8_SCHED;
;             PG8_LDB(B0, 1, 0); PG8_LDB(B1, 1, 1); PG8_SCHED; PG8_LDA(At, 1, 0); PG8_STAGE(PG8_SA(0, 1), a2 + hA, voffA);
;             PG8_WAIT_V(8); PG8_WAIT_L(0); PG8_BAR; PG8_MMA(0, 0, At, B0); PG8_MMA(0, 1, At, B1); PG8_BAR; PG8_SCHED;
	s_setprio 1
	s_waitcnt lgkmcnt(0)
	v_mfma_f32_16x16x32_bf16 v[92:95], v[142:145], v[208:211], v[92:95]
	v_mfma_f32_16x16x32_bf16 v[76:79], v[162:165], v[208:211], v[76:79]
	v_mfma_f32_16x16x32_bf16 v[88:91], v[142:145], v[216:219], v[88:91]
	v_mfma_f32_16x16x32_bf16 v[72:75], v[162:165], v[216:219], v[72:75]
	v_mfma_f32_16x16x32_bf16 v[84:87], v[142:145], v[224:227], v[84:87]
	v_mfma_f32_16x16x32_bf16 v[68:71], v[162:165], v[224:227], v[68:71]
	v_mfma_f32_16x16x32_bf16 v[80:83], v[142:145], v[232:235], v[80:83]
	v_mfma_f32_16x16x32_bf16 v[64:67], v[162:165], v[232:235], v[64:67]
	v_mfma_f32_16x16x32_bf16 v[92:95], v[158:161], v[212:215], v[92:95]
	v_mfma_f32_16x16x32_bf16 v[76:79], v[166:169], v[212:215], v[76:79]
	v_mfma_f32_16x16x32_bf16 v[88:91], v[158:161], v[220:223], v[88:91]
	v_mfma_f32_16x16x32_bf16 v[72:75], v[166:169], v[220:223], v[72:75]
	v_mfma_f32_16x16x32_bf16 v[84:87], v[158:161], v[228:231], v[84:87]
	v_mfma_f32_16x16x32_bf16 v[68:71], v[166:169], v[228:231], v[68:71]
	v_mfma_f32_16x16x32_bf16 v[80:83], v[158:161], v[236:239], v[80:83]
	v_mfma_f32_16x16x32_bf16 v[64:67], v[166:169], v[236:239], v[64:67]
	s_setprio 0
	s_setprio 1
	v_mfma_f32_16x16x32_bf16 v[28:31], v[184:187], v[208:211], v[28:31]
	v_mfma_f32_16x16x32_bf16 v[12:15], v[200:203], v[208:211], v[12:15]
	v_mfma_f32_16x16x32_bf16 v[24:27], v[184:187], v[216:219], v[24:27]
	v_mfma_f32_16x16x32_bf16 v[8:11], v[200:203], v[216:219], v[8:11]
	v_mfma_f32_16x16x32_bf16 v[20:23], v[184:187], v[224:227], v[20:23]
	v_mfma_f32_16x16x32_bf16 v[4:7], v[200:203], v[224:227], v[4:7]
	v_mfma_f32_16x16x32_bf16 v[16:19], v[184:187], v[232:235], v[16:19]
	v_mfma_f32_16x16x32_bf16 v[0:3], v[200:203], v[232:235], v[0:3]
	v_mfma_f32_16x16x32_bf16 v[28:31], v[188:191], v[212:215], v[28:31]
	v_mfma_f32_16x16x32_bf16 v[12:15], v[204:207], v[212:215], v[12:15]
	v_mfma_f32_16x16x32_bf16 v[24:27], v[188:191], v[220:223], v[24:27]
	v_mfma_f32_16x16x32_bf16 v[8:11], v[204:207], v[220:223], v[8:11]
	v_mfma_f32_16x16x32_bf16 v[20:23], v[188:191], v[228:231], v[20:23]
	v_mfma_f32_16x16x32_bf16 v[4:7], v[204:207], v[228:231], v[4:7]
	v_mfma_f32_16x16x32_bf16 v[16:19], v[188:191], v[236:239], v[16:19]
	v_mfma_f32_16x16x32_bf16 v[0:3], v[204:207], v[236:239], v[0:3]
	s_setprio 0
	s_barrier
	s_add_i32 s34, 0, 0x18000
	s_add_i32 s35, 0, 0x1c000
	v_add_u32_e32 v166, s34, v148
	v_add_u32_e32 v172, s35, v148
	ds_read_b128 v[142:145], v166
	ds_read_b128 v[158:161], v166 offset:1024
	ds_read_b128 v[162:165], v166 offset:2048
	ds_read_b128 v[166:169], v166 offset:3072
	ds_read_b128 v[184:187], v172
	ds_read_b128 v[188:191], v172 offset:1024
	ds_read_b128 v[200:203], v172 offset:2048
	ds_read_b128 v[204:207], v172 offset:3072
	s_add_u32 s30, s30, 0x40000
	s_addc_u32 s31, s31, 0
	s_mov_b32 m0, s70
	ds_read_b128 v[208:211], v157 offset:32768
	ds_read_b128 v[212:215], v157 offset:33792
	ds_read_b128 v[216:219], v157 offset:34816
	ds_read_b128 v[220:223], v157 offset:35840
	ds_read_b128 v[224:227], v157 offset:36864
	ds_read_b128 v[228:231], v157 offset:37888
	ds_read_b128 v[232:235], v157 offset:38912
	ds_read_b128 v[236:239], v157 offset:39936
	global_load_lds_dwordx4 v134, s[30:31]
	s_mov_b32 m0, s71
	s_nop 0
	global_load_lds_dwordx4 v130, s[30:31]
	s_waitcnt vmcnt(8)
	s_waitcnt lgkmcnt(0)
	s_barrier
	s_setprio 1
	s_waitcnt lgkmcnt(0)
	v_mfma_f32_16x16x32_bf16 v[124:127], v[142:145], v[208:211], v[124:127]
	v_mfma_f32_16x16x32_bf16 v[108:111], v[162:165], v[208:211], v[108:111]
	v_mfma_f32_16x16x32_bf16 v[120:123], v[142:145], v[216:219], v[120:123]
	v_mfma_f32_16x16x32_bf16 v[104:107], v[162:165], v[216:219], v[104:107]
	v_mfma_f32_16x16x32_bf16 v[116:119], v[142:145], v[224:227], v[116:119]
	v_mfma_f32_16x16x32_bf16 v[100:103], v[162:165], v[224:227], v[100:103]
	v_mfma_f32_16x16x32_bf16 v[112:115], v[142:145], v[232:235], v[112:115]
	v_mfma_f32_16x16x32_bf16 v[96:99], v[162:165], v[232:235], v[96:99]
	v_mfma_f32_16x16x32_bf16 v[124:127], v[158:161], v[212:215], v[124:127]
	v_mfma_f32_16x16x32_bf16 v[108:111], v[166:169], v[212:215], v[108:111]
	v_mfma_f32_16x16x32_bf16 v[120:123], v[158:161], v[220:223], v[120:123]
	v_mfma_f32_16x16x32_bf16 v[104:107], v[166:169], v[220:223], v[104:107]
	v_mfma_f32_16x16x32_bf16 v[116:119], v[158:161], v[228:231], v[116:119]
	v_mfma_f32_16x16x32_bf16 v[100:103], v[166:169], v[228:231], v[100:103]
	v_mfma_f32_16x16x32_bf16 v[112:115], v[158:161], v[236:239], v[112:115]
	v_mfma_f32_16x16x32_bf16 v[96:99], v[166:169], v[236:239], v[96:99]
	s_setprio 0
	s_setprio 1
	v_mfma_f32_16x16x32_bf16 v[60:63], v[184:187], v[208:211], v[60:63]
	v_mfma_f32_16x16x32_bf16 v[44:47], v[200:203], v[208:211], v[44:47]
	v_mfma_f32_16x16x32_bf16 v[56:59], v[184:187], v[216:219], v[56:59]
	v_mfma_f32_16x16x32_bf16 v[40:43], v[200:203], v[216:219], v[40:43]
	v_mfma_f32_16x16x32_bf16 v[52:55], v[184:187], v[224:227], v[52:55]
	v_mfma_f32_16x16x32_bf16 v[36:39], v[200:203], v[224:227], v[36:39]
	v_mfma_f32_16x16x32_bf16 v[48:51], v[184:187], v[232:235], v[48:51]
	v_mfma_f32_16x16x32_bf16 v[32:35], v[200:203], v[232:235], v[32:35]
	v_mfma_f32_16x16x32_bf16 v[60:63], v[188:191], v[212:215], v[60:63]
	v_mfma_f32_16x16x32_bf16 v[44:47], v[204:207], v[212:215], v[44:47]
	v_mfma_f32_16x16x32_bf16 v[56:59], v[188:191], v[220:223], v[56:59]
	v_mfma_f32_16x16x32_bf16 v[40:43], v[204:207], v[220:223], v[40:43]
	v_mfma_f32_16x16x32_bf16 v[52:55], v[188:191], v[228:231], v[52:55]
	v_mfma_f32_16x16x32_bf16 v[36:39], v[204:207], v[228:231], v[36:39]
	v_mfma_f32_16x16x32_bf16 v[48:51], v[188:191], v[236:239], v[48:51]
	v_mfma_f32_16x16x32_bf16 v[32:35], v[204:207], v[236:239], v[32:35]
	s_setprio 0
	s_barrier
; #define PG8_STAGE(bufoff, gbase, voff) do { _Pragma("unroll") for (int _i = 0; _i < 2; ++_i) \
;         __builtin_amdgcn_global_load_lds((const unsigned*)((const char*)(gbase) + (voff)[_i]), (PG8_LAS unsigned*)(lds + (bufoff) + ldsw + _i * 8192), 16, 0, 0); } while (0)
; #define PG8_LDA(dst, b, h) do { _Pragma("unroll") for (int m = 0; m < 4; ++m) _Pragma("unroll") for (int k = 0; k < 2; ++k) dst[m][k] = *(const PG8_LAS bf16x8*)(lds + PG8_SA(b, h) + aoff + m * 2048 + k * 1024); } while (0)
; #define PG8_LDB(dst, b, h) do { _Pragma("unroll") for (int n = 0; n < 2; ++n) _Pragma("unroll") for (int k = 0; k < 2; ++k) dst[n][k] = *(const PG8_LAS bf16x8*)(lds + PG8_SB(b, h) + boff + n * 2048 + k * 1024); } while (0)
; template <class Epi, class Sched, bool ALIGN_EPI = false, bool SP2 = false>
; __device__ __forceinline__ void gemm_phase(PG8_LAS unsigned char* lds, const Gemm g, const Sched& S, const Epi& E) {
;     ...
;         for (int t = 0; t < nt; t += 2) {
;             const bool last = (t == nt - 2);
;             const char* a1 = cA + (size_t)(t + 1) * kstep;
;             const char* a2 = last ? nA : cA + (size_t)(t + 2) * kstep; const char* b2 = last ? nB : cB + (size_t)(t + 2) * kstep;
;             const char* a3 = a2 + kstep; const char* b3 = b2 + kstep;
;             if (last && has_next) S.a_ready(nxt);
;             if constexpr (SP2) {
;             PG8_LDB(B0, 0, 0); PG8_LDB(B1, 0, 1); PG8_SCHED; PG8_LDA(At, 0, 0); PG8_STAGE(PG8_SA(1, 1), a1 + hA, voffA);
;             PG8_WAIT_V(8); PG8_WAIT_L(0); PG8_BAR; PG8_MMA(0, 0, At, B0); PG8_MMA(0, 1, At, B1); PG8_BAR; PG8_SCHED;
;             PG8_LDA(At, 0, 1); PG8_STAGE(PG8_SB(0, 0), b2, voffB); PG8_STAGE(PG8_SB(0, 1), b2 + hB, voffB); PG8_STAGE(PG8_SA(0, 0), a2, voffA);
;             PG8_WAIT_V(8); PG8_WAIT_L(0); PG8_BAR; PG8_MMA(1, 0, At, B0); PG8_MMA(1, 1, At, B1); PG8_BAR; PG8_SCHED;
;             PG8_LDB(B0, 1, 0); PG8_LDB(B1, 1, 1); PG8_SCHED; PG8_LDA(At, 1, 0); PG8_STAGE(PG8_SA(0, 1), a2 + hA, voffA);
;             PG8_WAIT_V(8); PG8_WAIT_L(0); PG8_BAR; PG8_MMA(0, 0, At, B0); PG8_MMA(0, 1, At, B1); PG8_BAR; PG8_SCHED;
;             PG8_LDA(At, 1, 1); PG8_STAGE(PG8_SB(1, 0), b3, voffB); PG8_STAGE(PG8_SB(1, 1), b3 + hB, voffB); PG8_STAGE(PG8_SA(1, 0), a3, voffA);
;             PG8_WAIT_V(8); PG8_WAIT_L(0); PG8_BAR; PG8_MMA(1, 0, At, B0); PG8_MMA(1, 1, At, B1); PG8_BAR; PG8_SCHED;
	s_add_i32 s30, s34, s46
	v_lshl_add_u64 v[146:147], v[146:147], 0, s[76:77]
	s_mov_b32 m0, s30
	ds_read_b128 v[208:211], v157 offset:49152
	ds_read_b128 v[212:215], v157 offset:50176
	ds_read_b128 v[216:219], v157 offset:51200
	ds_read_b128 v[220:223], v157 offset:52224
	ds_read_b128 v[224:227], v157 offset:53248
	ds_read_b128 v[228:231], v157 offset:54272
	ds_read_b128 v[232:235], v157 offset:55296
	ds_read_b128 v[236:239], v157 offset:56320
	global_load_lds_dwordx4 v[146:147], off
	s_add_i32 m0, s30, 0x2000
	s_add_u32 s18, s18, 0x40080
	v_lshl_add_u64 v[146:147], v[170:171], 0, s[76:77]
	s_addc_u32 s19, s19, 0
	s_add_i32 s30, s35, s46
	global_load_lds_dwordx4 v[146:147], off
	s_mov_b32 m0, s30
	s_nop 0
	global_load_lds_dwordx4 v132, s[18:19]
	s_add_i32 m0, s30, 0x2000
	s_nop 0
	global_load_lds_dwordx4 v128, s[18:19]
	v_lshl_add_u64 v[146:147], v[174:175], 0, s[76:77]
	s_mov_b32 m0, s97
	s_nop 0
	global_load_lds_dwordx4 v[146:147], off
	v_lshl_add_u64 v[146:147], v[176:177], 0, s[76:77]
	s_mov_b32 m0, s90
	s_nop 0
	global_load_lds_dwordx4 v[146:147], off
	s_waitcnt vmcnt(8)
	s_waitcnt lgkmcnt(0)
	s_barrier
	s_setprio 1
	s_waitcnt lgkmcnt(0)
	v_mfma_f32_16x16x32_bf16 v[92:95], v[142:145], v[208:211], v[92:95]
	v_mfma_f32_16x16x32_bf16 v[76:79], v[162:165], v[208:211], v[76:79]
	v_mfma_f32_16x16x32_bf16 v[88:91], v[142:145], v[216:219], v[88:91]
	v_mfma_f32_16x16x32_bf16 v[72:75], v[162:165], v[216:219], v[72:75]
	v_mfma_f32_16x16x32_bf16 v[84:87], v[142:145], v[224:227], v[84:87]
	v_mfma_f32_16x16x32_bf16 v[68:71], v[162:165], v[224:227], v[68:71]
	v_mfma_f32_16x16x32_bf16 v[80:83], v[142:145], v[232:235], v[80:83]
	v_mfma_f32_16x16x32_bf16 v[64:67], v[162:165], v[232:235], v[64:67]
	v_mfma_f32_16x16x32_bf16 v[92:95], v[158:161], v[212:215], v[92:95]
	v_mfma_f32_16x16x32_bf16 v[76:79], v[166:169], v[212:215], v[76:79]
	v_mfma_f32_16x16x32_bf16 v[88:91], v[158:161], v[220:223], v[88:91]
	v_mfma_f32_16x16x32_bf16 v[72:75], v[166:169], v[220:223], v[72:75]
	v_mfma_f32_16x16x32_bf16 v[84:87], v[158:161], v[228:231], v[84:87]
	v_mfma_f32_16x16x32_bf16 v[68:71], v[166:169], v[228:231], v[68:71]
	v_mfma_f32_16x16x32_bf16 v[80:83], v[158:161], v[236:239], v[80:83]
	v_mfma_f32_16x16x32_bf16 v[64:67], v[166:169], v[236:239], v[64:67]
	s_setprio 0
	s_setprio 1
	v_mfma_f32_16x16x32_bf16 v[28:31], v[184:187], v[208:211], v[28:31]
	v_mfma_f32_16x16x32_bf16 v[12:15], v[200:203], v[208:211], v[12:15]
	v_mfma_f32_16x16x32_bf16 v[24:27], v[184:187], v[216:219], v[24:27]
	v_mfma_f32_16x16x32_bf16 v[8:11], v[200:203], v[216:219], v[8:11]
	v_mfma_f32_16x16x32_bf16 v[20:23], v[184:187], v[224:227], v[20:23]
	v_mfma_f32_16x16x32_bf16 v[4:7], v[200:203], v[224:227], v[4:7]
	v_mfma_f32_16x16x32_bf16 v[16:19], v[184:187], v[232:235], v[16:19]
	v_mfma_f32_16x16x32_bf16 v[0:3], v[200:203], v[232:235], v[0:3]
	v_mfma_f32_16x16x32_bf16 v[28:31], v[188:191], v[212:215], v[28:31]
	v_mfma_f32_16x16x32_bf16 v[12:15], v[204:207], v[212:215], v[12:15]
	v_mfma_f32_16x16x32_bf16 v[24:27], v[188:191], v[220:223], v[24:27]
	v_mfma_f32_16x16x32_bf16 v[8:11], v[204:207], v[220:223], v[8:11]
	v_mfma_f32_16x16x32_bf16 v[20:23], v[188:191], v[228:231], v[20:23]
	v_mfma_f32_16x16x32_bf16 v[4:7], v[204:207], v[228:231], v[4:7]
	v_mfma_f32_16x16x32_bf16 v[16:19], v[188:191], v[236:239], v[16:19]
	v_mfma_f32_16x16x32_bf16 v[0:3], v[204:207], v[236:239], v[0:3]
	s_setprio 0
	s_barrier
	s_add_i32 s75, s75, 2
	s_add_u32 s0, s0, 0x100
	s_addc_u32 s1, s1, 0
	s_add_u32 s51, s51, 0x100
	s_addc_u32 s74, s74, 0
	s_cmp_gt_u32 s75, 13
	s_cbranch_scc0 .LBB0_193
	s_and_b64 vcc, exec, s[6:7]
	s_cbranch_vccz .LBB0_196
	s_barrier

; #define PG8_STAGE(bufoff, gbase, voff) do { _Pragma("unroll") for (int _i = 0; _i < 2; ++_i) \
;         __builtin_amdgcn_global_load_lds((const unsigned*)((const char*)(gbase) + (voff)[_i]), (PG8_LAS unsigned*)(lds + (bufoff) + ldsw + _i * 8192), 16, 0, 0); } while (0)
; #define PG8_WAIT_V(n) asm volatile("s_waitcnt vmcnt(" #n ")" ::: "memory")
; #define PG8_BAR __builtin_amdgcn_s_barrier()
; template <class Epi, class Sched, bool ALIGN_EPI = false, bool SP2 = false>
; __device__ __forceinline__ void gemm_phase(PG8_LAS unsigned char* lds, const Gemm g, const Sched& S, const Epi& E) {
;     int tid_ = threadIdx.x; asm volatile("" : "+v"(tid_)); const int tid = tid_, wid = __builtin_amdgcn_readfirstlane(tid >> 6), lane = tid & 63, wr = wid >> 2, wc = wid & 3, fr = lane & 15, fq = lane >> 4;
;     const int K = g.K, nt = K / BK;
;     unsigned voffA[2], voffB[2];
; #pragma unroll
;     for (int i = 0; i < 2; ++i) { int R, C; stage_rc(tid * 16 + i * 8192, R, C); const int Rb = Epi::PERM ? ((R & ~31) + perm32(R & 31)) : R;
;         voffA[i] = (unsigned)(R * g.lda + C) * 2u; voffB[i] = (unsigned)(Rb * g.ldb + C) * 2u; }
;     const size_t kstep = (size_t)(BK * 2);
;     const size_t hA = (size_t)HALF * g.lda * 2, hB = (size_t)HALF * g.ldb * 2;
;     const size_t tA = 2 * hA, tB = 2 * hB;
;     const unsigned ldsw = (unsigned)wid * 1024u;
;     const int aoff = lds_byte(wr * 64 + fr, fq * 8), boff = lds_byte(wc * 32 + fr, fq * 8);
;     ...
;     if constexpr (SP2) {
;         PG8_STAGE(PG8_SB(0, 0), cB, voffB); PG8_STAGE(PG8_SB(0, 1), cB + hB, voffB); PG8_STAGE(PG8_SA(0, 0), cA, voffA); PG8_STAGE(PG8_SA(0, 1), cA + hA, voffA);
;         if (wr == 1) PG8_BAR;
;         PG8_WAIT_V(2); PG8_BAR;
;         PG8_STAGE(PG8_SB(1, 0), cB + kstep, voffB); PG8_STAGE(PG8_SA(1, 0), cA + kstep, voffA); PG8_STAGE(PG8_SB(1, 1), cB + hB + kstep, voffB);
;         PG8_WAIT_V(6); PG8_BAR;
.LBB0_346:
	v_lshrrev_b32_e32 v18, 1, v8
	v_and_b32_e32 v18, 24, v18
	v_readlane_b32 s12, v253, 31
	v_and_b32_e32 v9, 15, v8
	v_lshlrev_b32_e32 v19, 1, v18
	v_lshlrev_b32_e32 v8, 2, v8
	s_lshl_b32 s1, s1, 5
	v_readlane_b32 s13, v253, 32
	v_lshl_or_b32 v140, s6, 6, v9
	v_lshl_or_b32 v9, v9, 6, v19
	s_lshl_b32 s6, s6, 13
	v_and_b32_e32 v8, 32, v8
	s_and_b32 s1, s1, 0x60
	v_lshl_add_u64 v[10:11], s[12:13], 0, v[172:173]
	v_mov_b32_e32 v129, v173
	v_readlane_b32 s10, v253, 27
	v_bitop3_b32 v19, v9, s6, v8 bitop3:0xde
	s_lshl_b32 s6, s1, 7
	v_lshl_add_u64 v[12:13], s[12:13], 0, v[128:129]
	v_mov_b32_e32 v133, v173
	v_readlane_b32 s11, v253, 28
	v_bitop3_b32 v141, v9, s6, v8 bitop3:0xde
	s_add_i32 m0, s19, 0x18000
	v_lshl_add_u64 v[8:9], v[10:11], 0, s[76:77]
	v_lshl_add_u64 v[14:15], s[10:11], 0, v[132:133]
	v_mov_b32_e32 v131, v173
	s_waitcnt vmcnt(2)
	s_barrier
	global_load_lds_dwordx4 v[8:9], off
	v_lshl_add_u64 v[8:9], v[12:13], 0, s[76:77]
	s_add_i32 m0, s19, 0x1a000
	s_add_i32 s43, s19, 0x8000
	v_lshl_add_u64 v[16:17], s[10:11], 0, v[130:131]
	global_load_lds_dwordx4 v[8:9], off
	v_lshl_add_u64 v[8:9], v[14:15], 0, s[76:77]
	s_mov_b32 m0, s43
	s_add_i32 s44, s19, 0xa000
	v_readlane_b32 s6, v253, 33
	global_load_lds_dwordx4 v[8:9], off
	v_lshl_add_u64 v[8:9], v[16:17], 0, s[76:77]
	s_mov_b32 m0, s44
	v_readlane_b32 s7, v253, 34
	global_load_lds_dwordx4 v[8:9], off
	s_add_i32 m0, s19, 0x1c000
	s_nop 0
	s_nop 1
	global_load_lds_dwordx4 v172, s[6:7]
	s_add_i32 m0, s19, 0x1e000
	s_movk_i32 s9, 0x1e00
	global_load_lds_dwordx4 v128, s[6:7]
	v_lshrrev_b32_e32 v5, 1, v5
	v_mul_lo_u32 v4, v4, s9
	s_mov_b32 s8, 0x1e000
	s_cmpk_lt_u32 s0, 0x100
	v_or_b32_e32 v142, s1, v18
	v_mad_u64_u32 v[4:5], s[0:1], v5, s8, v[4:5]
	v_or_b32_e32 v4, v4, v6
	v_add_lshl_u32 v4, v4, v7, 1
	v_mov_b32_e32 v5, v173
	s_mov_b64 s[14:15], 0x1e0080
	v_lshl_add_u64 v[134:135], v[4:5], 0, s[14:15]
	v_lshrrev_b32_e32 v4, 1, v0
	v_mul_lo_u32 v0, v1, s9
	v_mad_u64_u32 v[0:1], s[0:1], v4, s8, v[0:1]
	s_waitcnt vmcnt(6)
	v_or_b32_e32 v0, v0, v2
	v_add_lshl_u32 v0, v0, v3, 1
	v_mov_b32_e32 v1, v173
	s_cselect_b64 s[6:7], -1, 0
	v_lshl_add_u64 v[136:137], v[0:1], 0, s[14:15]
	s_mov_b32 s45, 0
	v_add_u32_e32 v143, 0, v19
	v_readlane_b32 s50, v253, 21
	v_readlane_b32 s51, v253, 26
	s_barrier
	s_branch .LBB0_349

; #define PG8_STAGE(bufoff, gbase, voff) do { _Pragma("unroll") for (int _i = 0; _i < 2; ++_i) \
;         __builtin_amdgcn_global_load_lds((const unsigned*)((const char*)(gbase) + (voff)[_i]), (PG8_LAS unsigned*)(lds + (bufoff) + ldsw + _i * 8192), 16, 0, 0); } while (0)
; #define PG8_LDA(dst, b, h) do { _Pragma("unroll") for (int m = 0; m < 4; ++m) _Pragma("unroll") for (int k = 0; k < 2; ++k) dst[m][k] = *(const PG8_LAS bf16x8*)(lds + PG8_SA(b, h) + aoff + m * 2048 + k * 1024); } while (0)
; #define PG8_LDB(dst, b, h) do { _Pragma("unroll") for (int n = 0; n < 2; ++n) _Pragma("unroll") for (int k = 0; k < 2; ++k) dst[n][k] = *(const PG8_LAS bf16x8*)(lds + PG8_SB(b, h) + boff + n * 2048 + k * 1024); } while (0)
; #define PG8_MMA(ai, bj, At, Bt) do { __builtin_amdgcn_s_setprio(1); _Pragma("unroll") for (int m = 0; m < 4; ++m) _Pragma("unroll") for (int n = 0; n < 2; ++n) _Pragma("unroll") for (int k = 0; k < 2; ++k) \
;         acc[ai][bj][m][n] = __builtin_amdgcn_mfma_f32_16x16x32_bf16(Bt[n][k], At[m][k], acc[ai][bj][m][n], 0, 0, 0); __builtin_amdgcn_s_setprio(0); } while (0)
; #define PG8_WAIT_V(n) asm volatile("s_waitcnt vmcnt(" #n ")" ::: "memory")
; #define PG8_WAIT_L(n) asm volatile("s_waitcnt lgkmcnt(" #n ")" ::: "memory")
; template <class Epi, class Sched, bool ALIGN_EPI = false, bool SP2 = false>
; __device__ __forceinline__ void gemm_phase(PG8_LAS unsigned char* lds, const Gemm g, const Sched& S, const Epi& E) {
;     ...
;         for (int t = 0; t < nt; t += 2) {
;             const bool last = (t == nt - 2);
;             const char* a1 = cA + (size_t)(t + 1) * kstep;
;             const char* a2 = last ? nA : cA + (size_t)(t + 2) * kstep; const char* b2 = last ? nB : cB + (size_t)(t + 2) * kstep;
;             const char* a3 = a2 + kstep; const char* b3 = b2 + kstep;
;             if (last && has_next) S.a_ready(nxt);
;             if constexpr (SP2) {
;             PG8_LDB(B0, 0, 0); PG8_LDB(B1, 0, 1); PG8_SCHED; PG8_LDA(At, 0, 0); PG8_STAGE(PG8_SA(1, 1), a1 + hA, voffA);
;             PG8_WAIT_V(8); PG8_WAIT_L(0); PG8_BAR; PG8_MMA(0, 0, At, B0); PG8_MMA(0, 1, At, B1); PG8_BAR; PG8_SCHED;
;             PG8_LDA(At, 0, 1); PG8_STAGE(PG8_SB(0, 0), b2, voffB); PG8_STAGE(PG8_SB(0, 1), b2 + hB, voffB); PG8_STAGE(PG8_SA(0, 0), a2, voffA);
;             PG8_WAIT_V(8); PG8_WAIT_L(0); PG8_BAR; PG8_MMA(1, 0, At, B0); PG8_MMA(1, 1, At, B1); PG8_BAR; PG8_SCHED;
.LBB0_356:
	s_add_u32 s12, s10, 0x100
	s_addc_u32 s13, s11, 0
	s_add_i32 s34, 0, 0x10000
	s_cmp_eq_u32 s71, 2
	s_cselect_b32 s17, s1, s13
	s_cselect_b32 s16, s0, s12
	v_add_u32_e32 v138, s34, v141
	s_cselect_b32 s15, s9, s70
	s_cselect_b32 s14, s8, s68
	s_add_i32 s35, 0, 0x14000
	ds_read_b128 v[144:147], v138
	ds_read_b128 v[148:151], v138 offset:1024
	ds_read_b128 v[152:155], v138 offset:2048
	ds_read_b128 v[156:159], v138 offset:3072
	v_add_u32_e32 v138, s35, v141
	ds_read_b128 v[160:163], v138
	ds_read_b128 v[164:167], v138 offset:1024
	ds_read_b128 v[168:171], v138 offset:2048
	ds_read_b128 v[184:187], v138 offset:3072
	v_lshl_add_u64 v[138:139], s[10:11], 0, v[134:135]
	s_add_i32 m0, s19, 0xc000
	ds_read_b128 v[188:191], v143
	ds_read_b128 v[200:203], v143 offset:1024
	ds_read_b128 v[204:207], v143 offset:2048
	ds_read_b128 v[208:211], v143 offset:3072
	ds_read_b128 v[212:215], v143 offset:4096
	ds_read_b128 v[216:219], v143 offset:5120
	ds_read_b128 v[220:223], v143 offset:6144
	ds_read_b128 v[224:227], v143 offset:7168
	global_load_lds_dwordx4 v[138:139], off
	v_lshl_add_u64 v[138:139], s[10:11], 0, v[136:137]
	s_add_i32 m0, s19, 0xe000
	s_nop 0
	global_load_lds_dwordx4 v[138:139], off
	s_waitcnt vmcnt(8)
	s_waitcnt lgkmcnt(0)
	s_barrier
	s_setprio 1
	s_waitcnt lgkmcnt(0)
	v_mfma_f32_16x16x32_bf16 v[124:127], v[144:147], v[188:191], v[124:127]
	v_mfma_f32_16x16x32_bf16 v[120:123], v[152:155], v[188:191], v[120:123]
	v_mfma_f32_16x16x32_bf16 v[108:111], v[144:147], v[204:207], v[108:111]
	v_mfma_f32_16x16x32_bf16 v[104:107], v[152:155], v[204:207], v[104:107]
	v_mfma_f32_16x16x32_bf16 v[92:95], v[144:147], v[212:215], v[92:95]
	v_mfma_f32_16x16x32_bf16 v[88:91], v[152:155], v[212:215], v[88:91]
	v_mfma_f32_16x16x32_bf16 v[76:79], v[144:147], v[220:223], v[76:79]
	v_mfma_f32_16x16x32_bf16 v[72:75], v[152:155], v[220:223], v[72:75]
	v_mfma_f32_16x16x32_bf16 v[124:127], v[148:151], v[200:203], v[124:127]
	v_mfma_f32_16x16x32_bf16 v[120:123], v[156:159], v[200:203], v[120:123]
	v_mfma_f32_16x16x32_bf16 v[108:111], v[148:151], v[208:211], v[108:111]
	v_mfma_f32_16x16x32_bf16 v[104:107], v[156:159], v[208:211], v[104:107]
	v_mfma_f32_16x16x32_bf16 v[92:95], v[148:151], v[216:219], v[92:95]
	v_mfma_f32_16x16x32_bf16 v[88:91], v[156:159], v[216:219], v[88:91]
	v_mfma_f32_16x16x32_bf16 v[76:79], v[148:151], v[224:227], v[76:79]
	v_mfma_f32_16x16x32_bf16 v[72:75], v[156:159], v[224:227], v[72:75]
	s_setprio 0
	s_setprio 1
	v_mfma_f32_16x16x32_bf16 v[116:119], v[160:163], v[188:191], v[116:119]
	v_mfma_f32_16x16x32_bf16 v[112:115], v[168:171], v[188:191], v[112:115]
	v_mfma_f32_16x16x32_bf16 v[100:103], v[160:163], v[204:207], v[100:103]
	v_mfma_f32_16x16x32_bf16 v[96:99], v[168:171], v[204:207], v[96:99]
	v_mfma_f32_16x16x32_bf16 v[84:87], v[160:163], v[212:215], v[84:87]
	v_mfma_f32_16x16x32_bf16 v[80:83], v[168:171], v[212:215], v[80:83]
	v_mfma_f32_16x16x32_bf16 v[68:71], v[160:163], v[220:223], v[68:71]
	v_mfma_f32_16x16x32_bf16 v[64:67], v[168:171], v[220:223], v[64:67]
	v_mfma_f32_16x16x32_bf16 v[116:119], v[164:167], v[200:203], v[116:119]
	v_mfma_f32_16x16x32_bf16 v[112:115], v[184:187], v[200:203], v[112:115]
	v_mfma_f32_16x16x32_bf16 v[100:103], v[164:167], v[208:211], v[100:103]
	v_mfma_f32_16x16x32_bf16 v[96:99], v[184:187], v[208:211], v[96:99]
	v_mfma_f32_16x16x32_bf16 v[84:87], v[164:167], v[216:219], v[84:87]
	v_mfma_f32_16x16x32_bf16 v[80:83], v[184:187], v[216:219], v[80:83]
	v_mfma_f32_16x16x32_bf16 v[68:71], v[164:167], v[224:227], v[68:71]
	v_mfma_f32_16x16x32_bf16 v[64:67], v[184:187], v[224:227], v[64:67]
	s_setprio 0
	s_barrier
	s_add_i32 s10, s34, s18
	v_lshl_add_u64 v[138:139], s[14:15], 0, v[172:173]
	s_mov_b32 m0, s10
	ds_read_b128 v[188:191], v143 offset:16384
	ds_read_b128 v[200:203], v143 offset:17408
	ds_read_b128 v[204:207], v143 offset:18432
	ds_read_b128 v[208:211], v143 offset:19456
	ds_read_b128 v[212:215], v143 offset:20480
	ds_read_b128 v[216:219], v143 offset:21504
	ds_read_b128 v[220:223], v143 offset:22528
	ds_read_b128 v[224:227], v143 offset:23552
	global_load_lds_dwordx4 v172, s[14:15]
	s_add_i32 m0, s10, 0x2000
	s_add_u32 s10, s14, 0x18000
	v_lshl_add_u64 v[174:175], s[14:15], 0, v[128:129]
	s_addc_u32 s11, s15, 0
	s_add_i32 s34, s35, s18
	global_load_lds_dwordx4 v128, s[14:15]
	s_mov_b32 m0, s34
	v_lshl_add_u64 v[180:181], s[16:17], 0, v[130:131]
	global_load_lds_dwordx4 v172, s[10:11]
	s_add_i32 m0, s34, 0x2000
	s_nop 0
	global_load_lds_dwordx4 v128, s[10:11]
	v_lshl_add_u64 v[176:177], s[16:17], 0, v[132:133]
	s_mov_b32 m0, s19
	s_nop 0
	global_load_lds_dwordx4 v132, s[16:17]
	s_mov_b32 m0, s30
	s_nop 0
	global_load_lds_dwordx4 v130, s[16:17]
	s_waitcnt vmcnt(8)
	s_waitcnt lgkmcnt(0)
	s_barrier
; #define PG8_STAGE(bufoff, gbase, voff) do { _Pragma("unroll") for (int _i = 0; _i < 2; ++_i) \
;         __builtin_amdgcn_global_load_lds((const unsigned*)((const char*)(gbase) + (voff)[_i]), (PG8_LAS unsigned*)(lds + (bufoff) + ldsw + _i * 8192), 16, 0, 0); } while (0)
; #define PG8_LDA(dst, b, h) do { _Pragma("unroll") for (int m = 0; m < 4; ++m) _Pragma("unroll") for (int k = 0; k < 2; ++k) dst[m][k] = *(const PG8_LAS bf16x8*)(lds + PG8_SA(b, h) + aoff + m * 2048 + k * 1024); } while (0)
; #define PG8_LDB(dst, b, h) do { _Pragma("unroll") for (int n = 0; n < 2; ++n) _Pragma("unroll") for (int k = 0; k < 2; ++k) dst[n][k] = *(const PG8_LAS bf16x8*)(lds + PG8_SB(b, h) + boff + n * 2048 + k * 1024); } while (0)
; #define PG8_MMA(ai, bj, At, Bt) do { __builtin_amdgcn_s_setprio(1); _Pragma("unroll") for (int m = 0; m < 4; ++m) _Pragma("unroll") for (int n = 0; n < 2; ++n) _Pragma("unroll") for (int k = 0; k < 2; ++k) \
;         acc[ai][bj][m][n] = __builtin_amdgcn_mfma_f32_16x16x32_bf16(Bt[n][k], At[m][k], acc[ai][bj][m][n], 0, 0, 0); __builtin_amdgcn_s_setprio(0); } while (0)
; #define PG8_WAIT_V(n) asm volatile("s_waitcnt vmcnt(" #n ")" ::: "memory")
; #define PG8_WAIT_L(n) asm volatile("s_waitcnt lgkmcnt(" #n ")" ::: "memory")
; #define PG8_BAR __builtin_amdgcn_s_barrier()
; #define PG8_SCHED __builtin_amdgcn_sched_barrier(0)
; template <class Epi, class Sched, bool ALIGN_EPI = false, bool SP2 = false>
; __device__ __forceinline__ void gemm_phase(PG8_LAS unsigned char* lds, const Gemm g, const Sched& S, const Epi& E) {
;     ...
;             PG8_WAIT_V(8); PG8_WAIT_L(0); PG8_BAR; PG8_MMA(1, 0, At, B0); PG8_MMA(1, 1, At, B1); PG8_BAR; PG8_SCHED;
;             PG8_LDB(B0, 1, 0); PG8_LDB(B1, 1, 1); PG8_SCHED; PG8_LDA(At, 1, 0); PG8_STAGE(PG8_SA(0, 1), a2 + hA, voffA);
;             PG8_WAIT_V(8); PG8_WAIT_L(0); PG8_BAR; PG8_MMA(0, 0, At, B0); PG8_MMA(0, 1, At, B1); PG8_BAR; PG8_SCHED;
	s_setprio 1
	s_waitcnt lgkmcnt(0)
	v_mfma_f32_16x16x32_bf16 v[60:63], v[144:147], v[188:191], v[60:63]
	v_mfma_f32_16x16x32_bf16 v[56:59], v[152:155], v[188:191], v[56:59]
	v_mfma_f32_16x16x32_bf16 v[44:47], v[144:147], v[204:207], v[44:47]
	v_mfma_f32_16x16x32_bf16 v[40:43], v[152:155], v[204:207], v[40:43]
	v_mfma_f32_16x16x32_bf16 v[28:31], v[144:147], v[212:215], v[28:31]
	v_mfma_f32_16x16x32_bf16 v[24:27], v[152:155], v[212:215], v[24:27]
	v_mfma_f32_16x16x32_bf16 v[12:15], v[144:147], v[220:223], v[12:15]
	v_mfma_f32_16x16x32_bf16 v[8:11], v[152:155], v[220:223], v[8:11]
	v_mfma_f32_16x16x32_bf16 v[60:63], v[148:151], v[200:203], v[60:63]
	v_mfma_f32_16x16x32_bf16 v[56:59], v[156:159], v[200:203], v[56:59]
	v_mfma_f32_16x16x32_bf16 v[44:47], v[148:151], v[208:211], v[44:47]
	v_mfma_f32_16x16x32_bf16 v[40:43], v[156:159], v[208:211], v[40:43]
	v_mfma_f32_16x16x32_bf16 v[28:31], v[148:151], v[216:219], v[28:31]
	v_mfma_f32_16x16x32_bf16 v[24:27], v[156:159], v[216:219], v[24:27]
	v_mfma_f32_16x16x32_bf16 v[12:15], v[148:151], v[224:227], v[12:15]
	v_mfma_f32_16x16x32_bf16 v[8:11], v[156:159], v[224:227], v[8:11]
	s_setprio 0
	s_setprio 1
	v_mfma_f32_16x16x32_bf16 v[52:55], v[160:163], v[188:191], v[52:55]
	v_mfma_f32_16x16x32_bf16 v[48:51], v[168:171], v[188:191], v[48:51]
	v_mfma_f32_16x16x32_bf16 v[36:39], v[160:163], v[204:207], v[36:39]
	v_mfma_f32_16x16x32_bf16 v[32:35], v[168:171], v[204:207], v[32:35]
	v_mfma_f32_16x16x32_bf16 v[20:23], v[160:163], v[212:215], v[20:23]
	v_mfma_f32_16x16x32_bf16 v[16:19], v[168:171], v[212:215], v[16:19]
	v_mfma_f32_16x16x32_bf16 v[4:7], v[160:163], v[220:223], v[4:7]
	v_mfma_f32_16x16x32_bf16 v[0:3], v[168:171], v[220:223], v[0:3]
	v_mfma_f32_16x16x32_bf16 v[52:55], v[164:167], v[200:203], v[52:55]
	v_mfma_f32_16x16x32_bf16 v[48:51], v[184:187], v[200:203], v[48:51]
	v_mfma_f32_16x16x32_bf16 v[36:39], v[164:167], v[208:211], v[36:39]
	v_mfma_f32_16x16x32_bf16 v[32:35], v[184:187], v[208:211], v[32:35]
	v_mfma_f32_16x16x32_bf16 v[20:23], v[164:167], v[216:219], v[20:23]
	v_mfma_f32_16x16x32_bf16 v[16:19], v[184:187], v[216:219], v[16:19]
	v_mfma_f32_16x16x32_bf16 v[4:7], v[164:167], v[224:227], v[4:7]
	v_mfma_f32_16x16x32_bf16 v[0:3], v[184:187], v[224:227], v[0:3]
	s_setprio 0
	s_barrier
	s_add_i32 s34, 0, 0x18000
	s_add_i32 s35, 0, 0x1c000
	v_add_u32_e32 v156, s34, v141
	v_add_u32_e32 v182, s35, v141
	ds_read_b128 v[144:147], v156
	ds_read_b128 v[148:151], v156 offset:1024
	ds_read_b128 v[152:155], v156 offset:2048
	ds_read_b128 v[156:159], v156 offset:3072
	ds_read_b128 v[160:163], v182
	ds_read_b128 v[164:167], v182 offset:1024
	ds_read_b128 v[168:171], v182 offset:2048
	ds_read_b128 v[184:187], v182 offset:3072
	s_add_u32 s10, s16, 0x1e0000
	s_addc_u32 s11, s17, 0
	s_mov_b32 m0, s31
	ds_read_b128 v[188:191], v143 offset:32768
	ds_read_b128 v[200:203], v143 offset:33792
	ds_read_b128 v[204:207], v143 offset:34816
	ds_read_b128 v[208:211], v143 offset:35840
	ds_read_b128 v[212:215], v143 offset:36864
	ds_read_b128 v[216:219], v143 offset:37888
	ds_read_b128 v[220:223], v143 offset:38912
	ds_read_b128 v[224:227], v143 offset:39936
	global_load_lds_dwordx4 v132, s[10:11]
	s_mov_b32 m0, s42
	s_nop 0
	global_load_lds_dwordx4 v130, s[10:11]
	s_waitcnt vmcnt(8)
	s_waitcnt lgkmcnt(0)
	s_barrier
	s_setprio 1
	s_waitcnt lgkmcnt(0)
	v_mfma_f32_16x16x32_bf16 v[124:127], v[144:147], v[188:191], v[124:127]
	v_mfma_f32_16x16x32_bf16 v[120:123], v[152:155], v[188:191], v[120:123]
	v_mfma_f32_16x16x32_bf16 v[108:111], v[144:147], v[204:207], v[108:111]
	v_mfma_f32_16x16x32_bf16 v[104:107], v[152:155], v[204:207], v[104:107]
	v_mfma_f32_16x16x32_bf16 v[92:95], v[144:147], v[212:215], v[92:95]
	v_mfma_f32_16x16x32_bf16 v[88:91], v[152:155], v[212:215], v[88:91]
	v_mfma_f32_16x16x32_bf16 v[76:79], v[144:147], v[220:223], v[76:79]
	v_mfma_f32_16x16x32_bf16 v[72:75], v[152:155], v[220:223], v[72:75]
	v_mfma_f32_16x16x32_bf16 v[124:127], v[148:151], v[200:203], v[124:127]
	v_mfma_f32_16x16x32_bf16 v[120:123], v[156:159], v[200:203], v[120:123]
	v_mfma_f32_16x16x32_bf16 v[108:111], v[148:151], v[208:211], v[108:111]
	v_mfma_f32_16x16x32_bf16 v[104:107], v[156:159], v[208:211], v[104:107]
	v_mfma_f32_16x16x32_bf16 v[92:95], v[148:151], v[216:219], v[92:95]
	v_mfma_f32_16x16x32_bf16 v[88:91], v[156:159], v[216:219], v[88:91]
	v_mfma_f32_16x16x32_bf16 v[76:79], v[148:151], v[224:227], v[76:79]
	v_mfma_f32_16x16x32_bf16 v[72:75], v[156:159], v[224:227], v[72:75]
	s_setprio 0
	s_setprio 1
	v_mfma_f32_16x16x32_bf16 v[116:119], v[160:163], v[188:191], v[116:119]
	v_mfma_f32_16x16x32_bf16 v[112:115], v[168:171], v[188:191], v[112:115]
	v_mfma_f32_16x16x32_bf16 v[100:103], v[160:163], v[204:207], v[100:103]
	v_mfma_f32_16x16x32_bf16 v[96:99], v[168:171], v[204:207], v[96:99]
	v_mfma_f32_16x16x32_bf16 v[84:87], v[160:163], v[212:215], v[84:87]
	v_mfma_f32_16x16x32_bf16 v[80:83], v[168:171], v[212:215], v[80:83]
	v_mfma_f32_16x16x32_bf16 v[68:71], v[160:163], v[220:223], v[68:71]
	v_mfma_f32_16x16x32_bf16 v[64:67], v[168:171], v[220:223], v[64:67]
	v_mfma_f32_16x16x32_bf16 v[116:119], v[164:167], v[200:203], v[116:119]
	v_mfma_f32_16x16x32_bf16 v[112:115], v[184:187], v[200:203], v[112:115]
	v_mfma_f32_16x16x32_bf16 v[100:103], v[164:167], v[208:211], v[100:103]
	v_mfma_f32_16x16x32_bf16 v[96:99], v[184:187], v[208:211], v[96:99]
	v_mfma_f32_16x16x32_bf16 v[84:87], v[164:167], v[216:219], v[84:87]
	v_mfma_f32_16x16x32_bf16 v[80:83], v[184:187], v[216:219], v[80:83]
	v_mfma_f32_16x16x32_bf16 v[68:71], v[164:167], v[224:227], v[68:71]
	v_mfma_f32_16x16x32_bf16 v[64:67], v[184:187], v[224:227], v[64:67]
	s_setprio 0
	s_barrier
; #define PG8_STAGE(bufoff, gbase, voff) do { _Pragma("unroll") for (int _i = 0; _i < 2; ++_i) \
;         __builtin_amdgcn_global_load_lds((const unsigned*)((const char*)(gbase) + (voff)[_i]), (PG8_LAS unsigned*)(lds + (bufoff) + ldsw + _i * 8192), 16, 0, 0); } while (0)
; #define PG8_LDA(dst, b, h) do { _Pragma("unroll") for (int m = 0; m < 4; ++m) _Pragma("unroll") for (int k = 0; k < 2; ++k) dst[m][k] = *(const PG8_LAS bf16x8*)(lds + PG8_SA(b, h) + aoff + m * 2048 + k * 1024); } while (0)
; #define PG8_LDB(dst, b, h) do { _Pragma("unroll") for (int n = 0; n < 2; ++n) _Pragma("unroll") for (int k = 0; k < 2; ++k) dst[n][k] = *(const PG8_LAS bf16x8*)(lds + PG8_SB(b, h) + boff + n * 2048 + k * 1024); } while (0)
; template <class Epi, class Sched, bool ALIGN_EPI = false, bool SP2 = false>
; __device__ __forceinline__ void gemm_phase(PG8_LAS unsigned char* lds, const Gemm g, const Sched& S, const Epi& E) {
;     ...
;         for (int t = 0; t < nt; t += 2) {
;             const bool last = (t == nt - 2);
;             const char* a1 = cA + (size_t)(t + 1) * kstep;
;             const char* a2 = last ? nA : cA + (size_t)(t + 2) * kstep; const char* b2 = last ? nB : cB + (size_t)(t + 2) * kstep;
;             const char* a3 = a2 + kstep; const char* b3 = b2 + kstep;
;             if (last && has_next) S.a_ready(nxt);
;             if constexpr (SP2) {
;             PG8_LDB(B0, 0, 0); PG8_LDB(B1, 0, 1); PG8_SCHED; PG8_LDA(At, 0, 0); PG8_STAGE(PG8_SA(1, 1), a1 + hA, voffA);
;             PG8_WAIT_V(8); PG8_WAIT_L(0); PG8_BAR; PG8_MMA(0, 0, At, B0); PG8_MMA(0, 1, At, B1); PG8_BAR; PG8_SCHED;
;             PG8_LDA(At, 0, 1); PG8_STAGE(PG8_SB(0, 0), b2, voffB); PG8_STAGE(PG8_SB(0, 1), b2 + hB, voffB); PG8_STAGE(PG8_SA(0, 0), a2, voffA);
;             PG8_WAIT_V(8); PG8_WAIT_L(0); PG8_BAR; PG8_MMA(1, 0, At, B0); PG8_MMA(1, 1, At, B1); PG8_BAR; PG8_SCHED;
;             PG8_LDB(B0, 1, 0); PG8_LDB(B1, 1, 1); PG8_SCHED; PG8_LDA(At, 1, 0); PG8_STAGE(PG8_SA(0, 1), a2 + hA, voffA);
;             PG8_WAIT_V(8); PG8_WAIT_L(0); PG8_BAR; PG8_MMA(0, 0, At, B0); PG8_MMA(0, 1, At, B1); PG8_BAR; PG8_SCHED;
;             PG8_LDA(At, 1, 1); PG8_STAGE(PG8_SB(1, 0), b3, voffB); PG8_STAGE(PG8_SB(1, 1), b3 + hB, voffB); PG8_STAGE(PG8_SA(1, 0), a3, voffA);
;             PG8_WAIT_V(8); PG8_WAIT_L(0); PG8_BAR; PG8_MMA(1, 0, At, B0); PG8_MMA(1, 1, At, B1); PG8_BAR; PG8_SCHED;
	s_add_i32 s10, s34, s18
	v_lshl_add_u64 v[138:139], v[138:139], 0, s[76:77]
	s_mov_b32 m0, s10
	ds_read_b128 v[188:191], v143 offset:49152
	ds_read_b128 v[200:203], v143 offset:50176
	ds_read_b128 v[204:207], v143 offset:51200
	ds_read_b128 v[208:211], v143 offset:52224
	ds_read_b128 v[212:215], v143 offset:53248
	ds_read_b128 v[216:219], v143 offset:54272
	ds_read_b128 v[220:223], v143 offset:55296
	ds_read_b128 v[224:227], v143 offset:56320
	global_load_lds_dwordx4 v[138:139], off
	s_add_i32 m0, s10, 0x2000
	s_add_u32 s10, s14, 0x18080
	v_lshl_add_u64 v[138:139], v[174:175], 0, s[76:77]
	s_addc_u32 s11, s15, 0
	s_add_i32 s14, s35, s18
	global_load_lds_dwordx4 v[138:139], off
	s_mov_b32 m0, s14
	s_nop 0
	global_load_lds_dwordx4 v172, s[10:11]
	s_add_i32 m0, s14, 0x2000
	s_nop 0
	global_load_lds_dwordx4 v128, s[10:11]
	v_lshl_add_u64 v[138:139], v[176:177], 0, s[76:77]
	s_mov_b32 m0, s43
	s_nop 0
	global_load_lds_dwordx4 v[138:139], off
	v_lshl_add_u64 v[138:139], v[180:181], 0, s[76:77]
	s_mov_b32 m0, s44
	s_nop 0
	global_load_lds_dwordx4 v[138:139], off
	s_waitcnt vmcnt(8)
	s_waitcnt lgkmcnt(0)
	s_barrier
	s_setprio 1
	s_waitcnt lgkmcnt(0)
	v_mfma_f32_16x16x32_bf16 v[60:63], v[144:147], v[188:191], v[60:63]
	v_mfma_f32_16x16x32_bf16 v[56:59], v[152:155], v[188:191], v[56:59]
	v_mfma_f32_16x16x32_bf16 v[44:47], v[144:147], v[204:207], v[44:47]
	v_mfma_f32_16x16x32_bf16 v[40:43], v[152:155], v[204:207], v[40:43]
	v_mfma_f32_16x16x32_bf16 v[28:31], v[144:147], v[212:215], v[28:31]
	v_mfma_f32_16x16x32_bf16 v[24:27], v[152:155], v[212:215], v[24:27]
	v_mfma_f32_16x16x32_bf16 v[12:15], v[144:147], v[220:223], v[12:15]
	v_mfma_f32_16x16x32_bf16 v[8:11], v[152:155], v[220:223], v[8:11]
	v_mfma_f32_16x16x32_bf16 v[60:63], v[148:151], v[200:203], v[60:63]
	v_mfma_f32_16x16x32_bf16 v[56:59], v[156:159], v[200:203], v[56:59]
	v_mfma_f32_16x16x32_bf16 v[44:47], v[148:151], v[208:211], v[44:47]
	v_mfma_f32_16x16x32_bf16 v[40:43], v[156:159], v[208:211], v[40:43]
	v_mfma_f32_16x16x32_bf16 v[28:31], v[148:151], v[216:219], v[28:31]
	v_mfma_f32_16x16x32_bf16 v[24:27], v[156:159], v[216:219], v[24:27]
	v_mfma_f32_16x16x32_bf16 v[12:15], v[148:151], v[224:227], v[12:15]
	v_mfma_f32_16x16x32_bf16 v[8:11], v[156:159], v[224:227], v[8:11]
	s_setprio 0
	s_setprio 1
	v_mfma_f32_16x16x32_bf16 v[52:55], v[160:163], v[188:191], v[52:55]
	v_mfma_f32_16x16x32_bf16 v[48:51], v[168:171], v[188:191], v[48:51]
	v_mfma_f32_16x16x32_bf16 v[36:39], v[160:163], v[204:207], v[36:39]
	v_mfma_f32_16x16x32_bf16 v[32:35], v[168:171], v[204:207], v[32:35]
	v_mfma_f32_16x16x32_bf16 v[20:23], v[160:163], v[212:215], v[20:23]
	v_mfma_f32_16x16x32_bf16 v[16:19], v[168:171], v[212:215], v[16:19]
	v_mfma_f32_16x16x32_bf16 v[4:7], v[160:163], v[220:223], v[4:7]
	v_mfma_f32_16x16x32_bf16 v[0:3], v[168:171], v[220:223], v[0:3]
	v_mfma_f32_16x16x32_bf16 v[52:55], v[164:167], v[200:203], v[52:55]
	v_mfma_f32_16x16x32_bf16 v[48:51], v[184:187], v[200:203], v[48:51]
	v_mfma_f32_16x16x32_bf16 v[36:39], v[164:167], v[208:211], v[36:39]
	v_mfma_f32_16x16x32_bf16 v[32:35], v[184:187], v[208:211], v[32:35]
	v_mfma_f32_16x16x32_bf16 v[20:23], v[164:167], v[216:219], v[20:23]
	v_mfma_f32_16x16x32_bf16 v[16:19], v[184:187], v[216:219], v[16:19]
	v_mfma_f32_16x16x32_bf16 v[4:7], v[164:167], v[224:227], v[4:7]
	v_mfma_f32_16x16x32_bf16 v[0:3], v[184:187], v[224:227], v[0:3]
	s_setprio 0
	s_barrier
	s_add_i32 s71, s71, 2
	s_add_u32 s68, s68, 0x100
	s_addc_u32 s70, s70, 0
	s_cmp_gt_u32 s71, 3
	s_mov_b64 s[10:11], s[12:13]
	s_cbranch_scc0 .LBB0_356
	s_and_b64 vcc, exec, s[6:7]
	s_cbranch_vccz .LBB0_359
	s_barrier

; #define PG8_STAGE(bufoff, gbase, voff) do { _Pragma("unroll") for (int _i = 0; _i < 2; ++_i) \
;         __builtin_amdgcn_global_load_lds((const unsigned*)((const char*)(gbase) + (voff)[_i]), (PG8_LAS unsigned*)(lds + (bufoff) + ldsw + _i * 8192), 16, 0, 0); } while (0)
; #define PG8_WAIT_V(n) asm volatile("s_waitcnt vmcnt(" #n ")" ::: "memory")
; #define PG8_BAR __builtin_amdgcn_s_barrier()
; template <class Epi, class Sched, bool ALIGN_EPI = false, bool SP2 = false>
; __device__ __forceinline__ void gemm_phase(PG8_LAS unsigned char* lds, const Gemm g, const Sched& S, const Epi& E) {
;     int tid_ = threadIdx.x; asm volatile("" : "+v"(tid_)); const int tid = tid_, wid = __builtin_amdgcn_readfirstlane(tid >> 6), lane = tid & 63, wr = wid >> 2, wc = wid & 3, fr = lane & 15, fq = lane >> 4;
;     const int K = g.K, nt = K / BK;
;     unsigned voffA[2], voffB[2];
; #pragma unroll
;     for (int i = 0; i < 2; ++i) { int R, C; stage_rc(tid * 16 + i * 8192, R, C); const int Rb = Epi::PERM ? ((R & ~31) + perm32(R & 31)) : R;
;         voffA[i] = (unsigned)(R * g.lda + C) * 2u; voffB[i] = (unsigned)(Rb * g.ldb + C) * 2u; }
;     const size_t kstep = (size_t)(BK * 2);
;     const size_t hA = (size_t)HALF * g.lda * 2, hB = (size_t)HALF * g.ldb * 2;
;     const size_t tA = 2 * hA, tB = 2 * hB;
;     const unsigned ldsw = (unsigned)wid * 1024u;
;     const int aoff = lds_byte(wr * 64 + fr, fq * 8), boff = lds_byte(wc * 32 + fr, fq * 8);
;     ...
;     if constexpr (SP2) {
;         PG8_STAGE(PG8_SB(0, 0), cB, voffB); PG8_STAGE(PG8_SB(0, 1), cB + hB, voffB); PG8_STAGE(PG8_SA(0, 0), cA, voffA); PG8_STAGE(PG8_SA(0, 1), cA + hA, voffA);
;         if (wr == 1) PG8_BAR;
;         PG8_WAIT_V(2); PG8_BAR;
;         PG8_STAGE(PG8_SB(1, 0), cB + kstep, voffB); PG8_STAGE(PG8_SA(1, 0), cA + kstep, voffA); PG8_STAGE(PG8_SB(1, 1), cB + hB + kstep, voffB);
;         PG8_WAIT_V(6); PG8_BAR;
.LBB0_366:
	v_lshrrev_b32_e32 v10, 1, v0
	v_and_b32_e32 v10, 24, v10
	v_readlane_b32 s16, v254, 23
	v_and_b32_e32 v1, 15, v0
	v_lshlrev_b32_e32 v11, 1, v10
	v_lshlrev_b32_e32 v0, 2, v0
	v_mov_b32_e32 v133, v173
	v_readlane_b32 s17, v254, 24
	s_and_b32 s1, s1, 3
	v_lshl_or_b32 v137, s6, 6, v1
	v_lshl_or_b32 v1, v1, 6, v11
	s_lshl_b32 s6, s6, 13
	v_and_b32_e32 v0, 32, v0
	v_lshl_add_u64 v[2:3], s[16:17], 0, v[132:133]
	v_mov_b32_e32 v129, v173
	v_readlane_b32 s18, v254, 19
	v_bitop3_b32 v11, v1, s6, v0 bitop3:0xde
	s_lshl_b32 s6, s1, 12
	v_lshl_add_u64 v[4:5], s[16:17], 0, v[128:129]
	v_mov_b32_e32 v135, v173
	v_readlane_b32 s19, v254, 20
	v_bitop3_b32 v146, v1, s6, v0 bitop3:0xde
	s_add_i32 m0, s60, 0x18000
	v_lshl_add_u64 v[0:1], v[2:3], 0, s[76:77]
	v_lshl_add_u64 v[6:7], s[18:19], 0, v[134:135]
	v_mov_b32_e32 v131, v173
	s_waitcnt vmcnt(2)
	s_barrier
	global_load_lds_dwordx4 v[0:1], off
	v_lshl_add_u64 v[0:1], v[4:5], 0, s[76:77]
	s_add_i32 m0, s60, 0x1a000
	s_add_i32 s85, s60, 0x8000
	v_lshl_add_u64 v[8:9], s[18:19], 0, v[130:131]
	global_load_lds_dwordx4 v[0:1], off
	v_lshl_add_u64 v[0:1], v[6:7], 0, s[76:77]
	s_mov_b32 m0, s85
	s_add_i32 s79, s60, 0xa000
	v_readlane_b32 s6, v254, 25
	global_load_lds_dwordx4 v[0:1], off
	v_lshl_add_u64 v[0:1], v[8:9], 0, s[76:77]
	s_mov_b32 m0, s79
	v_readlane_b32 s7, v254, 26
	global_load_lds_dwordx4 v[0:1], off
	s_add_i32 m0, s60, 0x1c000
	s_nop 0
	s_nop 1
	global_load_lds_dwordx4 v132, s[6:7]
	s_add_i32 m0, s60, 0x1e000
	s_cmpk_lt_u32 s0, 0x100
	global_load_lds_dwordx4 v128, s[6:7]
	s_waitcnt vmcnt(6)
	s_cselect_b64 s[6:7], -1, 0
	v_lshl_or_b32 v136, s1, 5, v10
	s_cmp_gt_u32 s1, 1
	v_readlane_b32 s0, v254, 39
	s_cselect_b64 s[8:9], -1, 0
	v_subrev_u32_e32 v147, 64, v136
	s_mov_b32 s84, 0
	v_add_u32_e32 v148, 0, v11
	v_readlane_b32 s51, v253, 36
	s_mov_b32 s50, s0
	s_barrier
	v_readlane_b32 s1, v254, 40
	s_branch .LBB0_369

; #define PG8_STAGE(bufoff, gbase, voff) do { _Pragma("unroll") for (int _i = 0; _i < 2; ++_i) \
;         __builtin_amdgcn_global_load_lds((const unsigned*)((const char*)(gbase) + (voff)[_i]), (PG8_LAS unsigned*)(lds + (bufoff) + ldsw + _i * 8192), 16, 0, 0); } while (0)
; #define PG8_LDA(dst, b, h) do { _Pragma("unroll") for (int m = 0; m < 4; ++m) _Pragma("unroll") for (int k = 0; k < 2; ++k) dst[m][k] = *(const PG8_LAS bf16x8*)(lds + PG8_SA(b, h) + aoff + m * 2048 + k * 1024); } while (0)
; #define PG8_LDB(dst, b, h) do { _Pragma("unroll") for (int n = 0; n < 2; ++n) _Pragma("unroll") for (int k = 0; k < 2; ++k) dst[n][k] = *(const PG8_LAS bf16x8*)(lds + PG8_SB(b, h) + boff + n * 2048 + k * 1024); } while (0)
; #define PG8_MMA(ai, bj, At, Bt) do { __builtin_amdgcn_s_setprio(1); _Pragma("unroll") for (int m = 0; m < 4; ++m) _Pragma("unroll") for (int n = 0; n < 2; ++n) _Pragma("unroll") for (int k = 0; k < 2; ++k) \
;         acc[ai][bj][m][n] = __builtin_amdgcn_mfma_f32_16x16x32_bf16(Bt[n][k], At[m][k], acc[ai][bj][m][n], 0, 0, 0); __builtin_amdgcn_s_setprio(0); } while (0)
; #define PG8_BAR __builtin_amdgcn_s_barrier()
; template <class Epi, class Sched, bool ALIGN_EPI = false, bool SP2 = false>
; __device__ __forceinline__ void gemm_phase(PG8_LAS unsigned char* lds, const Gemm g, const Sched& S, const Epi& E) {
;     ...
;             if constexpr (SP2) {
;             PG8_LDB(B0, 0, 0); PG8_LDB(B1, 0, 1); PG8_SCHED; PG8_LDA(At, 0, 0); PG8_STAGE(PG8_SA(1, 1), a1 + hA, voffA);
;             PG8_WAIT_V(8); PG8_WAIT_L(0); PG8_BAR; PG8_MMA(0, 0, At, B0); PG8_MMA(0, 1, At, B1); PG8_BAR; PG8_SCHED;
;             PG8_LDA(At, 0, 1); PG8_STAGE(PG8_SB(0, 0), b2, voffB); PG8_STAGE(PG8_SB(0, 1), b2 + hB, voffB); PG8_STAGE(PG8_SA(0, 0), a2, voffA);
;             PG8_WAIT_V(8); PG8_WAIT_L(0); PG8_BAR; PG8_MMA(1, 0, At, B0); PG8_MMA(1, 1, At, B1); PG8_BAR; PG8_SCHED;
;             PG8_LDB(B0, 1, 0); PG8_LDB(B1, 1, 1); PG8_SCHED; PG8_LDA(At, 1, 0); PG8_STAGE(PG8_SA(0, 1), a2 + hA, voffA);
;             PG8_WAIT_V(8); PG8_WAIT_L(0); PG8_BAR; PG8_MMA(0, 0, At, B0); PG8_MMA(0, 1, At, B1); PG8_BAR; PG8_SCHED;
;             PG8_LDA(At, 1, 1); PG8_STAGE(PG8_SB(1, 0), b3, voffB); PG8_STAGE(PG8_SB(1, 1), b3 + hB, voffB); PG8_STAGE(PG8_SA(1, 0), a3, voffA);
;             PG8_WAIT_V(8); PG8_WAIT_L(0); PG8_BAR; PG8_MMA(1, 0, At, B0); PG8_MMA(1, 1, At, B1); PG8_BAR; PG8_SCHED;
.LBB0_378:
	s_add_u32 s40, s18, s44
	s_addc_u32 s41, s19, s45
	s_add_u32 s46, s40, 0x100
	s_addc_u32 s47, s41, 0
	s_and_b64 s[34:35], s[30:31], exec
	s_cselect_b32 s47, s13, s47
	s_cselect_b32 s46, s12, s46
	s_add_u32 s34, s16, s44
	s_addc_u32 s35, s17, s45
	s_add_u32 s34, s34, 0x100
	s_addc_u32 s35, s35, 0
	s_add_i32 s58, 0, 0x10000
	s_and_b64 s[30:31], s[30:31], exec
	s_cselect_b32 vcc_hi, s11, s35
	s_cselect_b32 vcc_lo, s75, s34
	s_add_i32 s31, 0, 0x14000
	s_add_u32 s70, s40, 0x1e0080
	s_addc_u32 s71, s41, 0
	s_add_i32 s57, s58, s68
	s_add_i32 m0, s60, 0xc000
	s_add_i32 s90, s60, 0xe000
	s_add_i32 s54, s57, 0x2000
	v_add_u32_e32 v149, s58, v146
	s_add_u32 s40, vcc_lo, 0x10000
	ds_read_b128 v[138:141], v149
	ds_read_b128 v[142:145], v149 offset:1024
	ds_read_b128 v[150:153], v149 offset:2048
	ds_read_b128 v[154:157], v149 offset:3072
	v_add_u32_e32 v149, s31, v146
	s_addc_u32 s41, vcc_hi, 0
	s_add_i32 s55, s31, s68
	ds_read_b128 v[158:161], v149
	ds_read_b128 v[162:165], v149 offset:1024
	ds_read_b128 v[166:169], v149 offset:2048
	ds_read_b128 v[184:187], v149 offset:3072
	s_add_i32 s56, s55, 0x2000
	s_add_i32 s53, 0, 0x18000
	s_add_i32 s52, 0, 0x1c000
	s_add_u32 s44, s46, 0x1e0000
	s_addc_u32 s45, s47, 0
	s_add_i32 s35, s53, s68
	s_add_i32 s34, s35, 0x2000
	s_add_u32 s30, vcc_lo, 0x10080
	s_addc_u32 s31, vcc_hi, 0
	s_add_i32 s59, s52, s68
	s_add_i32 s58, s59, 0x2000
	ds_read_b128 v[188:191], v148
	ds_read_b128 v[200:203], v148 offset:1024
	ds_read_b128 v[204:207], v148 offset:2048
	ds_read_b128 v[208:211], v148 offset:3072
	ds_read_b128 v[212:215], v148 offset:4096
	ds_read_b128 v[216:219], v148 offset:5120
	ds_read_b128 v[220:223], v148 offset:6144
	ds_read_b128 v[224:227], v148 offset:7168
	global_load_lds_dwordx4 v134, s[70:71]
	s_mov_b32 m0, s90
	s_nop 0
	global_load_lds_dwordx4 v130, s[70:71]
	s_waitcnt vmcnt(8)
	s_waitcnt lgkmcnt(0)
	s_barrier
	s_setprio 1
	s_waitcnt lgkmcnt(0)
	v_mfma_f32_16x16x32_bf16 v[124:127], v[138:141], v[188:191], v[124:127]
	v_mfma_f32_16x16x32_bf16 v[120:123], v[150:153], v[188:191], v[120:123]
	v_mfma_f32_16x16x32_bf16 v[108:111], v[138:141], v[204:207], v[108:111]
	v_mfma_f32_16x16x32_bf16 v[104:107], v[150:153], v[204:207], v[104:107]
	v_mfma_f32_16x16x32_bf16 v[92:95], v[138:141], v[212:215], v[92:95]
	v_mfma_f32_16x16x32_bf16 v[88:91], v[150:153], v[212:215], v[88:91]
	v_mfma_f32_16x16x32_bf16 v[76:79], v[138:141], v[220:223], v[76:79]
	v_mfma_f32_16x16x32_bf16 v[72:75], v[150:153], v[220:223], v[72:75]
	v_mfma_f32_16x16x32_bf16 v[124:127], v[142:145], v[200:203], v[124:127]
	v_mfma_f32_16x16x32_bf16 v[120:123], v[154:157], v[200:203], v[120:123]
	v_mfma_f32_16x16x32_bf16 v[108:111], v[142:145], v[208:211], v[108:111]
	v_mfma_f32_16x16x32_bf16 v[104:107], v[154:157], v[208:211], v[104:107]
	v_mfma_f32_16x16x32_bf16 v[92:95], v[142:145], v[216:219], v[92:95]
	v_mfma_f32_16x16x32_bf16 v[88:91], v[154:157], v[216:219], v[88:91]
	v_mfma_f32_16x16x32_bf16 v[76:79], v[142:145], v[224:227], v[76:79]
	v_mfma_f32_16x16x32_bf16 v[72:75], v[154:157], v[224:227], v[72:75]
	s_setprio 0
	s_setprio 1
	v_mfma_f32_16x16x32_bf16 v[116:119], v[158:161], v[188:191], v[116:119]
	v_mfma_f32_16x16x32_bf16 v[112:115], v[166:169], v[188:191], v[112:115]
	v_mfma_f32_16x16x32_bf16 v[100:103], v[158:161], v[204:207], v[100:103]
	v_mfma_f32_16x16x32_bf16 v[96:99], v[166:169], v[204:207], v[96:99]
	v_mfma_f32_16x16x32_bf16 v[84:87], v[158:161], v[212:215], v[84:87]
	v_mfma_f32_16x16x32_bf16 v[80:83], v[166:169], v[212:215], v[80:83]
	v_mfma_f32_16x16x32_bf16 v[68:71], v[158:161], v[220:223], v[68:71]
	v_mfma_f32_16x16x32_bf16 v[64:67], v[166:169], v[220:223], v[64:67]
	v_mfma_f32_16x16x32_bf16 v[116:119], v[162:165], v[200:203], v[116:119]
	v_mfma_f32_16x16x32_bf16 v[112:115], v[184:187], v[200:203], v[112:115]
	v_mfma_f32_16x16x32_bf16 v[100:103], v[162:165], v[208:211], v[100:103]
	v_mfma_f32_16x16x32_bf16 v[96:99], v[184:187], v[208:211], v[96:99]
	v_mfma_f32_16x16x32_bf16 v[84:87], v[162:165], v[216:219], v[84:87]
	v_mfma_f32_16x16x32_bf16 v[80:83], v[184:187], v[216:219], v[80:83]
	v_mfma_f32_16x16x32_bf16 v[68:71], v[162:165], v[224:227], v[68:71]
	v_mfma_f32_16x16x32_bf16 v[64:67], v[184:187], v[224:227], v[64:67]
	s_setprio 0
	s_barrier
	s_mov_b32 m0, s57
	v_lshl_add_u64 v[170:171], vcc, 0, v[132:133]
	ds_read_b128 v[188:191], v148 offset:16384
	ds_read_b128 v[200:203], v148 offset:17408
	ds_read_b128 v[204:207], v148 offset:18432
	ds_read_b128 v[208:211], v148 offset:19456
	ds_read_b128 v[212:215], v148 offset:20480
	ds_read_b128 v[216:219], v148 offset:21504
	ds_read_b128 v[220:223], v148 offset:22528
	ds_read_b128 v[224:227], v148 offset:23552
	global_load_lds_dwordx4 v[170:171], off
	v_lshl_add_u64 v[174:175], vcc, 0, v[128:129]
	s_mov_b32 m0, s54
	s_nop 0
	global_load_lds_dwordx4 v[174:175], off
	s_mov_b32 m0, s55
	v_lshl_add_u64 v[180:181], s[46:47], 0, v[130:131]
	global_load_lds_dwordx4 v132, s[40:41]
	s_mov_b32 m0, s56
	s_nop 0
	global_load_lds_dwordx4 v128, s[40:41]
	v_lshl_add_u64 v[176:177], s[46:47], 0, v[134:135]
	s_mov_b32 m0, s60
	s_nop 0
	global_load_lds_dwordx4 v134, s[46:47]
	s_mov_b32 m0, s91
	s_nop 0
	global_load_lds_dwordx4 v130, s[46:47]
	s_waitcnt vmcnt(8)
	s_waitcnt lgkmcnt(0)
	s_barrier
; #define PG8_STAGE(bufoff, gbase, voff) do { _Pragma("unroll") for (int _i = 0; _i < 2; ++_i) \
;         __builtin_amdgcn_global_load_lds((const unsigned*)((const char*)(gbase) + (voff)[_i]), (PG8_LAS unsigned*)(lds + (bufoff) + ldsw + _i * 8192), 16, 0, 0); } while (0)
; #define PG8_LDA(dst, b, h) do { _Pragma("unroll") for (int m = 0; m < 4; ++m) _Pragma("unroll") for (int k = 0; k < 2; ++k) dst[m][k] = *(const PG8_LAS bf16x8*)(lds + PG8_SA(b, h) + aoff + m * 2048 + k * 1024); } while (0)
; #define PG8_LDB(dst, b, h) do { _Pragma("unroll") for (int n = 0; n < 2; ++n) _Pragma("unroll") for (int k = 0; k < 2; ++k) dst[n][k] = *(const PG8_LAS bf16x8*)(lds + PG8_SB(b, h) + boff + n * 2048 + k * 1024); } while (0)
; #define PG8_MMA(ai, bj, At, Bt) do { __builtin_amdgcn_s_setprio(1); _Pragma("unroll") for (int m = 0; m < 4; ++m) _Pragma("unroll") for (int n = 0; n < 2; ++n) _Pragma("unroll") for (int k = 0; k < 2; ++k) \
;         acc[ai][bj][m][n] = __builtin_amdgcn_mfma_f32_16x16x32_bf16(Bt[n][k], At[m][k], acc[ai][bj][m][n], 0, 0, 0); __builtin_amdgcn_s_setprio(0); } while (0)
; #define PG8_BAR __builtin_amdgcn_s_barrier()
; template <class Epi, class Sched, bool ALIGN_EPI = false, bool SP2 = false>
; __device__ __forceinline__ void gemm_phase(PG8_LAS unsigned char* lds, const Gemm g, const Sched& S, const Epi& E) {
;     ...
;             if constexpr (SP2) {
;             PG8_LDB(B0, 0, 0); PG8_LDB(B1, 0, 1); PG8_SCHED; PG8_LDA(At, 0, 0); PG8_STAGE(PG8_SA(1, 1), a1 + hA, voffA);
;             PG8_WAIT_V(8); PG8_WAIT_L(0); PG8_BAR; PG8_MMA(0, 0, At, B0); PG8_MMA(0, 1, At, B1); PG8_BAR; PG8_SCHED;
;             PG8_LDA(At, 0, 1); PG8_STAGE(PG8_SB(0, 0), b2, voffB); PG8_STAGE(PG8_SB(0, 1), b2 + hB, voffB); PG8_STAGE(PG8_SA(0, 0), a2, voffA);
;             PG8_WAIT_V(8); PG8_WAIT_L(0); PG8_BAR; PG8_MMA(1, 0, At, B0); PG8_MMA(1, 1, At, B1); PG8_BAR; PG8_SCHED;
;             PG8_LDB(B0, 1, 0); PG8_LDB(B1, 1, 1); PG8_SCHED; PG8_LDA(At, 1, 0); PG8_STAGE(PG8_SA(0, 1), a2 + hA, voffA);
;             PG8_WAIT_V(8); PG8_WAIT_L(0); PG8_BAR; PG8_MMA(0, 0, At, B0); PG8_MMA(0, 1, At, B1); PG8_BAR; PG8_SCHED;
;             PG8_LDA(At, 1, 1); PG8_STAGE(PG8_SB(1, 0), b3, voffB); PG8_STAGE(PG8_SB(1, 1), b3 + hB, voffB); PG8_STAGE(PG8_SA(1, 0), a3, voffA);
;             PG8_WAIT_V(8); PG8_WAIT_L(0); PG8_BAR; PG8_MMA(1, 0, At, B0); PG8_MMA(1, 1, At, B1); PG8_BAR; PG8_SCHED;
	s_setprio 1
	s_waitcnt lgkmcnt(0)
	v_mfma_f32_16x16x32_bf16 v[60:63], v[138:141], v[188:191], v[60:63]
	v_mfma_f32_16x16x32_bf16 v[56:59], v[150:153], v[188:191], v[56:59]
	v_mfma_f32_16x16x32_bf16 v[44:47], v[138:141], v[204:207], v[44:47]
	v_mfma_f32_16x16x32_bf16 v[40:43], v[150:153], v[204:207], v[40:43]
	v_mfma_f32_16x16x32_bf16 v[28:31], v[138:141], v[212:215], v[28:31]
	v_mfma_f32_16x16x32_bf16 v[24:27], v[150:153], v[212:215], v[24:27]
	v_mfma_f32_16x16x32_bf16 v[12:15], v[138:141], v[220:223], v[12:15]
	v_mfma_f32_16x16x32_bf16 v[8:11], v[150:153], v[220:223], v[8:11]
	v_mfma_f32_16x16x32_bf16 v[60:63], v[142:145], v[200:203], v[60:63]
	v_mfma_f32_16x16x32_bf16 v[56:59], v[154:157], v[200:203], v[56:59]
	v_mfma_f32_16x16x32_bf16 v[44:47], v[142:145], v[208:211], v[44:47]
	v_mfma_f32_16x16x32_bf16 v[40:43], v[154:157], v[208:211], v[40:43]
	v_mfma_f32_16x16x32_bf16 v[28:31], v[142:145], v[216:219], v[28:31]
	v_mfma_f32_16x16x32_bf16 v[24:27], v[154:157], v[216:219], v[24:27]
	v_mfma_f32_16x16x32_bf16 v[12:15], v[142:145], v[224:227], v[12:15]
	v_mfma_f32_16x16x32_bf16 v[8:11], v[154:157], v[224:227], v[8:11]
	s_setprio 0
	s_setprio 1
	v_mfma_f32_16x16x32_bf16 v[52:55], v[158:161], v[188:191], v[52:55]
	v_mfma_f32_16x16x32_bf16 v[48:51], v[166:169], v[188:191], v[48:51]
	v_mfma_f32_16x16x32_bf16 v[36:39], v[158:161], v[204:207], v[36:39]
	v_mfma_f32_16x16x32_bf16 v[32:35], v[166:169], v[204:207], v[32:35]
	v_mfma_f32_16x16x32_bf16 v[20:23], v[158:161], v[212:215], v[20:23]
	v_mfma_f32_16x16x32_bf16 v[16:19], v[166:169], v[212:215], v[16:19]
	v_mfma_f32_16x16x32_bf16 v[4:7], v[158:161], v[220:223], v[4:7]
	v_mfma_f32_16x16x32_bf16 v[0:3], v[166:169], v[220:223], v[0:3]
	v_mfma_f32_16x16x32_bf16 v[52:55], v[162:165], v[200:203], v[52:55]
	v_mfma_f32_16x16x32_bf16 v[48:51], v[184:187], v[200:203], v[48:51]
	v_mfma_f32_16x16x32_bf16 v[36:39], v[162:165], v[208:211], v[36:39]
	v_mfma_f32_16x16x32_bf16 v[32:35], v[184:187], v[208:211], v[32:35]
	v_mfma_f32_16x16x32_bf16 v[20:23], v[162:165], v[216:219], v[20:23]
	v_mfma_f32_16x16x32_bf16 v[16:19], v[184:187], v[216:219], v[16:19]
	v_mfma_f32_16x16x32_bf16 v[4:7], v[162:165], v[224:227], v[4:7]
	v_mfma_f32_16x16x32_bf16 v[0:3], v[184:187], v[224:227], v[0:3]
	s_setprio 0
	s_barrier
	v_add_u32_e32 v149, s53, v146
	ds_read_b128 v[138:141], v149
	ds_read_b128 v[142:145], v149 offset:1024
	ds_read_b128 v[150:153], v149 offset:2048
	ds_read_b128 v[154:157], v149 offset:3072
	v_add_u32_e32 v149, s52, v146
	ds_read_b128 v[158:161], v149
	ds_read_b128 v[162:165], v149 offset:1024
	ds_read_b128 v[166:169], v149 offset:2048
	ds_read_b128 v[184:187], v149 offset:3072
	s_mov_b32 m0, s95
	ds_read_b128 v[188:191], v148 offset:32768
	ds_read_b128 v[200:203], v148 offset:33792
	ds_read_b128 v[204:207], v148 offset:34816
	ds_read_b128 v[208:211], v148 offset:35840
	ds_read_b128 v[212:215], v148 offset:36864
	ds_read_b128 v[216:219], v148 offset:37888
	ds_read_b128 v[220:223], v148 offset:38912
	ds_read_b128 v[224:227], v148 offset:39936
	global_load_lds_dwordx4 v134, s[44:45]
	s_mov_b32 m0, s97
	s_nop 0
	global_load_lds_dwordx4 v130, s[44:45]
	s_waitcnt vmcnt(8)
	s_waitcnt lgkmcnt(0)
	s_barrier
	s_setprio 1
	s_waitcnt lgkmcnt(0)
	v_mfma_f32_16x16x32_bf16 v[124:127], v[138:141], v[188:191], v[124:127]
	v_mfma_f32_16x16x32_bf16 v[120:123], v[150:153], v[188:191], v[120:123]
	v_mfma_f32_16x16x32_bf16 v[108:111], v[138:141], v[204:207], v[108:111]
	v_mfma_f32_16x16x32_bf16 v[104:107], v[150:153], v[204:207], v[104:107]
	v_mfma_f32_16x16x32_bf16 v[92:95], v[138:141], v[212:215], v[92:95]
	v_mfma_f32_16x16x32_bf16 v[88:91], v[150:153], v[212:215], v[88:91]
	v_mfma_f32_16x16x32_bf16 v[76:79], v[138:141], v[220:223], v[76:79]
	v_mfma_f32_16x16x32_bf16 v[72:75], v[150:153], v[220:223], v[72:75]
	v_mfma_f32_16x16x32_bf16 v[124:127], v[142:145], v[200:203], v[124:127]
	v_mfma_f32_16x16x32_bf16 v[120:123], v[154:157], v[200:203], v[120:123]
	v_mfma_f32_16x16x32_bf16 v[108:111], v[142:145], v[208:211], v[108:111]
	v_mfma_f32_16x16x32_bf16 v[104:107], v[154:157], v[208:211], v[104:107]
	v_mfma_f32_16x16x32_bf16 v[92:95], v[142:145], v[216:219], v[92:95]
	v_mfma_f32_16x16x32_bf16 v[88:91], v[154:157], v[216:219], v[88:91]
	v_mfma_f32_16x16x32_bf16 v[76:79], v[142:145], v[224:227], v[76:79]
	v_mfma_f32_16x16x32_bf16 v[72:75], v[154:157], v[224:227], v[72:75]
	s_setprio 0
	s_setprio 1
	v_mfma_f32_16x16x32_bf16 v[116:119], v[158:161], v[188:191], v[116:119]
	v_mfma_f32_16x16x32_bf16 v[112:115], v[166:169], v[188:191], v[112:115]
	v_mfma_f32_16x16x32_bf16 v[100:103], v[158:161], v[204:207], v[100:103]
	v_mfma_f32_16x16x32_bf16 v[96:99], v[166:169], v[204:207], v[96:99]
	v_mfma_f32_16x16x32_bf16 v[84:87], v[158:161], v[212:215], v[84:87]
	v_mfma_f32_16x16x32_bf16 v[80:83], v[166:169], v[212:215], v[80:83]
	v_mfma_f32_16x16x32_bf16 v[68:71], v[158:161], v[220:223], v[68:71]
	v_mfma_f32_16x16x32_bf16 v[64:67], v[166:169], v[220:223], v[64:67]
	v_mfma_f32_16x16x32_bf16 v[116:119], v[162:165], v[200:203], v[116:119]
	v_mfma_f32_16x16x32_bf16 v[112:115], v[184:187], v[200:203], v[112:115]
	v_mfma_f32_16x16x32_bf16 v[100:103], v[162:165], v[208:211], v[100:103]
	v_mfma_f32_16x16x32_bf16 v[96:99], v[184:187], v[208:211], v[96:99]
	v_mfma_f32_16x16x32_bf16 v[84:87], v[162:165], v[216:219], v[84:87]
	v_mfma_f32_16x16x32_bf16 v[80:83], v[184:187], v[216:219], v[80:83]
	v_mfma_f32_16x16x32_bf16 v[68:71], v[162:165], v[224:227], v[68:71]
	v_mfma_f32_16x16x32_bf16 v[64:67], v[184:187], v[224:227], v[64:67]
	s_setprio 0
	s_barrier
; #define PG8_STAGE(bufoff, gbase, voff) do { _Pragma("unroll") for (int _i = 0; _i < 2; ++_i) \
;         __builtin_amdgcn_global_load_lds((const unsigned*)((const char*)(gbase) + (voff)[_i]), (PG8_LAS unsigned*)(lds + (bufoff) + ldsw + _i * 8192), 16, 0, 0); } while (0)
; #define PG8_LDA(dst, b, h) do { _Pragma("unroll") for (int m = 0; m < 4; ++m) _Pragma("unroll") for (int k = 0; k < 2; ++k) dst[m][k] = *(const PG8_LAS bf16x8*)(lds + PG8_SA(b, h) + aoff + m * 2048 + k * 1024); } while (0)
; #define PG8_LDB(dst, b, h) do { _Pragma("unroll") for (int n = 0; n < 2; ++n) _Pragma("unroll") for (int k = 0; k < 2; ++k) dst[n][k] = *(const PG8_LAS bf16x8*)(lds + PG8_SB(b, h) + boff + n * 2048 + k * 1024); } while (0)
; #define PG8_MMA(ai, bj, At, Bt) do { __builtin_amdgcn_s_setprio(1); _Pragma("unroll") for (int m = 0; m < 4; ++m) _Pragma("unroll") for (int n = 0; n < 2; ++n) _Pragma("unroll") for (int k = 0; k < 2; ++k) \
;         acc[ai][bj][m][n] = __builtin_amdgcn_mfma_f32_16x16x32_bf16(Bt[n][k], At[m][k], acc[ai][bj][m][n], 0, 0, 0); __builtin_amdgcn_s_setprio(0); } while (0)
; #define PG8_BAR __builtin_amdgcn_s_barrier()
; template <class Epi, class Sched, bool ALIGN_EPI = false, bool SP2 = false>
; __device__ __forceinline__ void gemm_phase(PG8_LAS unsigned char* lds, const Gemm g, const Sched& S, const Epi& E) {
;     ...
;             if constexpr (SP2) {
;             PG8_LDB(B0, 0, 0); PG8_LDB(B1, 0, 1); PG8_SCHED; PG8_LDA(At, 0, 0); PG8_STAGE(PG8_SA(1, 1), a1 + hA, voffA);
;             PG8_WAIT_V(8); PG8_WAIT_L(0); PG8_BAR; PG8_MMA(0, 0, At, B0); PG8_MMA(0, 1, At, B1); PG8_BAR; PG8_SCHED;
;             PG8_LDA(At, 0, 1); PG8_STAGE(PG8_SB(0, 0), b2, voffB); PG8_STAGE(PG8_SB(0, 1), b2 + hB, voffB); PG8_STAGE(PG8_SA(0, 0), a2, voffA);
;             PG8_WAIT_V(8); PG8_WAIT_L(0); PG8_BAR; PG8_MMA(1, 0, At, B0); PG8_MMA(1, 1, At, B1); PG8_BAR; PG8_SCHED;
;             PG8_LDB(B0, 1, 0); PG8_LDB(B1, 1, 1); PG8_SCHED; PG8_LDA(At, 1, 0); PG8_STAGE(PG8_SA(0, 1), a2 + hA, voffA);
;             PG8_WAIT_V(8); PG8_WAIT_L(0); PG8_BAR; PG8_MMA(0, 0, At, B0); PG8_MMA(0, 1, At, B1); PG8_BAR; PG8_SCHED;
;             PG8_LDA(At, 1, 1); PG8_STAGE(PG8_SB(1, 0), b3, voffB); PG8_STAGE(PG8_SB(1, 1), b3 + hB, voffB); PG8_STAGE(PG8_SA(1, 0), a3, voffA);
;             PG8_WAIT_V(8); PG8_WAIT_L(0); PG8_BAR; PG8_MMA(1, 0, At, B0); PG8_MMA(1, 1, At, B1); PG8_BAR; PG8_SCHED;
	s_mov_b32 m0, s35
	v_lshl_add_u64 v[170:171], v[170:171], 0, s[76:77]
	ds_read_b128 v[188:191], v148 offset:49152
	ds_read_b128 v[200:203], v148 offset:50176
	ds_read_b128 v[204:207], v148 offset:51200
	ds_read_b128 v[208:211], v148 offset:52224
	ds_read_b128 v[212:215], v148 offset:53248
	ds_read_b128 v[216:219], v148 offset:54272
	ds_read_b128 v[220:223], v148 offset:55296
	ds_read_b128 v[224:227], v148 offset:56320
	global_load_lds_dwordx4 v[170:171], off
	v_lshl_add_u64 v[170:171], v[174:175], 0, s[76:77]
	s_mov_b32 m0, s34
	s_nop 0
	global_load_lds_dwordx4 v[170:171], off
	s_mov_b32 m0, s59
	s_nop 0
	global_load_lds_dwordx4 v132, s[30:31]
	s_mov_b32 m0, s58
	s_nop 0
	global_load_lds_dwordx4 v128, s[30:31]
	v_lshl_add_u64 v[170:171], v[176:177], 0, s[76:77]
	s_mov_b32 m0, s85
	s_nop 0
	global_load_lds_dwordx4 v[170:171], off
	v_lshl_add_u64 v[170:171], v[180:181], 0, s[76:77]
	s_mov_b32 m0, s79
	s_nop 0
	global_load_lds_dwordx4 v[170:171], off
	s_waitcnt vmcnt(8)
	s_waitcnt lgkmcnt(0)
	s_barrier
	s_setprio 1
	s_waitcnt lgkmcnt(0)
	v_mfma_f32_16x16x32_bf16 v[60:63], v[138:141], v[188:191], v[60:63]
	v_mfma_f32_16x16x32_bf16 v[56:59], v[150:153], v[188:191], v[56:59]
	v_mfma_f32_16x16x32_bf16 v[44:47], v[138:141], v[204:207], v[44:47]
	v_mfma_f32_16x16x32_bf16 v[40:43], v[150:153], v[204:207], v[40:43]
	v_mfma_f32_16x16x32_bf16 v[28:31], v[138:141], v[212:215], v[28:31]
	v_mfma_f32_16x16x32_bf16 v[24:27], v[150:153], v[212:215], v[24:27]
	v_mfma_f32_16x16x32_bf16 v[12:15], v[138:141], v[220:223], v[12:15]
	v_mfma_f32_16x16x32_bf16 v[8:11], v[150:153], v[220:223], v[8:11]
	v_mfma_f32_16x16x32_bf16 v[60:63], v[142:145], v[200:203], v[60:63]
	v_mfma_f32_16x16x32_bf16 v[56:59], v[154:157], v[200:203], v[56:59]
	v_mfma_f32_16x16x32_bf16 v[44:47], v[142:145], v[208:211], v[44:47]
	v_mfma_f32_16x16x32_bf16 v[40:43], v[154:157], v[208:211], v[40:43]
	v_mfma_f32_16x16x32_bf16 v[28:31], v[142:145], v[216:219], v[28:31]
	v_mfma_f32_16x16x32_bf16 v[24:27], v[154:157], v[216:219], v[24:27]
	v_mfma_f32_16x16x32_bf16 v[12:15], v[142:145], v[224:227], v[12:15]
	v_mfma_f32_16x16x32_bf16 v[8:11], v[154:157], v[224:227], v[8:11]
	s_setprio 0
	s_setprio 1
	v_mfma_f32_16x16x32_bf16 v[52:55], v[158:161], v[188:191], v[52:55]
	v_mfma_f32_16x16x32_bf16 v[48:51], v[166:169], v[188:191], v[48:51]
	v_mfma_f32_16x16x32_bf16 v[36:39], v[158:161], v[204:207], v[36:39]
	v_mfma_f32_16x16x32_bf16 v[32:35], v[166:169], v[204:207], v[32:35]
	v_mfma_f32_16x16x32_bf16 v[20:23], v[158:161], v[212:215], v[20:23]
	v_mfma_f32_16x16x32_bf16 v[16:19], v[166:169], v[212:215], v[16:19]
	v_mfma_f32_16x16x32_bf16 v[4:7], v[158:161], v[220:223], v[4:7]
	v_mfma_f32_16x16x32_bf16 v[0:3], v[166:169], v[220:223], v[0:3]
	v_mfma_f32_16x16x32_bf16 v[52:55], v[162:165], v[200:203], v[52:55]
	v_mfma_f32_16x16x32_bf16 v[48:51], v[184:187], v[200:203], v[48:51]
	v_mfma_f32_16x16x32_bf16 v[36:39], v[162:165], v[208:211], v[36:39]
	v_mfma_f32_16x16x32_bf16 v[32:35], v[184:187], v[208:211], v[32:35]
	v_mfma_f32_16x16x32_bf16 v[20:23], v[162:165], v[216:219], v[20:23]
	v_mfma_f32_16x16x32_bf16 v[16:19], v[184:187], v[216:219], v[16:19]
	v_mfma_f32_16x16x32_bf16 v[4:7], v[162:165], v[224:227], v[4:7]
	v_mfma_f32_16x16x32_bf16 v[0:3], v[184:187], v[224:227], v[0:3]
	s_setprio 0
	s_barrier
	s_andn2_b64 vcc, exec, s[0:1]
	s_mov_b64 s[30:31], -1
	s_mov_b64 s[0:1], 0
	s_mov_b64 s[44:45], 0x100
	s_cbranch_vccz .LBB0_378
	s_and_b64 vcc, exec, s[6:7]
	s_cbranch_vccz .LBB0_381
	s_barrier

; #define PG8_STAGE(bufoff, gbase, voff) do { _Pragma("unroll") for (int _i = 0; _i < 2; ++_i) \
;         __builtin_amdgcn_global_load_lds((const unsigned*)((const char*)(gbase) + (voff)[_i]), (PG8_LAS unsigned*)(lds + (bufoff) + ldsw + _i * 8192), 16, 0, 0); } while (0)
; #define PG8_WAIT_V(n) asm volatile("s_waitcnt vmcnt(" #n ")" ::: "memory")
; #define PG8_BAR __builtin_amdgcn_s_barrier()
; template <class Epi, class Sched, bool ALIGN_EPI = false, bool SP2 = false>
; __device__ __forceinline__ void gemm_phase(PG8_LAS unsigned char* lds, const Gemm g, const Sched& S, const Epi& E) {
;     ...
;     for (int i = 0; i < 2; ++i) { int R, C; stage_rc(tid * 16 + i * 8192, R, C); const int Rb = Epi::PERM ? ((R & ~31) + perm32(R & 31)) : R;
;         voffA[i] = (unsigned)(R * g.lda + C) * 2u; voffB[i] = (unsigned)(Rb * g.ldb + C) * 2u; }
;     const size_t kstep = (size_t)(BK * 2);
;     const size_t hA = (size_t)HALF * g.lda * 2, hB = (size_t)HALF * g.ldb * 2;
;     const size_t tA = 2 * hA, tB = 2 * hB;
;     const unsigned ldsw = (unsigned)wid * 1024u;
;     const int aoff = lds_byte(wr * 64 + fr, fq * 8), boff = lds_byte(wc * 32 + fr, fq * 8);
;     ...
;         PG8_STAGE(PG8_SB(0, 0), cB, voffB); PG8_STAGE(PG8_SB(0, 1), cB + hB, voffB); PG8_STAGE(PG8_SA(0, 0), cA, voffA); PG8_STAGE(PG8_SA(0, 1), cA + hA, voffA);
;         if (wr == 1) PG8_BAR;
;         PG8_WAIT_V(2); PG8_BAR;
;         PG8_STAGE(PG8_SB(1, 0), cB + kstep, voffB); PG8_STAGE(PG8_SA(1, 0), cA + kstep, voffA); PG8_STAGE(PG8_SB(1, 1), cB + hB + kstep, voffB);
;         PG8_WAIT_V(6); PG8_BAR;
.LBB0_710:
	v_lshrrev_b32_e32 v16, 1, v6
	v_and_b32_e32 v16, 24, v16
	v_and_b32_e32 v7, 15, v6
	v_lshlrev_b32_e32 v17, 1, v16
	v_lshlrev_b32_e32 v6, 2, v6
	v_readlane_b32 s18, v254, 35
	v_lshl_or_b32 v146, s6, 6, v7
	v_lshl_or_b32 v7, v7, 6, v17
	s_lshl_b32 s6, s6, 13
	v_and_b32_e32 v6, 32, v6
	s_lshl_b32 s5, s5, 5
	v_mov_b32_e32 v133, v173
	v_readlane_b32 s19, v254, 36
	v_bitop3_b32 v17, v7, s6, v6 bitop3:0xde
	s_and_b32 s6, s5, 0x60
	v_lshl_add_u64 v[8:9], s[18:19], 0, v[132:133]
	v_mov_b32_e32 v129, v173
	v_readlane_b32 s16, v254, 31
	s_lshl_b32 s5, s6, 7
	v_lshl_add_u64 v[10:11], s[18:19], 0, v[128:129]
	v_mov_b32_e32 v135, v173
	v_readlane_b32 s17, v254, 32
	v_bitop3_b32 v147, v7, s5, v6 bitop3:0xde
	s_add_i32 m0, s41, 0x18000
	v_lshl_add_u64 v[6:7], v[8:9], 0, s[76:77]
	v_lshl_add_u64 v[12:13], s[16:17], 0, v[134:135]
	v_mov_b32_e32 v131, v173
	s_waitcnt vmcnt(2)
	s_barrier
	global_load_lds_dwordx4 v[6:7], off
	v_lshl_add_u64 v[6:7], v[10:11], 0, s[76:77]
	s_add_i32 m0, s41, 0x1a000
	s_add_i32 s70, s41, 0x8000
	v_lshl_add_u64 v[14:15], s[16:17], 0, v[130:131]
	global_load_lds_dwordx4 v[6:7], off
	v_lshl_add_u64 v[6:7], v[12:13], 0, s[76:77]
	s_mov_b32 m0, s70
	s_add_i32 s71, s41, 0xa000
	v_readlane_b32 s8, v254, 37
	global_load_lds_dwordx4 v[6:7], off
	v_lshl_add_u64 v[6:7], v[14:15], 0, s[76:77]
	s_mov_b32 m0, s71
	v_readlane_b32 s9, v254, 38
	global_load_lds_dwordx4 v[6:7], off
	s_add_i32 m0, s41, 0x1c000
	s_nop 0
	s_nop 1
	global_load_lds_dwordx4 v132, s[8:9]
	s_add_i32 m0, s41, 0x1e000
	s_cmpk_lt_u32 s4, 0x100
	global_load_lds_dwordx4 v128, s[8:9]
	v_lshlrev_b32_e32 v6, 13, v4
	v_and_b32_e32 v6, 0xffffc000, v6
	v_lshl_add_u32 v3, v3, 10, v6
	v_and_b32_e32 v4, 1, v4
	v_lshl_or_b32 v3, v4, 6, v3
	v_lshl_add_u32 v136, v5, 1, v3
	v_lshlrev_b32_e32 v3, 13, v0
	v_and_b32_e32 v3, 0xffffc000, v3
	s_waitcnt vmcnt(6)
	v_lshl_add_u32 v1, v1, 10, v3
	v_and_b32_e32 v0, 1, v0
	v_or_b32_e32 v148, s6, v16
	v_lshl_or_b32 v0, v0, 6, v1
	v_readlane_b32 s6, v254, 39
	s_cselect_b64 s[4:5], -1, 0
	v_mov_b32_e32 v137, v173
	v_lshl_add_u32 v138, v2, 1, v0
	v_mov_b32_e32 v139, v173
	s_mov_b32 s42, 0
	v_add_u32_e32 v149, 0, v17
	v_readlane_b32 s43, v253, 36
	s_mov_b32 s44, s6
	s_barrier
	v_readlane_b32 s7, v254, 40
	s_branch .LBB0_713

; #define PG8_STAGE(bufoff, gbase, voff) do { _Pragma("unroll") for (int _i = 0; _i < 2; ++_i) \
;         __builtin_amdgcn_global_load_lds((const unsigned*)((const char*)(gbase) + (voff)[_i]), (PG8_LAS unsigned*)(lds + (bufoff) + ldsw + _i * 8192), 16, 0, 0); } while (0)
; #define PG8_LDA(dst, b, h) do { _Pragma("unroll") for (int m = 0; m < 4; ++m) _Pragma("unroll") for (int k = 0; k < 2; ++k) dst[m][k] = *(const PG8_LAS bf16x8*)(lds + PG8_SA(b, h) + aoff + m * 2048 + k * 1024); } while (0)
; #define PG8_LDB(dst, b, h) do { _Pragma("unroll") for (int n = 0; n < 2; ++n) _Pragma("unroll") for (int k = 0; k < 2; ++k) dst[n][k] = *(const PG8_LAS bf16x8*)(lds + PG8_SB(b, h) + boff + n * 2048 + k * 1024); } while (0)
; #define PG8_MMA(ai, bj, At, Bt) do { __builtin_amdgcn_s_setprio(1); _Pragma("unroll") for (int m = 0; m < 4; ++m) _Pragma("unroll") for (int n = 0; n < 2; ++n) _Pragma("unroll") for (int k = 0; k < 2; ++k) \
;         acc[ai][bj][m][n] = __builtin_amdgcn_mfma_f32_16x16x32_bf16(Bt[n][k], At[m][k], acc[ai][bj][m][n], 0, 0, 0); __builtin_amdgcn_s_setprio(0); } while (0)
; #define PG8_BAR __builtin_amdgcn_s_barrier()
; template <class Epi, class Sched, bool ALIGN_EPI = false, bool SP2 = false>
; __device__ __forceinline__ void gemm_phase(PG8_LAS unsigned char* lds, const Gemm g, const Sched& S, const Epi& E) {
;     ...
;             if constexpr (SP2) {
;             PG8_LDB(B0, 0, 0); PG8_LDB(B1, 0, 1); PG8_SCHED; PG8_LDA(At, 0, 0); PG8_STAGE(PG8_SA(1, 1), a1 + hA, voffA);
;             PG8_WAIT_V(8); PG8_WAIT_L(0); PG8_BAR; PG8_MMA(0, 0, At, B0); PG8_MMA(0, 1, At, B1); PG8_BAR; PG8_SCHED;
;             PG8_LDA(At, 0, 1); PG8_STAGE(PG8_SB(0, 0), b2, voffB); PG8_STAGE(PG8_SB(0, 1), b2 + hB, voffB); PG8_STAGE(PG8_SA(0, 0), a2, voffA);
;             PG8_WAIT_V(8); PG8_WAIT_L(0); PG8_BAR; PG8_MMA(1, 0, At, B0); PG8_MMA(1, 1, At, B1); PG8_BAR; PG8_SCHED;
;             PG8_LDB(B0, 1, 0); PG8_LDB(B1, 1, 1); PG8_SCHED; PG8_LDA(At, 1, 0); PG8_STAGE(PG8_SA(0, 1), a2 + hA, voffA);
;             PG8_WAIT_V(8); PG8_WAIT_L(0); PG8_BAR; PG8_MMA(0, 0, At, B0); PG8_MMA(0, 1, At, B1); PG8_BAR; PG8_SCHED;
;             PG8_LDA(At, 1, 1); PG8_STAGE(PG8_SB(1, 0), b3, voffB); PG8_STAGE(PG8_SB(1, 1), b3 + hB, voffB); PG8_STAGE(PG8_SA(1, 0), a3, voffA);
;             PG8_WAIT_V(8); PG8_WAIT_L(0); PG8_BAR; PG8_MMA(1, 0, At, B0); PG8_MMA(1, 1, At, B1); PG8_BAR; PG8_SCHED;
.LBB0_720:
	s_add_u32 s18, s16, 0xfffe0080
	s_addc_u32 s19, s17, -1
	s_add_i32 s34, 0, 0x10000
	s_cmp_eq_u32 s75, 4
	s_cselect_b32 s31, s9, s19
	s_cselect_b32 s30, s45, s18
	v_add_u32_e32 v144, s34, v147
	s_cselect_b32 s19, s11, s74
	s_cselect_b32 s18, s50, s51
	s_add_i32 s52, 0, 0x14000
	ds_read_b128 v[140:143], v144
	ds_read_b128 v[150:153], v144 offset:1024
	ds_read_b128 v[154:157], v144 offset:2048
	ds_read_b128 v[158:161], v144 offset:3072
	v_add_u32_e32 v144, s52, v147
	ds_read_b128 v[162:165], v144
	ds_read_b128 v[166:169], v144 offset:1024
	ds_read_b128 v[174:177], v144 offset:2048
	ds_read_b128 v[180:183], v144 offset:3072
	s_add_i32 m0, s41, 0xc000
	ds_read_b128 v[184:187], v149
	ds_read_b128 v[188:191], v149 offset:1024
	ds_read_b128 v[192:195], v149 offset:2048
	ds_read_b128 v[200:203], v149 offset:3072
	ds_read_b128 v[204:207], v149 offset:4096
	ds_read_b128 v[208:211], v149 offset:5120
	ds_read_b128 v[212:215], v149 offset:6144
	ds_read_b128 v[216:219], v149 offset:7168
	global_load_lds_dwordx4 v136, s[16:17]
	s_add_i32 m0, s41, 0xe000
	s_nop 0
	global_load_lds_dwordx4 v138, s[16:17]
	s_waitcnt vmcnt(8)
	s_waitcnt lgkmcnt(0)
	s_barrier
	s_setprio 1
	s_waitcnt lgkmcnt(0)
	v_mfma_f32_16x16x32_bf16 v[124:127], v[140:143], v[184:187], v[124:127]
	v_mfma_f32_16x16x32_bf16 v[120:123], v[154:157], v[184:187], v[120:123]
	v_mfma_f32_16x16x32_bf16 v[108:111], v[140:143], v[192:195], v[108:111]
	v_mfma_f32_16x16x32_bf16 v[104:107], v[154:157], v[192:195], v[104:107]
	v_mfma_f32_16x16x32_bf16 v[92:95], v[140:143], v[204:207], v[92:95]
	v_mfma_f32_16x16x32_bf16 v[88:91], v[154:157], v[204:207], v[88:91]
	v_mfma_f32_16x16x32_bf16 v[76:79], v[140:143], v[212:215], v[76:79]
	v_mfma_f32_16x16x32_bf16 v[72:75], v[154:157], v[212:215], v[72:75]
	v_mfma_f32_16x16x32_bf16 v[124:127], v[150:153], v[188:191], v[124:127]
	v_mfma_f32_16x16x32_bf16 v[120:123], v[158:161], v[188:191], v[120:123]
	v_mfma_f32_16x16x32_bf16 v[108:111], v[150:153], v[200:203], v[108:111]
	v_mfma_f32_16x16x32_bf16 v[104:107], v[158:161], v[200:203], v[104:107]
	v_mfma_f32_16x16x32_bf16 v[92:95], v[150:153], v[208:211], v[92:95]
	v_mfma_f32_16x16x32_bf16 v[88:91], v[158:161], v[208:211], v[88:91]
	v_mfma_f32_16x16x32_bf16 v[76:79], v[150:153], v[216:219], v[76:79]
	v_mfma_f32_16x16x32_bf16 v[72:75], v[158:161], v[216:219], v[72:75]
	s_setprio 0
	s_setprio 1
	v_mfma_f32_16x16x32_bf16 v[116:119], v[162:165], v[184:187], v[116:119]
	v_mfma_f32_16x16x32_bf16 v[112:115], v[174:177], v[184:187], v[112:115]
	v_mfma_f32_16x16x32_bf16 v[100:103], v[162:165], v[192:195], v[100:103]
	v_mfma_f32_16x16x32_bf16 v[96:99], v[174:177], v[192:195], v[96:99]
	v_mfma_f32_16x16x32_bf16 v[84:87], v[162:165], v[204:207], v[84:87]
	v_mfma_f32_16x16x32_bf16 v[80:83], v[174:177], v[204:207], v[80:83]
	v_mfma_f32_16x16x32_bf16 v[68:71], v[162:165], v[212:215], v[68:71]
	v_mfma_f32_16x16x32_bf16 v[64:67], v[174:177], v[212:215], v[64:67]
	v_mfma_f32_16x16x32_bf16 v[116:119], v[166:169], v[188:191], v[116:119]
	v_mfma_f32_16x16x32_bf16 v[112:115], v[180:183], v[188:191], v[112:115]
	v_mfma_f32_16x16x32_bf16 v[100:103], v[166:169], v[200:203], v[100:103]
	v_mfma_f32_16x16x32_bf16 v[96:99], v[180:183], v[200:203], v[96:99]
	v_mfma_f32_16x16x32_bf16 v[84:87], v[166:169], v[208:211], v[84:87]
	v_mfma_f32_16x16x32_bf16 v[80:83], v[180:183], v[208:211], v[80:83]
	v_mfma_f32_16x16x32_bf16 v[68:71], v[166:169], v[216:219], v[68:71]
	v_mfma_f32_16x16x32_bf16 v[64:67], v[180:183], v[216:219], v[64:67]
	s_setprio 0
	s_barrier
	s_add_i32 s34, s34, s40
	v_lshl_add_u64 v[144:145], s[18:19], 0, v[132:133]
	s_mov_b32 m0, s34
	ds_read_b128 v[184:187], v149 offset:16384
	ds_read_b128 v[188:191], v149 offset:17408
	ds_read_b128 v[192:195], v149 offset:18432
	ds_read_b128 v[200:203], v149 offset:19456
	ds_read_b128 v[204:207], v149 offset:20480
	ds_read_b128 v[208:211], v149 offset:21504
	ds_read_b128 v[212:215], v149 offset:22528
	ds_read_b128 v[216:219], v149 offset:23552
	global_load_lds_dwordx4 v132, s[18:19]
	s_add_i32 m0, s34, 0x2000
	s_add_u32 s34, s18, 0x20000
	v_lshl_add_u64 v[170:171], s[18:19], 0, v[128:129]
	s_addc_u32 s35, s19, 0
	s_add_i32 s52, s52, s40
	global_load_lds_dwordx4 v128, s[18:19]
	s_mov_b32 m0, s52
	v_lshl_add_u64 v[222:223], s[30:31], 0, v[130:131]
	global_load_lds_dwordx4 v132, s[34:35]
	s_add_i32 m0, s52, 0x2000
	s_nop 0
	global_load_lds_dwordx4 v128, s[34:35]
	v_lshl_add_u64 v[220:221], s[30:31], 0, v[134:135]
	s_mov_b32 m0, s41
	s_nop 0
	global_load_lds_dwordx4 v134, s[30:31]
	s_mov_b32 m0, s46
	s_nop 0
	global_load_lds_dwordx4 v130, s[30:31]
	s_waitcnt vmcnt(8)
	s_waitcnt lgkmcnt(0)
	s_barrier
; #define PG8_STAGE(bufoff, gbase, voff) do { _Pragma("unroll") for (int _i = 0; _i < 2; ++_i) \
;         __builtin_amdgcn_global_load_lds((const unsigned*)((const char*)(gbase) + (voff)[_i]), (PG8_LAS unsigned*)(lds + (bufoff) + ldsw + _i * 8192), 16, 0, 0); } while (0)
; #define PG8_LDA(dst, b, h) do { _Pragma("unroll") for (int m = 0; m < 4; ++m) _Pragma("unroll") for (int k = 0; k < 2; ++k) dst[m][k] = *(const PG8_LAS bf16x8*)(lds + PG8_SA(b, h) + aoff + m * 2048 + k * 1024); } while (0)
; #define PG8_LDB(dst, b, h) do { _Pragma("unroll") for (int n = 0; n < 2; ++n) _Pragma("unroll") for (int k = 0; k < 2; ++k) dst[n][k] = *(const PG8_LAS bf16x8*)(lds + PG8_SB(b, h) + boff + n * 2048 + k * 1024); } while (0)
; #define PG8_MMA(ai, bj, At, Bt) do { __builtin_amdgcn_s_setprio(1); _Pragma("unroll") for (int m = 0; m < 4; ++m) _Pragma("unroll") for (int n = 0; n < 2; ++n) _Pragma("unroll") for (int k = 0; k < 2; ++k) \
;         acc[ai][bj][m][n] = __builtin_amdgcn_mfma_f32_16x16x32_bf16(Bt[n][k], At[m][k], acc[ai][bj][m][n], 0, 0, 0); __builtin_amdgcn_s_setprio(0); } while (0)
; #define PG8_BAR __builtin_amdgcn_s_barrier()
; template <class Epi, class Sched, bool ALIGN_EPI = false, bool SP2 = false>
; __device__ __forceinline__ void gemm_phase(PG8_LAS unsigned char* lds, const Gemm g, const Sched& S, const Epi& E) {
;     ...
;             if constexpr (SP2) {
;             PG8_LDB(B0, 0, 0); PG8_LDB(B1, 0, 1); PG8_SCHED; PG8_LDA(At, 0, 0); PG8_STAGE(PG8_SA(1, 1), a1 + hA, voffA);
;             PG8_WAIT_V(8); PG8_WAIT_L(0); PG8_BAR; PG8_MMA(0, 0, At, B0); PG8_MMA(0, 1, At, B1); PG8_BAR; PG8_SCHED;
;             PG8_LDA(At, 0, 1); PG8_STAGE(PG8_SB(0, 0), b2, voffB); PG8_STAGE(PG8_SB(0, 1), b2 + hB, voffB); PG8_STAGE(PG8_SA(0, 0), a2, voffA);
;             PG8_WAIT_V(8); PG8_WAIT_L(0); PG8_BAR; PG8_MMA(1, 0, At, B0); PG8_MMA(1, 1, At, B1); PG8_BAR; PG8_SCHED;
;             PG8_LDB(B0, 1, 0); PG8_LDB(B1, 1, 1); PG8_SCHED; PG8_LDA(At, 1, 0); PG8_STAGE(PG8_SA(0, 1), a2 + hA, voffA);
;             PG8_WAIT_V(8); PG8_WAIT_L(0); PG8_BAR; PG8_MMA(0, 0, At, B0); PG8_MMA(0, 1, At, B1); PG8_BAR; PG8_SCHED;
;             PG8_LDA(At, 1, 1); PG8_STAGE(PG8_SB(1, 0), b3, voffB); PG8_STAGE(PG8_SB(1, 1), b3 + hB, voffB); PG8_STAGE(PG8_SA(1, 0), a3, voffA);
;             PG8_WAIT_V(8); PG8_WAIT_L(0); PG8_BAR; PG8_MMA(1, 0, At, B0); PG8_MMA(1, 1, At, B1); PG8_BAR; PG8_SCHED;
	s_setprio 1
	s_waitcnt lgkmcnt(0)
	v_mfma_f32_16x16x32_bf16 v[60:63], v[140:143], v[184:187], v[60:63]
	v_mfma_f32_16x16x32_bf16 v[56:59], v[154:157], v[184:187], v[56:59]
	v_mfma_f32_16x16x32_bf16 v[44:47], v[140:143], v[192:195], v[44:47]
	v_mfma_f32_16x16x32_bf16 v[40:43], v[154:157], v[192:195], v[40:43]
	v_mfma_f32_16x16x32_bf16 v[28:31], v[140:143], v[204:207], v[28:31]
	v_mfma_f32_16x16x32_bf16 v[24:27], v[154:157], v[204:207], v[24:27]
	v_mfma_f32_16x16x32_bf16 v[12:15], v[140:143], v[212:215], v[12:15]
	v_mfma_f32_16x16x32_bf16 v[8:11], v[154:157], v[212:215], v[8:11]
	v_mfma_f32_16x16x32_bf16 v[60:63], v[150:153], v[188:191], v[60:63]
	v_mfma_f32_16x16x32_bf16 v[56:59], v[158:161], v[188:191], v[56:59]
	v_mfma_f32_16x16x32_bf16 v[44:47], v[150:153], v[200:203], v[44:47]
	v_mfma_f32_16x16x32_bf16 v[40:43], v[158:161], v[200:203], v[40:43]
	v_mfma_f32_16x16x32_bf16 v[28:31], v[150:153], v[208:211], v[28:31]
	v_mfma_f32_16x16x32_bf16 v[24:27], v[158:161], v[208:211], v[24:27]
	v_mfma_f32_16x16x32_bf16 v[12:15], v[150:153], v[216:219], v[12:15]
	v_mfma_f32_16x16x32_bf16 v[8:11], v[158:161], v[216:219], v[8:11]
	s_setprio 0
	s_setprio 1
	v_mfma_f32_16x16x32_bf16 v[52:55], v[162:165], v[184:187], v[52:55]
	v_mfma_f32_16x16x32_bf16 v[48:51], v[174:177], v[184:187], v[48:51]
	v_mfma_f32_16x16x32_bf16 v[36:39], v[162:165], v[192:195], v[36:39]
	v_mfma_f32_16x16x32_bf16 v[32:35], v[174:177], v[192:195], v[32:35]
	v_mfma_f32_16x16x32_bf16 v[20:23], v[162:165], v[204:207], v[20:23]
	v_mfma_f32_16x16x32_bf16 v[16:19], v[174:177], v[204:207], v[16:19]
	v_mfma_f32_16x16x32_bf16 v[4:7], v[162:165], v[212:215], v[4:7]
	v_mfma_f32_16x16x32_bf16 v[0:3], v[174:177], v[212:215], v[0:3]
	v_mfma_f32_16x16x32_bf16 v[52:55], v[166:169], v[188:191], v[52:55]
	v_mfma_f32_16x16x32_bf16 v[48:51], v[180:183], v[188:191], v[48:51]
	v_mfma_f32_16x16x32_bf16 v[36:39], v[166:169], v[200:203], v[36:39]
	v_mfma_f32_16x16x32_bf16 v[32:35], v[180:183], v[200:203], v[32:35]
	v_mfma_f32_16x16x32_bf16 v[20:23], v[166:169], v[208:211], v[20:23]
	v_mfma_f32_16x16x32_bf16 v[16:19], v[180:183], v[208:211], v[16:19]
	v_mfma_f32_16x16x32_bf16 v[4:7], v[166:169], v[216:219], v[4:7]
	v_mfma_f32_16x16x32_bf16 v[0:3], v[180:183], v[216:219], v[0:3]
	s_setprio 0
	s_barrier
	s_add_i32 s34, 0, 0x18000
	s_add_i32 s35, 0, 0x1c000
	v_add_u32_e32 v158, s34, v147
	v_add_u32_e32 v172, s35, v147
	ds_read_b128 v[140:143], v158
	ds_read_b128 v[150:153], v158 offset:1024
	ds_read_b128 v[154:157], v158 offset:2048
	ds_read_b128 v[158:161], v158 offset:3072
	ds_read_b128 v[162:165], v172
	ds_read_b128 v[166:169], v172 offset:1024
	ds_read_b128 v[174:177], v172 offset:2048
	ds_read_b128 v[180:183], v172 offset:3072
	s_add_u32 s30, s30, 0x20000
	s_addc_u32 s31, s31, 0
	s_mov_b32 m0, s47
	ds_read_b128 v[184:187], v149 offset:32768
	ds_read_b128 v[188:191], v149 offset:33792
	ds_read_b128 v[192:195], v149 offset:34816
	ds_read_b128 v[200:203], v149 offset:35840
	ds_read_b128 v[204:207], v149 offset:36864
	ds_read_b128 v[208:211], v149 offset:37888
	ds_read_b128 v[212:215], v149 offset:38912
	ds_read_b128 v[216:219], v149 offset:39936
	global_load_lds_dwordx4 v134, s[30:31]
	s_mov_b32 m0, s68
	s_nop 0
	global_load_lds_dwordx4 v130, s[30:31]
	s_waitcnt vmcnt(8)
	s_waitcnt lgkmcnt(0)
	s_barrier
	s_setprio 1
	s_waitcnt lgkmcnt(0)
	v_mfma_f32_16x16x32_bf16 v[124:127], v[140:143], v[184:187], v[124:127]
	v_mfma_f32_16x16x32_bf16 v[120:123], v[154:157], v[184:187], v[120:123]
	v_mfma_f32_16x16x32_bf16 v[108:111], v[140:143], v[192:195], v[108:111]
	v_mfma_f32_16x16x32_bf16 v[104:107], v[154:157], v[192:195], v[104:107]
	v_mfma_f32_16x16x32_bf16 v[92:95], v[140:143], v[204:207], v[92:95]
	v_mfma_f32_16x16x32_bf16 v[88:91], v[154:157], v[204:207], v[88:91]
	v_mfma_f32_16x16x32_bf16 v[76:79], v[140:143], v[212:215], v[76:79]
	v_mfma_f32_16x16x32_bf16 v[72:75], v[154:157], v[212:215], v[72:75]
	v_mfma_f32_16x16x32_bf16 v[124:127], v[150:153], v[188:191], v[124:127]
	v_mfma_f32_16x16x32_bf16 v[120:123], v[158:161], v[188:191], v[120:123]
	v_mfma_f32_16x16x32_bf16 v[108:111], v[150:153], v[200:203], v[108:111]
	v_mfma_f32_16x16x32_bf16 v[104:107], v[158:161], v[200:203], v[104:107]
	v_mfma_f32_16x16x32_bf16 v[92:95], v[150:153], v[208:211], v[92:95]
	v_mfma_f32_16x16x32_bf16 v[88:91], v[158:161], v[208:211], v[88:91]
	v_mfma_f32_16x16x32_bf16 v[76:79], v[150:153], v[216:219], v[76:79]
	v_mfma_f32_16x16x32_bf16 v[72:75], v[158:161], v[216:219], v[72:75]
	s_setprio 0
	s_setprio 1
	v_mfma_f32_16x16x32_bf16 v[116:119], v[162:165], v[184:187], v[116:119]
	v_mfma_f32_16x16x32_bf16 v[112:115], v[174:177], v[184:187], v[112:115]
	v_mfma_f32_16x16x32_bf16 v[100:103], v[162:165], v[192:195], v[100:103]
	v_mfma_f32_16x16x32_bf16 v[96:99], v[174:177], v[192:195], v[96:99]
	v_mfma_f32_16x16x32_bf16 v[84:87], v[162:165], v[204:207], v[84:87]
	v_mfma_f32_16x16x32_bf16 v[80:83], v[174:177], v[204:207], v[80:83]
	v_mfma_f32_16x16x32_bf16 v[68:71], v[162:165], v[212:215], v[68:71]
	v_mfma_f32_16x16x32_bf16 v[64:67], v[174:177], v[212:215], v[64:67]
	v_mfma_f32_16x16x32_bf16 v[116:119], v[166:169], v[188:191], v[116:119]
	v_mfma_f32_16x16x32_bf16 v[112:115], v[180:183], v[188:191], v[112:115]
	v_mfma_f32_16x16x32_bf16 v[100:103], v[166:169], v[200:203], v[100:103]
	v_mfma_f32_16x16x32_bf16 v[96:99], v[180:183], v[200:203], v[96:99]
	v_mfma_f32_16x16x32_bf16 v[84:87], v[166:169], v[208:211], v[84:87]
	v_mfma_f32_16x16x32_bf16 v[80:83], v[180:183], v[208:211], v[80:83]
	v_mfma_f32_16x16x32_bf16 v[68:71], v[166:169], v[216:219], v[68:71]
	v_mfma_f32_16x16x32_bf16 v[64:67], v[180:183], v[216:219], v[64:67]
	s_setprio 0
	s_barrier
; #define PG8_STAGE(bufoff, gbase, voff) do { _Pragma("unroll") for (int _i = 0; _i < 2; ++_i) \
;         __builtin_amdgcn_global_load_lds((const unsigned*)((const char*)(gbase) + (voff)[_i]), (PG8_LAS unsigned*)(lds + (bufoff) + ldsw + _i * 8192), 16, 0, 0); } while (0)
; #define PG8_LDA(dst, b, h) do { _Pragma("unroll") for (int m = 0; m < 4; ++m) _Pragma("unroll") for (int k = 0; k < 2; ++k) dst[m][k] = *(const PG8_LAS bf16x8*)(lds + PG8_SA(b, h) + aoff + m * 2048 + k * 1024); } while (0)
; #define PG8_LDB(dst, b, h) do { _Pragma("unroll") for (int n = 0; n < 2; ++n) _Pragma("unroll") for (int k = 0; k < 2; ++k) dst[n][k] = *(const PG8_LAS bf16x8*)(lds + PG8_SB(b, h) + boff + n * 2048 + k * 1024); } while (0)
; #define PG8_MMA(ai, bj, At, Bt) do { __builtin_amdgcn_s_setprio(1); _Pragma("unroll") for (int m = 0; m < 4; ++m) _Pragma("unroll") for (int n = 0; n < 2; ++n) _Pragma("unroll") for (int k = 0; k < 2; ++k) \
;         acc[ai][bj][m][n] = __builtin_amdgcn_mfma_f32_16x16x32_bf16(Bt[n][k], At[m][k], acc[ai][bj][m][n], 0, 0, 0); __builtin_amdgcn_s_setprio(0); } while (0)
; #define PG8_BAR __builtin_amdgcn_s_barrier()
; template <class Epi, class Sched, bool ALIGN_EPI = false, bool SP2 = false>
; __device__ __forceinline__ void gemm_phase(PG8_LAS unsigned char* lds, const Gemm g, const Sched& S, const Epi& E) {
;     ...
;             if constexpr (SP2) {
;             PG8_LDB(B0, 0, 0); PG8_LDB(B1, 0, 1); PG8_SCHED; PG8_LDA(At, 0, 0); PG8_STAGE(PG8_SA(1, 1), a1 + hA, voffA);
;             PG8_WAIT_V(8); PG8_WAIT_L(0); PG8_BAR; PG8_MMA(0, 0, At, B0); PG8_MMA(0, 1, At, B1); PG8_BAR; PG8_SCHED;
;             PG8_LDA(At, 0, 1); PG8_STAGE(PG8_SB(0, 0), b2, voffB); PG8_STAGE(PG8_SB(0, 1), b2 + hB, voffB); PG8_STAGE(PG8_SA(0, 0), a2, voffA);
;             PG8_WAIT_V(8); PG8_WAIT_L(0); PG8_BAR; PG8_MMA(1, 0, At, B0); PG8_MMA(1, 1, At, B1); PG8_BAR; PG8_SCHED;
;             PG8_LDB(B0, 1, 0); PG8_LDB(B1, 1, 1); PG8_SCHED; PG8_LDA(At, 1, 0); PG8_STAGE(PG8_SA(0, 1), a2 + hA, voffA);
;             PG8_WAIT_V(8); PG8_WAIT_L(0); PG8_BAR; PG8_MMA(0, 0, At, B0); PG8_MMA(0, 1, At, B1); PG8_BAR; PG8_SCHED;
;             PG8_LDA(At, 1, 1); PG8_STAGE(PG8_SB(1, 0), b3, voffB); PG8_STAGE(PG8_SB(1, 1), b3 + hB, voffB); PG8_STAGE(PG8_SA(1, 0), a3, voffA);
;             PG8_WAIT_V(8); PG8_WAIT_L(0); PG8_BAR; PG8_MMA(1, 0, At, B0); PG8_MMA(1, 1, At, B1); PG8_BAR; PG8_SCHED;
	s_add_i32 s30, s34, s40
	v_lshl_add_u64 v[144:145], v[144:145], 0, s[76:77]
	s_mov_b32 m0, s30
	ds_read_b128 v[184:187], v149 offset:49152
	ds_read_b128 v[188:191], v149 offset:50176
	ds_read_b128 v[192:195], v149 offset:51200
	ds_read_b128 v[200:203], v149 offset:52224
	ds_read_b128 v[204:207], v149 offset:53248
	ds_read_b128 v[208:211], v149 offset:54272
	ds_read_b128 v[212:215], v149 offset:55296
	ds_read_b128 v[216:219], v149 offset:56320
	global_load_lds_dwordx4 v[144:145], off
	s_add_i32 m0, s30, 0x2000
	s_add_u32 s18, s18, 0x20080
	v_lshl_add_u64 v[144:145], v[170:171], 0, s[76:77]
	s_addc_u32 s19, s19, 0
	s_add_i32 s30, s35, s40
	global_load_lds_dwordx4 v[144:145], off
	s_mov_b32 m0, s30
	s_nop 0
	global_load_lds_dwordx4 v132, s[18:19]
	s_add_i32 m0, s30, 0x2000
	s_nop 0
	global_load_lds_dwordx4 v128, s[18:19]
	v_lshl_add_u64 v[144:145], v[220:221], 0, s[76:77]
	s_mov_b32 m0, s70
	s_nop 0
	global_load_lds_dwordx4 v[144:145], off
	v_lshl_add_u64 v[144:145], v[222:223], 0, s[76:77]
	s_mov_b32 m0, s71
	s_nop 0
	global_load_lds_dwordx4 v[144:145], off
	s_waitcnt vmcnt(8)
	s_waitcnt lgkmcnt(0)
	s_barrier
	s_setprio 1
	s_waitcnt lgkmcnt(0)
	v_mfma_f32_16x16x32_bf16 v[60:63], v[140:143], v[184:187], v[60:63]
	v_mfma_f32_16x16x32_bf16 v[56:59], v[154:157], v[184:187], v[56:59]
	v_mfma_f32_16x16x32_bf16 v[44:47], v[140:143], v[192:195], v[44:47]
	v_mfma_f32_16x16x32_bf16 v[40:43], v[154:157], v[192:195], v[40:43]
	v_mfma_f32_16x16x32_bf16 v[28:31], v[140:143], v[204:207], v[28:31]
	v_mfma_f32_16x16x32_bf16 v[24:27], v[154:157], v[204:207], v[24:27]
	v_mfma_f32_16x16x32_bf16 v[12:15], v[140:143], v[212:215], v[12:15]
	v_mfma_f32_16x16x32_bf16 v[8:11], v[154:157], v[212:215], v[8:11]
	v_mfma_f32_16x16x32_bf16 v[60:63], v[150:153], v[188:191], v[60:63]
	v_mfma_f32_16x16x32_bf16 v[56:59], v[158:161], v[188:191], v[56:59]
	v_mfma_f32_16x16x32_bf16 v[44:47], v[150:153], v[200:203], v[44:47]
	v_mfma_f32_16x16x32_bf16 v[40:43], v[158:161], v[200:203], v[40:43]
	v_mfma_f32_16x16x32_bf16 v[28:31], v[150:153], v[208:211], v[28:31]
	v_mfma_f32_16x16x32_bf16 v[24:27], v[158:161], v[208:211], v[24:27]
	v_mfma_f32_16x16x32_bf16 v[12:15], v[150:153], v[216:219], v[12:15]
	v_mfma_f32_16x16x32_bf16 v[8:11], v[158:161], v[216:219], v[8:11]
	s_setprio 0
	s_setprio 1
	v_mfma_f32_16x16x32_bf16 v[52:55], v[162:165], v[184:187], v[52:55]
	v_mfma_f32_16x16x32_bf16 v[48:51], v[174:177], v[184:187], v[48:51]
	v_mfma_f32_16x16x32_bf16 v[36:39], v[162:165], v[192:195], v[36:39]
	v_mfma_f32_16x16x32_bf16 v[32:35], v[174:177], v[192:195], v[32:35]
	v_mfma_f32_16x16x32_bf16 v[20:23], v[162:165], v[204:207], v[20:23]
	v_mfma_f32_16x16x32_bf16 v[16:19], v[174:177], v[204:207], v[16:19]
	v_mfma_f32_16x16x32_bf16 v[4:7], v[162:165], v[212:215], v[4:7]
	v_mfma_f32_16x16x32_bf16 v[0:3], v[174:177], v[212:215], v[0:3]
	v_mfma_f32_16x16x32_bf16 v[52:55], v[166:169], v[188:191], v[52:55]
	v_mfma_f32_16x16x32_bf16 v[48:51], v[180:183], v[188:191], v[48:51]
	v_mfma_f32_16x16x32_bf16 v[36:39], v[166:169], v[200:203], v[36:39]
	v_mfma_f32_16x16x32_bf16 v[32:35], v[180:183], v[200:203], v[32:35]
	v_mfma_f32_16x16x32_bf16 v[20:23], v[166:169], v[208:211], v[20:23]
	v_mfma_f32_16x16x32_bf16 v[16:19], v[180:183], v[208:211], v[16:19]
	v_mfma_f32_16x16x32_bf16 v[4:7], v[166:169], v[216:219], v[4:7]
	v_mfma_f32_16x16x32_bf16 v[0:3], v[180:183], v[216:219], v[0:3]
	s_setprio 0
	s_barrier
	s_add_i32 s75, s75, 2
	s_add_u32 s16, s16, 0x100
	s_addc_u32 s17, s17, 0
	s_add_u32 s51, s51, 0x100
	s_addc_u32 s74, s74, 0
	s_cmp_gt_u32 s75, 5
	s_cbranch_scc0 .LBB0_720
	s_and_b64 vcc, exec, s[4:5]
	s_cbranch_vccz .LBB0_723
	s_barrier

; #define PG8_STAGE(bufoff, gbase, voff) do { _Pragma("unroll") for (int _i = 0; _i < 2; ++_i) \
;         __builtin_amdgcn_global_load_lds((const unsigned*)((const char*)(gbase) + (voff)[_i]), (PG8_LAS unsigned*)(lds + (bufoff) + ldsw + _i * 8192), 16, 0, 0); } while (0)
; #define PG8_WAIT_V(n) asm volatile("s_waitcnt vmcnt(" #n ")" ::: "memory")
; #define PG8_BAR __builtin_amdgcn_s_barrier()
; template <class Epi, class Sched, bool ALIGN_EPI = false, bool SP2 = false>
; __device__ __forceinline__ void gemm_phase(PG8_LAS unsigned char* lds, const Gemm g, const Sched& S, const Epi& E) {
;     ...
;         PG8_STAGE(PG8_SB(0, 0), cB, voffB); PG8_STAGE(PG8_SB(0, 1), cB + hB, voffB); PG8_STAGE(PG8_SA(0, 0), cA, voffA); PG8_STAGE(PG8_SA(0, 1), cA + hA, voffA);
;         if (wr == 1) PG8_BAR;
;         PG8_WAIT_V(2); PG8_BAR;
;         PG8_STAGE(PG8_SB(1, 0), cB + kstep, voffB); PG8_STAGE(PG8_SA(1, 0), cA + kstep, voffA); PG8_STAGE(PG8_SB(1, 1), cB + hB + kstep, voffB);
;         PG8_WAIT_V(6); PG8_BAR;
.LBB0_814:
	v_bfe_u32 v16, v6, 4, 2
	v_and_b32_e32 v7, 15, v6
	v_lshlrev_b32_e32 v17, 4, v16
	v_lshlrev_b32_e32 v6, 2, v6
	v_readlane_b32 s18, v254, 49
	v_lshl_or_b32 v131, s8, 6, v7
	v_lshl_or_b32 v7, v7, 6, v17
	s_lshl_b32 s8, s8, 13
	v_and_b32_e32 v6, 32, v6
	s_lshl_b32 s7, s7, 5
	v_readlane_b32 s19, v254, 50
	v_bitop3_b32 v17, v7, s8, v6 bitop3:0xde
	s_and_b32 s8, s7, 0x60
	v_lshl_add_u64 v[8:9], s[18:19], 0, v[172:173]
	v_mov_b32_e32 v129, v173
	v_readlane_b32 s16, v254, 45
	s_lshl_b32 s7, s8, 7
	v_lshl_add_u64 v[10:11], s[18:19], 0, v[128:129]
	v_readlane_b32 s17, v254, 46
	v_bitop3_b32 v142, v7, s7, v6 bitop3:0xde
	s_add_i32 m0, s41, 0x18000
	v_lshl_add_u64 v[6:7], v[8:9], 0, s[76:77]
	v_lshl_add_u64 v[12:13], s[16:17], 0, v[172:173]
	s_waitcnt vmcnt(2)
	s_barrier
	global_load_lds_dwordx4 v[6:7], off
	v_lshl_add_u64 v[6:7], v[10:11], 0, s[76:77]
	s_add_i32 m0, s41, 0x1a000
	s_add_i32 s70, s41, 0x8000
	v_lshl_add_u64 v[14:15], s[16:17], 0, v[128:129]
	global_load_lds_dwordx4 v[6:7], off
	v_lshl_add_u64 v[6:7], v[12:13], 0, s[76:77]
	s_mov_b32 m0, s70
	s_add_i32 s71, s41, 0xa000
	v_readlane_b32 s10, v254, 51
	global_load_lds_dwordx4 v[6:7], off
	v_lshl_add_u64 v[6:7], v[14:15], 0, s[76:77]
	s_mov_b32 m0, s71
	v_readlane_b32 s11, v254, 52
	global_load_lds_dwordx4 v[6:7], off
	s_add_i32 m0, s41, 0x1c000
	v_lshl_add_u64 v[6:7], s[10:11], 0, v[172:173]
	global_load_lds_dwordx4 v[6:7], off
	s_add_i32 m0, s41, 0x1e000
	s_cmpk_lt_u32 s6, 0x100
	global_load_lds_dwordx4 v128, s[10:11]
	v_lshlrev_b32_e32 v6, 14, v3
	v_and_b32_e32 v6, 0xffff8000, v6
	v_lshl_add_u32 v4, v4, 11, v6
	v_and_b32_e32 v3, 1, v3
	v_lshl_or_b32 v3, v3, 6, v4
	v_lshl_add_u32 v132, v5, 1, v3
	v_lshlrev_b32_e32 v3, 14, v0
	v_and_b32_e32 v3, 0xffff8000, v3
	s_waitcnt vmcnt(6)
	v_lshl_add_u32 v1, v1, 11, v3
	v_and_b32_e32 v0, 1, v0
	v_lshl_or_b32 v130, v16, 2, s8
	v_lshl_or_b32 v0, v0, 6, v1
	v_readlane_b32 s8, v254, 39
	s_cselect_b64 s[6:7], -1, 0
	s_mov_b32 s97, 0
	v_cmp_eq_u32_e64 s[44:45], 0, v16
	v_mov_b32_e32 v133, v173
	v_lshl_add_u32 v134, v2, 1, v0
	v_mov_b32_e32 v135, v173
	v_add_u32_e32 v143, 0, v17
	v_readlane_b32 s50, v253, 36
	s_mov_b32 s51, s8
	s_barrier
	v_readlane_b32 s9, v254, 40
	s_branch .LBB0_817

; #define PG8_STAGE(bufoff, gbase, voff) do { _Pragma("unroll") for (int _i = 0; _i < 2; ++_i) \
;         __builtin_amdgcn_global_load_lds((const unsigned*)((const char*)(gbase) + (voff)[_i]), (PG8_LAS unsigned*)(lds + (bufoff) + ldsw + _i * 8192), 16, 0, 0); } while (0)
; #define PG8_LDA(dst, b, h) do { _Pragma("unroll") for (int m = 0; m < 4; ++m) _Pragma("unroll") for (int k = 0; k < 2; ++k) dst[m][k] = *(const PG8_LAS bf16x8*)(lds + PG8_SA(b, h) + aoff + m * 2048 + k * 1024); } while (0)
; #define PG8_LDB(dst, b, h) do { _Pragma("unroll") for (int n = 0; n < 2; ++n) _Pragma("unroll") for (int k = 0; k < 2; ++k) dst[n][k] = *(const PG8_LAS bf16x8*)(lds + PG8_SB(b, h) + boff + n * 2048 + k * 1024); } while (0)
; #define PG8_MMA(ai, bj, At, Bt) do { __builtin_amdgcn_s_setprio(1); _Pragma("unroll") for (int m = 0; m < 4; ++m) _Pragma("unroll") for (int n = 0; n < 2; ++n) _Pragma("unroll") for (int k = 0; k < 2; ++k) \
;         acc[ai][bj][m][n] = __builtin_amdgcn_mfma_f32_16x16x32_bf16(Bt[n][k], At[m][k], acc[ai][bj][m][n], 0, 0, 0); __builtin_amdgcn_s_setprio(0); } while (0)
; #define PG8_BAR __builtin_amdgcn_s_barrier()
; template <class Epi, class Sched, bool ALIGN_EPI = false, bool SP2 = false>
; __device__ __forceinline__ void gemm_phase(PG8_LAS unsigned char* lds, const Gemm g, const Sched& S, const Epi& E) {
;     ...
;             if constexpr (SP2) {
;             PG8_LDB(B0, 0, 0); PG8_LDB(B1, 0, 1); PG8_SCHED; PG8_LDA(At, 0, 0); PG8_STAGE(PG8_SA(1, 1), a1 + hA, voffA);
;             PG8_WAIT_V(8); PG8_WAIT_L(0); PG8_BAR; PG8_MMA(0, 0, At, B0); PG8_MMA(0, 1, At, B1); PG8_BAR; PG8_SCHED;
;             PG8_LDA(At, 0, 1); PG8_STAGE(PG8_SB(0, 0), b2, voffB); PG8_STAGE(PG8_SB(0, 1), b2 + hB, voffB); PG8_STAGE(PG8_SA(0, 0), a2, voffA);
;             PG8_WAIT_V(8); PG8_WAIT_L(0); PG8_BAR; PG8_MMA(1, 0, At, B0); PG8_MMA(1, 1, At, B1); PG8_BAR; PG8_SCHED;
;             PG8_LDB(B0, 1, 0); PG8_LDB(B1, 1, 1); PG8_SCHED; PG8_LDA(At, 1, 0); PG8_STAGE(PG8_SA(0, 1), a2 + hA, voffA);
;             PG8_WAIT_V(8); PG8_WAIT_L(0); PG8_BAR; PG8_MMA(0, 0, At, B0); PG8_MMA(0, 1, At, B1); PG8_BAR; PG8_SCHED;
;             PG8_LDA(At, 1, 1); PG8_STAGE(PG8_SB(1, 0), b3, voffB); PG8_STAGE(PG8_SB(1, 1), b3 + hB, voffB); PG8_STAGE(PG8_SA(1, 0), a3, voffA);
;             PG8_WAIT_V(8); PG8_WAIT_L(0); PG8_BAR; PG8_MMA(1, 0, At, B0); PG8_MMA(1, 1, At, B1); PG8_BAR; PG8_SCHED;
.LBB0_824:
	s_add_u32 s18, s16, 0xfffc0080
	s_addc_u32 s19, s17, -1
	s_add_i32 s34, 0, 0x10000
	s_cmp_eq_u32 s85, 12
	s_cselect_b32 s31, s11, s19
	s_cselect_b32 s30, s74, s18
	v_add_u32_e32 v140, s34, v142
	s_cselect_b32 s19, s9, s84
	s_cselect_b32 s18, s75, s79
	s_add_i32 s52, 0, 0x14000
	ds_read_b128 v[136:139], v140
	ds_read_b128 v[144:147], v140 offset:1024
	ds_read_b128 v[148:151], v140 offset:2048
	ds_read_b128 v[152:155], v140 offset:3072
	v_add_u32_e32 v140, s52, v142
	ds_read_b128 v[156:159], v140
	ds_read_b128 v[160:163], v140 offset:1024
	ds_read_b128 v[164:167], v140 offset:2048
	ds_read_b128 v[168:171], v140 offset:3072
	s_add_i32 m0, s41, 0xc000
	ds_read_b128 v[174:177], v143
	ds_read_b128 v[180:183], v143 offset:1024
	ds_read_b128 v[184:187], v143 offset:2048
	ds_read_b128 v[188:191], v143 offset:3072
	ds_read_b128 v[192:195], v143 offset:4096
	ds_read_b128 v[200:203], v143 offset:5120
	ds_read_b128 v[204:207], v143 offset:6144
	ds_read_b128 v[208:211], v143 offset:7168
	global_load_lds_dwordx4 v132, s[16:17]
	s_add_i32 m0, s41, 0xe000
	s_nop 0
	global_load_lds_dwordx4 v134, s[16:17]
	s_waitcnt vmcnt(8)
	s_waitcnt lgkmcnt(0)
	s_barrier
	s_setprio 1
	s_waitcnt lgkmcnt(0)
	v_mfma_f32_16x16x32_bf16 v[124:127], v[136:139], v[174:177], v[124:127]
	v_mfma_f32_16x16x32_bf16 v[120:123], v[148:151], v[174:177], v[120:123]
	v_mfma_f32_16x16x32_bf16 v[108:111], v[136:139], v[184:187], v[108:111]
	v_mfma_f32_16x16x32_bf16 v[104:107], v[148:151], v[184:187], v[104:107]
	v_mfma_f32_16x16x32_bf16 v[92:95], v[136:139], v[192:195], v[92:95]
	v_mfma_f32_16x16x32_bf16 v[88:91], v[148:151], v[192:195], v[88:91]
	v_mfma_f32_16x16x32_bf16 v[76:79], v[136:139], v[204:207], v[76:79]
	v_mfma_f32_16x16x32_bf16 v[72:75], v[148:151], v[204:207], v[72:75]
	v_mfma_f32_16x16x32_bf16 v[124:127], v[144:147], v[180:183], v[124:127]
	v_mfma_f32_16x16x32_bf16 v[120:123], v[152:155], v[180:183], v[120:123]
	v_mfma_f32_16x16x32_bf16 v[108:111], v[144:147], v[188:191], v[108:111]
	v_mfma_f32_16x16x32_bf16 v[104:107], v[152:155], v[188:191], v[104:107]
	v_mfma_f32_16x16x32_bf16 v[92:95], v[144:147], v[200:203], v[92:95]
	v_mfma_f32_16x16x32_bf16 v[88:91], v[152:155], v[200:203], v[88:91]
	v_mfma_f32_16x16x32_bf16 v[76:79], v[144:147], v[208:211], v[76:79]
	v_mfma_f32_16x16x32_bf16 v[72:75], v[152:155], v[208:211], v[72:75]
	s_setprio 0
	s_setprio 1
	v_mfma_f32_16x16x32_bf16 v[116:119], v[156:159], v[174:177], v[116:119]
	v_mfma_f32_16x16x32_bf16 v[112:115], v[164:167], v[174:177], v[112:115]
	v_mfma_f32_16x16x32_bf16 v[100:103], v[156:159], v[184:187], v[100:103]
	v_mfma_f32_16x16x32_bf16 v[96:99], v[164:167], v[184:187], v[96:99]
	v_mfma_f32_16x16x32_bf16 v[84:87], v[156:159], v[192:195], v[84:87]
	v_mfma_f32_16x16x32_bf16 v[80:83], v[164:167], v[192:195], v[80:83]
	v_mfma_f32_16x16x32_bf16 v[68:71], v[156:159], v[204:207], v[68:71]
	v_mfma_f32_16x16x32_bf16 v[64:67], v[164:167], v[204:207], v[64:67]
	v_mfma_f32_16x16x32_bf16 v[116:119], v[160:163], v[180:183], v[116:119]
	v_mfma_f32_16x16x32_bf16 v[112:115], v[168:171], v[180:183], v[112:115]
	v_mfma_f32_16x16x32_bf16 v[100:103], v[160:163], v[188:191], v[100:103]
	v_mfma_f32_16x16x32_bf16 v[96:99], v[168:171], v[188:191], v[96:99]
	v_mfma_f32_16x16x32_bf16 v[84:87], v[160:163], v[200:203], v[84:87]
	v_mfma_f32_16x16x32_bf16 v[80:83], v[168:171], v[200:203], v[80:83]
	v_mfma_f32_16x16x32_bf16 v[68:71], v[160:163], v[208:211], v[68:71]
	v_mfma_f32_16x16x32_bf16 v[64:67], v[168:171], v[208:211], v[64:67]
	s_setprio 0
	s_barrier
	s_add_i32 s34, s34, s40
	v_lshl_add_u64 v[140:141], s[18:19], 0, v[172:173]
	s_mov_b32 m0, s34
	ds_read_b128 v[174:177], v143 offset:16384
	ds_read_b128 v[180:183], v143 offset:17408
	ds_read_b128 v[184:187], v143 offset:18432
	ds_read_b128 v[188:191], v143 offset:19456
	ds_read_b128 v[192:195], v143 offset:20480
	ds_read_b128 v[200:203], v143 offset:21504
	ds_read_b128 v[204:207], v143 offset:22528
	ds_read_b128 v[208:211], v143 offset:23552
	global_load_lds_dwordx4 v[140:141], off
	s_add_i32 m0, s34, 0x2000
	s_add_u32 s34, s18, 0x40000
	v_lshl_add_u64 v[212:213], s[18:19], 0, v[128:129]
	s_addc_u32 s35, s19, 0
	s_add_i32 s52, s52, s40
	global_load_lds_dwordx4 v128, s[18:19]
	v_lshl_add_u64 v[214:215], s[34:35], 0, v[172:173]
	s_mov_b32 m0, s52
	v_lshl_add_u64 v[216:217], s[30:31], 0, v[128:129]
	global_load_lds_dwordx4 v[214:215], off
	s_add_i32 m0, s52, 0x2000
	s_nop 0
	global_load_lds_dwordx4 v128, s[34:35]
	v_lshl_add_u64 v[214:215], s[30:31], 0, v[172:173]
	s_mov_b32 m0, s41
	s_nop 0
	global_load_lds_dwordx4 v[214:215], off
	s_mov_b32 m0, s42
	s_nop 0
	global_load_lds_dwordx4 v128, s[30:31]
	s_waitcnt vmcnt(8)
	s_waitcnt lgkmcnt(0)
	s_barrier
; #define PG8_STAGE(bufoff, gbase, voff) do { _Pragma("unroll") for (int _i = 0; _i < 2; ++_i) \
;         __builtin_amdgcn_global_load_lds((const unsigned*)((const char*)(gbase) + (voff)[_i]), (PG8_LAS unsigned*)(lds + (bufoff) + ldsw + _i * 8192), 16, 0, 0); } while (0)
; #define PG8_LDA(dst, b, h) do { _Pragma("unroll") for (int m = 0; m < 4; ++m) _Pragma("unroll") for (int k = 0; k < 2; ++k) dst[m][k] = *(const PG8_LAS bf16x8*)(lds + PG8_SA(b, h) + aoff + m * 2048 + k * 1024); } while (0)
; #define PG8_LDB(dst, b, h) do { _Pragma("unroll") for (int n = 0; n < 2; ++n) _Pragma("unroll") for (int k = 0; k < 2; ++k) dst[n][k] = *(const PG8_LAS bf16x8*)(lds + PG8_SB(b, h) + boff + n * 2048 + k * 1024); } while (0)
; #define PG8_MMA(ai, bj, At, Bt) do { __builtin_amdgcn_s_setprio(1); _Pragma("unroll") for (int m = 0; m < 4; ++m) _Pragma("unroll") for (int n = 0; n < 2; ++n) _Pragma("unroll") for (int k = 0; k < 2; ++k) \
;         acc[ai][bj][m][n] = __builtin_amdgcn_mfma_f32_16x16x32_bf16(Bt[n][k], At[m][k], acc[ai][bj][m][n], 0, 0, 0); __builtin_amdgcn_s_setprio(0); } while (0)
; #define PG8_BAR __builtin_amdgcn_s_barrier()
; template <class Epi, class Sched, bool ALIGN_EPI = false, bool SP2 = false>
; __device__ __forceinline__ void gemm_phase(PG8_LAS unsigned char* lds, const Gemm g, const Sched& S, const Epi& E) {
;     ...
;             if constexpr (SP2) {
;             PG8_LDB(B0, 0, 0); PG8_LDB(B1, 0, 1); PG8_SCHED; PG8_LDA(At, 0, 0); PG8_STAGE(PG8_SA(1, 1), a1 + hA, voffA);
;             PG8_WAIT_V(8); PG8_WAIT_L(0); PG8_BAR; PG8_MMA(0, 0, At, B0); PG8_MMA(0, 1, At, B1); PG8_BAR; PG8_SCHED;
;             PG8_LDA(At, 0, 1); PG8_STAGE(PG8_SB(0, 0), b2, voffB); PG8_STAGE(PG8_SB(0, 1), b2 + hB, voffB); PG8_STAGE(PG8_SA(0, 0), a2, voffA);
;             PG8_WAIT_V(8); PG8_WAIT_L(0); PG8_BAR; PG8_MMA(1, 0, At, B0); PG8_MMA(1, 1, At, B1); PG8_BAR; PG8_SCHED;
;             PG8_LDB(B0, 1, 0); PG8_LDB(B1, 1, 1); PG8_SCHED; PG8_LDA(At, 1, 0); PG8_STAGE(PG8_SA(0, 1), a2 + hA, voffA);
;             PG8_WAIT_V(8); PG8_WAIT_L(0); PG8_BAR; PG8_MMA(0, 0, At, B0); PG8_MMA(0, 1, At, B1); PG8_BAR; PG8_SCHED;
;             PG8_LDA(At, 1, 1); PG8_STAGE(PG8_SB(1, 0), b3, voffB); PG8_STAGE(PG8_SB(1, 1), b3 + hB, voffB); PG8_STAGE(PG8_SA(1, 0), a3, voffA);
;             PG8_WAIT_V(8); PG8_WAIT_L(0); PG8_BAR; PG8_MMA(1, 0, At, B0); PG8_MMA(1, 1, At, B1); PG8_BAR; PG8_SCHED;
	s_setprio 1
	s_waitcnt lgkmcnt(0)
	v_mfma_f32_16x16x32_bf16 v[60:63], v[136:139], v[174:177], v[60:63]
	v_mfma_f32_16x16x32_bf16 v[56:59], v[148:151], v[174:177], v[56:59]
	v_mfma_f32_16x16x32_bf16 v[44:47], v[136:139], v[184:187], v[44:47]
	v_mfma_f32_16x16x32_bf16 v[40:43], v[148:151], v[184:187], v[40:43]
	v_mfma_f32_16x16x32_bf16 v[28:31], v[136:139], v[192:195], v[28:31]
	v_mfma_f32_16x16x32_bf16 v[24:27], v[148:151], v[192:195], v[24:27]
	v_mfma_f32_16x16x32_bf16 v[12:15], v[136:139], v[204:207], v[12:15]
	v_mfma_f32_16x16x32_bf16 v[8:11], v[148:151], v[204:207], v[8:11]
	v_mfma_f32_16x16x32_bf16 v[60:63], v[144:147], v[180:183], v[60:63]
	v_mfma_f32_16x16x32_bf16 v[56:59], v[152:155], v[180:183], v[56:59]
	v_mfma_f32_16x16x32_bf16 v[44:47], v[144:147], v[188:191], v[44:47]
	v_mfma_f32_16x16x32_bf16 v[40:43], v[152:155], v[188:191], v[40:43]
	v_mfma_f32_16x16x32_bf16 v[28:31], v[144:147], v[200:203], v[28:31]
	v_mfma_f32_16x16x32_bf16 v[24:27], v[152:155], v[200:203], v[24:27]
	v_mfma_f32_16x16x32_bf16 v[12:15], v[144:147], v[208:211], v[12:15]
	v_mfma_f32_16x16x32_bf16 v[8:11], v[152:155], v[208:211], v[8:11]
	s_setprio 0
	s_setprio 1
	v_mfma_f32_16x16x32_bf16 v[52:55], v[156:159], v[174:177], v[52:55]
	v_mfma_f32_16x16x32_bf16 v[48:51], v[164:167], v[174:177], v[48:51]
	v_mfma_f32_16x16x32_bf16 v[36:39], v[156:159], v[184:187], v[36:39]
	v_mfma_f32_16x16x32_bf16 v[32:35], v[164:167], v[184:187], v[32:35]
	v_mfma_f32_16x16x32_bf16 v[20:23], v[156:159], v[192:195], v[20:23]
	v_mfma_f32_16x16x32_bf16 v[16:19], v[164:167], v[192:195], v[16:19]
	v_mfma_f32_16x16x32_bf16 v[4:7], v[156:159], v[204:207], v[4:7]
	v_mfma_f32_16x16x32_bf16 v[0:3], v[164:167], v[204:207], v[0:3]
	v_mfma_f32_16x16x32_bf16 v[52:55], v[160:163], v[180:183], v[52:55]
	v_mfma_f32_16x16x32_bf16 v[48:51], v[168:171], v[180:183], v[48:51]
	v_mfma_f32_16x16x32_bf16 v[36:39], v[160:163], v[188:191], v[36:39]
	v_mfma_f32_16x16x32_bf16 v[32:35], v[168:171], v[188:191], v[32:35]
	v_mfma_f32_16x16x32_bf16 v[20:23], v[160:163], v[200:203], v[20:23]
	v_mfma_f32_16x16x32_bf16 v[16:19], v[168:171], v[200:203], v[16:19]
	v_mfma_f32_16x16x32_bf16 v[4:7], v[160:163], v[208:211], v[4:7]
	v_mfma_f32_16x16x32_bf16 v[0:3], v[168:171], v[208:211], v[0:3]
	s_setprio 0
	s_barrier
	s_add_i32 s34, 0, 0x18000
	s_add_i32 s35, 0, 0x1c000
	v_add_u32_e32 v152, s34, v142
	v_add_u32_e32 v168, s35, v142
	ds_read_b128 v[136:139], v152
	ds_read_b128 v[144:147], v152 offset:1024
	ds_read_b128 v[148:151], v152 offset:2048
	ds_read_b128 v[152:155], v152 offset:3072
	ds_read_b128 v[156:159], v168
	ds_read_b128 v[160:163], v168 offset:1024
	ds_read_b128 v[164:167], v168 offset:2048
	ds_read_b128 v[168:171], v168 offset:3072
	s_add_u32 s30, s30, 0x40000
	s_addc_u32 s31, s31, 0
	s_mov_b32 m0, s43
	v_lshl_add_u64 v[218:219], s[30:31], 0, v[172:173]
	ds_read_b128 v[174:177], v143 offset:32768
	ds_read_b128 v[180:183], v143 offset:33792
	ds_read_b128 v[184:187], v143 offset:34816
	ds_read_b128 v[188:191], v143 offset:35840
	ds_read_b128 v[192:195], v143 offset:36864
	ds_read_b128 v[200:203], v143 offset:37888
	ds_read_b128 v[204:207], v143 offset:38912
	ds_read_b128 v[208:211], v143 offset:39936
	global_load_lds_dwordx4 v[218:219], off
	s_mov_b32 m0, s68
	s_nop 0
	global_load_lds_dwordx4 v128, s[30:31]
	s_waitcnt vmcnt(8)
	s_waitcnt lgkmcnt(0)
	s_barrier
	s_setprio 1
	s_waitcnt lgkmcnt(0)
	v_mfma_f32_16x16x32_bf16 v[124:127], v[136:139], v[174:177], v[124:127]
	v_mfma_f32_16x16x32_bf16 v[120:123], v[148:151], v[174:177], v[120:123]
	v_mfma_f32_16x16x32_bf16 v[108:111], v[136:139], v[184:187], v[108:111]
	v_mfma_f32_16x16x32_bf16 v[104:107], v[148:151], v[184:187], v[104:107]
	v_mfma_f32_16x16x32_bf16 v[92:95], v[136:139], v[192:195], v[92:95]
	v_mfma_f32_16x16x32_bf16 v[88:91], v[148:151], v[192:195], v[88:91]
	v_mfma_f32_16x16x32_bf16 v[76:79], v[136:139], v[204:207], v[76:79]
	v_mfma_f32_16x16x32_bf16 v[72:75], v[148:151], v[204:207], v[72:75]
	v_mfma_f32_16x16x32_bf16 v[124:127], v[144:147], v[180:183], v[124:127]
	v_mfma_f32_16x16x32_bf16 v[120:123], v[152:155], v[180:183], v[120:123]
	v_mfma_f32_16x16x32_bf16 v[108:111], v[144:147], v[188:191], v[108:111]
	v_mfma_f32_16x16x32_bf16 v[104:107], v[152:155], v[188:191], v[104:107]
	v_mfma_f32_16x16x32_bf16 v[92:95], v[144:147], v[200:203], v[92:95]
	v_mfma_f32_16x16x32_bf16 v[88:91], v[152:155], v[200:203], v[88:91]
	v_mfma_f32_16x16x32_bf16 v[76:79], v[144:147], v[208:211], v[76:79]
	v_mfma_f32_16x16x32_bf16 v[72:75], v[152:155], v[208:211], v[72:75]
	s_setprio 0
	s_setprio 1
	v_mfma_f32_16x16x32_bf16 v[116:119], v[156:159], v[174:177], v[116:119]
	v_mfma_f32_16x16x32_bf16 v[112:115], v[164:167], v[174:177], v[112:115]
	v_mfma_f32_16x16x32_bf16 v[100:103], v[156:159], v[184:187], v[100:103]
	v_mfma_f32_16x16x32_bf16 v[96:99], v[164:167], v[184:187], v[96:99]
	v_mfma_f32_16x16x32_bf16 v[84:87], v[156:159], v[192:195], v[84:87]
	v_mfma_f32_16x16x32_bf16 v[80:83], v[164:167], v[192:195], v[80:83]
	v_mfma_f32_16x16x32_bf16 v[68:71], v[156:159], v[204:207], v[68:71]
	v_mfma_f32_16x16x32_bf16 v[64:67], v[164:167], v[204:207], v[64:67]
	v_mfma_f32_16x16x32_bf16 v[116:119], v[160:163], v[180:183], v[116:119]
	v_mfma_f32_16x16x32_bf16 v[112:115], v[168:171], v[180:183], v[112:115]
	v_mfma_f32_16x16x32_bf16 v[100:103], v[160:163], v[188:191], v[100:103]
	v_mfma_f32_16x16x32_bf16 v[96:99], v[168:171], v[188:191], v[96:99]
	v_mfma_f32_16x16x32_bf16 v[84:87], v[160:163], v[200:203], v[84:87]
	v_mfma_f32_16x16x32_bf16 v[80:83], v[168:171], v[200:203], v[80:83]
	v_mfma_f32_16x16x32_bf16 v[68:71], v[160:163], v[208:211], v[68:71]
	v_mfma_f32_16x16x32_bf16 v[64:67], v[168:171], v[208:211], v[64:67]
	s_setprio 0
	s_barrier
; #define PG8_STAGE(bufoff, gbase, voff) do { _Pragma("unroll") for (int _i = 0; _i < 2; ++_i) \
;         __builtin_amdgcn_global_load_lds((const unsigned*)((const char*)(gbase) + (voff)[_i]), (PG8_LAS unsigned*)(lds + (bufoff) + ldsw + _i * 8192), 16, 0, 0); } while (0)
; #define PG8_LDA(dst, b, h) do { _Pragma("unroll") for (int m = 0; m < 4; ++m) _Pragma("unroll") for (int k = 0; k < 2; ++k) dst[m][k] = *(const PG8_LAS bf16x8*)(lds + PG8_SA(b, h) + aoff + m * 2048 + k * 1024); } while (0)
; #define PG8_LDB(dst, b, h) do { _Pragma("unroll") for (int n = 0; n < 2; ++n) _Pragma("unroll") for (int k = 0; k < 2; ++k) dst[n][k] = *(const PG8_LAS bf16x8*)(lds + PG8_SB(b, h) + boff + n * 2048 + k * 1024); } while (0)
; #define PG8_MMA(ai, bj, At, Bt) do { __builtin_amdgcn_s_setprio(1); _Pragma("unroll") for (int m = 0; m < 4; ++m) _Pragma("unroll") for (int n = 0; n < 2; ++n) _Pragma("unroll") for (int k = 0; k < 2; ++k) \
;         acc[ai][bj][m][n] = __builtin_amdgcn_mfma_f32_16x16x32_bf16(Bt[n][k], At[m][k], acc[ai][bj][m][n], 0, 0, 0); __builtin_amdgcn_s_setprio(0); } while (0)
; #define PG8_BAR __builtin_amdgcn_s_barrier()
; template <class Epi, class Sched, bool ALIGN_EPI = false, bool SP2 = false>
; __device__ __forceinline__ void gemm_phase(PG8_LAS unsigned char* lds, const Gemm g, const Sched& S, const Epi& E) {
;     ...
;             if constexpr (SP2) {
;             PG8_LDB(B0, 0, 0); PG8_LDB(B1, 0, 1); PG8_SCHED; PG8_LDA(At, 0, 0); PG8_STAGE(PG8_SA(1, 1), a1 + hA, voffA);
;             PG8_WAIT_V(8); PG8_WAIT_L(0); PG8_BAR; PG8_MMA(0, 0, At, B0); PG8_MMA(0, 1, At, B1); PG8_BAR; PG8_SCHED;
;             PG8_LDA(At, 0, 1); PG8_STAGE(PG8_SB(0, 0), b2, voffB); PG8_STAGE(PG8_SB(0, 1), b2 + hB, voffB); PG8_STAGE(PG8_SA(0, 0), a2, voffA);
;             PG8_WAIT_V(8); PG8_WAIT_L(0); PG8_BAR; PG8_MMA(1, 0, At, B0); PG8_MMA(1, 1, At, B1); PG8_BAR; PG8_SCHED;
;             PG8_LDB(B0, 1, 0); PG8_LDB(B1, 1, 1); PG8_SCHED; PG8_LDA(At, 1, 0); PG8_STAGE(PG8_SA(0, 1), a2 + hA, voffA);
;             PG8_WAIT_V(8); PG8_WAIT_L(0); PG8_BAR; PG8_MMA(0, 0, At, B0); PG8_MMA(0, 1, At, B1); PG8_BAR; PG8_SCHED;
;             PG8_LDA(At, 1, 1); PG8_STAGE(PG8_SB(1, 0), b3, voffB); PG8_STAGE(PG8_SB(1, 1), b3 + hB, voffB); PG8_STAGE(PG8_SA(1, 0), a3, voffA);
;             PG8_WAIT_V(8); PG8_WAIT_L(0); PG8_BAR; PG8_MMA(1, 0, At, B0); PG8_MMA(1, 1, At, B1); PG8_BAR; PG8_SCHED;
	s_add_i32 s30, s34, s40
	v_lshl_add_u64 v[140:141], v[140:141], 0, s[76:77]
	s_mov_b32 m0, s30
	ds_read_b128 v[174:177], v143 offset:49152
	ds_read_b128 v[180:183], v143 offset:50176
	ds_read_b128 v[184:187], v143 offset:51200
	ds_read_b128 v[188:191], v143 offset:52224
	ds_read_b128 v[192:195], v143 offset:53248
	ds_read_b128 v[200:203], v143 offset:54272
	ds_read_b128 v[204:207], v143 offset:55296
	ds_read_b128 v[208:211], v143 offset:56320
	global_load_lds_dwordx4 v[140:141], off
	s_add_i32 m0, s30, 0x2000
	s_add_u32 s18, s18, 0x40080
	v_lshl_add_u64 v[140:141], v[212:213], 0, s[76:77]
	s_addc_u32 s19, s19, 0
	s_add_i32 s30, s35, s40
	global_load_lds_dwordx4 v[140:141], off
	v_lshl_add_u64 v[140:141], s[18:19], 0, v[172:173]
	s_mov_b32 m0, s30
	s_nop 0
	global_load_lds_dwordx4 v[140:141], off
	s_add_i32 m0, s30, 0x2000
	s_nop 0
	global_load_lds_dwordx4 v128, s[18:19]
	v_lshl_add_u64 v[140:141], v[214:215], 0, s[76:77]
	s_mov_b32 m0, s70
	s_nop 0
	global_load_lds_dwordx4 v[140:141], off
	v_lshl_add_u64 v[140:141], v[216:217], 0, s[76:77]
	s_mov_b32 m0, s71
	s_nop 0
	global_load_lds_dwordx4 v[140:141], off
	s_waitcnt vmcnt(8)
	s_waitcnt lgkmcnt(0)
	s_barrier
	s_setprio 1
	s_waitcnt lgkmcnt(0)
	v_mfma_f32_16x16x32_bf16 v[60:63], v[136:139], v[174:177], v[60:63]
	v_mfma_f32_16x16x32_bf16 v[56:59], v[148:151], v[174:177], v[56:59]
	v_mfma_f32_16x16x32_bf16 v[44:47], v[136:139], v[184:187], v[44:47]
	v_mfma_f32_16x16x32_bf16 v[40:43], v[148:151], v[184:187], v[40:43]
	v_mfma_f32_16x16x32_bf16 v[28:31], v[136:139], v[192:195], v[28:31]
	v_mfma_f32_16x16x32_bf16 v[24:27], v[148:151], v[192:195], v[24:27]
	v_mfma_f32_16x16x32_bf16 v[12:15], v[136:139], v[204:207], v[12:15]
	v_mfma_f32_16x16x32_bf16 v[8:11], v[148:151], v[204:207], v[8:11]
	v_mfma_f32_16x16x32_bf16 v[60:63], v[144:147], v[180:183], v[60:63]
	v_mfma_f32_16x16x32_bf16 v[56:59], v[152:155], v[180:183], v[56:59]
	v_mfma_f32_16x16x32_bf16 v[44:47], v[144:147], v[188:191], v[44:47]
	v_mfma_f32_16x16x32_bf16 v[40:43], v[152:155], v[188:191], v[40:43]
	v_mfma_f32_16x16x32_bf16 v[28:31], v[144:147], v[200:203], v[28:31]
	v_mfma_f32_16x16x32_bf16 v[24:27], v[152:155], v[200:203], v[24:27]
	v_mfma_f32_16x16x32_bf16 v[12:15], v[144:147], v[208:211], v[12:15]
	v_mfma_f32_16x16x32_bf16 v[8:11], v[152:155], v[208:211], v[8:11]
	s_setprio 0
	s_setprio 1
	v_mfma_f32_16x16x32_bf16 v[52:55], v[156:159], v[174:177], v[52:55]
	v_mfma_f32_16x16x32_bf16 v[48:51], v[164:167], v[174:177], v[48:51]
	v_mfma_f32_16x16x32_bf16 v[36:39], v[156:159], v[184:187], v[36:39]
	v_mfma_f32_16x16x32_bf16 v[32:35], v[164:167], v[184:187], v[32:35]
	v_mfma_f32_16x16x32_bf16 v[20:23], v[156:159], v[192:195], v[20:23]
	v_mfma_f32_16x16x32_bf16 v[16:19], v[164:167], v[192:195], v[16:19]
	v_mfma_f32_16x16x32_bf16 v[4:7], v[156:159], v[204:207], v[4:7]
	v_mfma_f32_16x16x32_bf16 v[0:3], v[164:167], v[204:207], v[0:3]
	v_mfma_f32_16x16x32_bf16 v[52:55], v[160:163], v[180:183], v[52:55]
	v_mfma_f32_16x16x32_bf16 v[48:51], v[168:171], v[180:183], v[48:51]
	v_mfma_f32_16x16x32_bf16 v[36:39], v[160:163], v[188:191], v[36:39]
	v_mfma_f32_16x16x32_bf16 v[32:35], v[168:171], v[188:191], v[32:35]
	v_mfma_f32_16x16x32_bf16 v[20:23], v[160:163], v[200:203], v[20:23]
	v_mfma_f32_16x16x32_bf16 v[16:19], v[168:171], v[200:203], v[16:19]
	v_mfma_f32_16x16x32_bf16 v[4:7], v[160:163], v[208:211], v[4:7]
	v_mfma_f32_16x16x32_bf16 v[0:3], v[168:171], v[208:211], v[0:3]
	s_setprio 0
	s_barrier
	s_add_i32 s85, s85, 2
	s_add_u32 s16, s16, 0x100
	s_addc_u32 s17, s17, 0
	s_add_u32 s79, s79, 0x100
	s_addc_u32 s84, s84, 0
	s_cmp_gt_u32 s85, 13
	s_cbranch_scc0 .LBB0_824
	s_and_b64 vcc, exec, s[6:7]
	s_cbranch_vccz .LBB0_827
	s_barrier

; #define PG8_STAGE(bufoff, gbase, voff) do { _Pragma("unroll") for (int _i = 0; _i < 2; ++_i) \
;         __builtin_amdgcn_global_load_lds((const unsigned*)((const char*)(gbase) + (voff)[_i]), (PG8_LAS unsigned*)(lds + (bufoff) + ldsw + _i * 8192), 16, 0, 0); } while (0)
; #define PG8_WAIT_V(n) asm volatile("s_waitcnt vmcnt(" #n ")" ::: "memory")
; #define PG8_BAR __builtin_amdgcn_s_barrier()
; template <class Epi, class Sched, bool ALIGN_EPI = false, bool SP2 = false>
; __device__ __forceinline__ void gemm_phase(PG8_LAS unsigned char* lds, const Gemm g, const Sched& S, const Epi& E) {
;     ...
;     for (int i = 0; i < 2; ++i) { int R, C; stage_rc(tid * 16 + i * 8192, R, C); const int Rb = Epi::PERM ? ((R & ~31) + perm32(R & 31)) : R;
;         voffA[i] = (unsigned)(R * g.lda + C) * 2u; voffB[i] = (unsigned)(Rb * g.ldb + C) * 2u; }
;     const size_t kstep = (size_t)(BK * 2);
;     const size_t hA = (size_t)HALF * g.lda * 2, hB = (size_t)HALF * g.ldb * 2;
;     const size_t tA = 2 * hA, tB = 2 * hB;
;     const unsigned ldsw = (unsigned)wid * 1024u;
;     const int aoff = lds_byte(wr * 64 + fr, fq * 8), boff = lds_byte(wc * 32 + fr, fq * 8);
;     ...
;         PG8_STAGE(PG8_SB(0, 0), cB, voffB); PG8_STAGE(PG8_SB(0, 1), cB + hB, voffB); PG8_STAGE(PG8_SA(0, 0), cA, voffA); PG8_STAGE(PG8_SA(0, 1), cA + hA, voffA);
;         if (wr == 1) PG8_BAR;
;         PG8_WAIT_V(2); PG8_BAR;
;         PG8_STAGE(PG8_SB(1, 0), cB + kstep, voffB); PG8_STAGE(PG8_SA(1, 0), cA + kstep, voffA); PG8_STAGE(PG8_SB(1, 1), cB + hB + kstep, voffB);
;         PG8_WAIT_V(6); PG8_BAR;
.LBB0_902:
	v_readlane_b32 s18, v253, 47
	v_mov_b32_e32 v133, v173
	v_readlane_b32 s19, v253, 48
	v_mov_b32_e32 v129, v173
	v_readlane_b32 s14, v253, 43
	v_lshl_add_u64 v[8:9], s[18:19], 0, v[132:133]
	v_lshl_add_u64 v[10:11], s[18:19], 0, v[128:129]
	v_mov_b32_e32 v135, v173
	v_readlane_b32 s15, v253, 44
	s_add_i32 m0, s41, 0x18000
	v_lshl_add_u64 v[8:9], v[8:9], 0, s[76:77]
	v_lshl_add_u64 v[12:13], s[14:15], 0, v[134:135]
	v_mov_b32_e32 v131, v173
	s_waitcnt vmcnt(2)
	s_barrier
	global_load_lds_dwordx4 v[8:9], off
	v_lshl_add_u64 v[8:9], v[10:11], 0, s[76:77]
	s_add_i32 m0, s41, 0x1a000
	s_add_i32 s47, s41, 0x8000
	v_lshl_add_u64 v[14:15], s[14:15], 0, v[130:131]
	global_load_lds_dwordx4 v[8:9], off
	v_lshl_add_u64 v[8:9], v[12:13], 0, s[76:77]
	s_mov_b32 m0, s47
	s_add_i32 s48, s41, 0xa000
	v_readlane_b32 s10, v253, 49
	global_load_lds_dwordx4 v[8:9], off
	v_lshl_add_u64 v[8:9], v[14:15], 0, s[76:77]
	s_mov_b32 m0, s48
	v_readlane_b32 s11, v253, 50
	global_load_lds_dwordx4 v[8:9], off
	s_add_i32 m0, s41, 0x1c000
	s_nop 0
	s_nop 1
	global_load_lds_dwordx4 v132, s[10:11]
	s_add_i32 m0, s41, 0x1e000
	v_and_b32_e32 v7, 15, v2
	global_load_lds_dwordx4 v128, s[10:11]
	v_lshrrev_b32_e32 v8, 1, v2
	v_and_b32_e32 v8, 24, v8
	v_lshlrev_b32_e32 v9, 1, v8
	v_lshlrev_b32_e32 v2, 2, v2
	s_lshl_b32 s1, s1, 5
	v_lshl_or_b32 v142, s8, 6, v7
	v_lshl_or_b32 v7, v7, 6, v9
	s_lshl_b32 s8, s8, 13
	v_and_b32_e32 v2, 32, v2
	s_and_b32 s1, s1, 0x60
	v_bitop3_b32 v9, v7, s8, v2 bitop3:0xde
	s_lshl_b32 s8, s1, 7
	v_bitop3_b32 v143, v7, s8, v2 bitop3:0xde
	v_lshlrev_b32_e32 v2, 14, v5
	v_and_b32_e32 v2, 0xffff8000, v2
	v_lshl_add_u32 v2, v4, 11, v2
	v_and_b32_e32 v4, 1, v5
	v_lshl_or_b32 v2, v4, 6, v2
	v_lshl_add_u32 v136, v6, 1, v2
	v_lshlrev_b32_e32 v2, 14, v0
	s_cmpk_lt_u32 s0, 0x100
	v_and_b32_e32 v2, 0xffff8000, v2
	s_waitcnt vmcnt(6)
	s_cselect_b64 s[8:9], -1, 0
	v_lshl_add_u32 v1, v1, 11, v2
	v_and_b32_e32 v0, 1, v0
	s_lshl_b32 s68, s1, 1
	v_readlane_b32 s0, v253, 37
	v_lshl_or_b32 v0, v0, 6, v1
	v_readlane_b32 s1, v253, 38
	v_mov_b32_e32 v137, v173
	v_lshl_add_u32 v138, v3, 1, v0
	v_mov_b32_e32 v139, v173
	s_mov_b32 s49, 0
	v_add_u32_e32 v144, 0, v9
	v_lshlrev_b32_e32 v172, 1, v8
	v_readlane_b32 s50, v253, 35
	s_mov_b32 s51, s0
	s_mov_b64 s[0:1], s[14:15]
	s_barrier
	s_branch .LBB0_905

; #define PG8_STAGE(bufoff, gbase, voff) do { _Pragma("unroll") for (int _i = 0; _i < 2; ++_i) \
;         __builtin_amdgcn_global_load_lds((const unsigned*)((const char*)(gbase) + (voff)[_i]), (PG8_LAS unsigned*)(lds + (bufoff) + ldsw + _i * 8192), 16, 0, 0); } while (0)
; #define PG8_LDA(dst, b, h) do { _Pragma("unroll") for (int m = 0; m < 4; ++m) _Pragma("unroll") for (int k = 0; k < 2; ++k) dst[m][k] = *(const PG8_LAS bf16x8*)(lds + PG8_SA(b, h) + aoff + m * 2048 + k * 1024); } while (0)
; #define PG8_LDB(dst, b, h) do { _Pragma("unroll") for (int n = 0; n < 2; ++n) _Pragma("unroll") for (int k = 0; k < 2; ++k) dst[n][k] = *(const PG8_LAS bf16x8*)(lds + PG8_SB(b, h) + boff + n * 2048 + k * 1024); } while (0)
; #define PG8_MMA(ai, bj, At, Bt) do { __builtin_amdgcn_s_setprio(1); _Pragma("unroll") for (int m = 0; m < 4; ++m) _Pragma("unroll") for (int n = 0; n < 2; ++n) _Pragma("unroll") for (int k = 0; k < 2; ++k) \
;         acc[ai][bj][m][n] = __builtin_amdgcn_mfma_f32_16x16x32_bf16(Bt[n][k], At[m][k], acc[ai][bj][m][n], 0, 0, 0); __builtin_amdgcn_s_setprio(0); } while (0)
; #define PG8_BAR __builtin_amdgcn_s_barrier()
; template <class Epi, class Sched, bool ALIGN_EPI = false, bool SP2 = false>
; __device__ __forceinline__ void gemm_phase(PG8_LAS unsigned char* lds, const Gemm g, const Sched& S, const Epi& E) {
;     ...
;             if constexpr (SP2) {
;             PG8_LDB(B0, 0, 0); PG8_LDB(B1, 0, 1); PG8_SCHED; PG8_LDA(At, 0, 0); PG8_STAGE(PG8_SA(1, 1), a1 + hA, voffA);
;             PG8_WAIT_V(8); PG8_WAIT_L(0); PG8_BAR; PG8_MMA(0, 0, At, B0); PG8_MMA(0, 1, At, B1); PG8_BAR; PG8_SCHED;
;             PG8_LDA(At, 0, 1); PG8_STAGE(PG8_SB(0, 0), b2, voffB); PG8_STAGE(PG8_SB(0, 1), b2 + hB, voffB); PG8_STAGE(PG8_SA(0, 0), a2, voffA);
;             PG8_WAIT_V(8); PG8_WAIT_L(0); PG8_BAR; PG8_MMA(1, 0, At, B0); PG8_MMA(1, 1, At, B1); PG8_BAR; PG8_SCHED;
;             PG8_LDB(B0, 1, 0); PG8_LDB(B1, 1, 1); PG8_SCHED; PG8_LDA(At, 1, 0); PG8_STAGE(PG8_SA(0, 1), a2 + hA, voffA);
;             PG8_WAIT_V(8); PG8_WAIT_L(0); PG8_BAR; PG8_MMA(0, 0, At, B0); PG8_MMA(0, 1, At, B1); PG8_BAR; PG8_SCHED;
;             PG8_LDA(At, 1, 1); PG8_STAGE(PG8_SB(1, 0), b3, voffB); PG8_STAGE(PG8_SB(1, 1), b3 + hB, voffB); PG8_STAGE(PG8_SA(1, 0), a3, voffA);
;             PG8_WAIT_V(8); PG8_WAIT_L(0); PG8_BAR; PG8_MMA(1, 0, At, B0); PG8_MMA(1, 1, At, B1); PG8_BAR; PG8_SCHED;
.LBB0_912:
	s_add_u32 s18, s0, 0xfffc0080
	s_addc_u32 s19, s1, -1
	s_add_i32 s34, 0, 0x10000
	s_cmp_eq_u32 s79, 12
	s_cselect_b32 s31, s13, s19
	s_cselect_b32 s30, s70, s18
	v_add_u32_e32 v140, s34, v143
	s_cselect_b32 s19, s11, s75
	s_cselect_b32 s18, s71, s74
	s_add_i32 s52, 0, 0x14000
	ds_read_b128 v[146:149], v140
	ds_read_b128 v[150:153], v140 offset:1024
	ds_read_b128 v[154:157], v140 offset:2048
	ds_read_b128 v[158:161], v140 offset:3072
	v_add_u32_e32 v140, s52, v143
	ds_read_b128 v[162:165], v140
	ds_read_b128 v[166:169], v140 offset:1024
	ds_read_b128 v[174:177], v140 offset:2048
	ds_read_b128 v[180:183], v140 offset:3072
	s_add_i32 m0, s41, 0xc000
	ds_read_b128 v[184:187], v144
	ds_read_b128 v[188:191], v144 offset:1024
	ds_read_b128 v[192:195], v144 offset:2048
	ds_read_b128 v[200:203], v144 offset:3072
	ds_read_b128 v[204:207], v144 offset:4096
	ds_read_b128 v[208:211], v144 offset:5120
	ds_read_b128 v[212:215], v144 offset:6144
	ds_read_b128 v[216:219], v144 offset:7168
	global_load_lds_dwordx4 v136, s[0:1]
	s_add_i32 m0, s41, 0xe000
	s_nop 0
	global_load_lds_dwordx4 v138, s[0:1]
	s_waitcnt vmcnt(8)
	s_waitcnt lgkmcnt(0)
	s_barrier
	s_setprio 1
	s_waitcnt lgkmcnt(0)
	v_mfma_f32_16x16x32_bf16 v[124:127], v[146:149], v[184:187], v[124:127]
	v_mfma_f32_16x16x32_bf16 v[120:123], v[154:157], v[184:187], v[120:123]
	v_mfma_f32_16x16x32_bf16 v[108:111], v[146:149], v[192:195], v[108:111]
	v_mfma_f32_16x16x32_bf16 v[104:107], v[154:157], v[192:195], v[104:107]
	v_mfma_f32_16x16x32_bf16 v[92:95], v[146:149], v[204:207], v[92:95]
	v_mfma_f32_16x16x32_bf16 v[88:91], v[154:157], v[204:207], v[88:91]
	v_mfma_f32_16x16x32_bf16 v[76:79], v[146:149], v[212:215], v[76:79]
	v_mfma_f32_16x16x32_bf16 v[72:75], v[154:157], v[212:215], v[72:75]
	v_mfma_f32_16x16x32_bf16 v[124:127], v[150:153], v[188:191], v[124:127]
	v_mfma_f32_16x16x32_bf16 v[120:123], v[158:161], v[188:191], v[120:123]
	v_mfma_f32_16x16x32_bf16 v[108:111], v[150:153], v[200:203], v[108:111]
	v_mfma_f32_16x16x32_bf16 v[104:107], v[158:161], v[200:203], v[104:107]
	v_mfma_f32_16x16x32_bf16 v[92:95], v[150:153], v[208:211], v[92:95]
	v_mfma_f32_16x16x32_bf16 v[88:91], v[158:161], v[208:211], v[88:91]
	v_mfma_f32_16x16x32_bf16 v[76:79], v[150:153], v[216:219], v[76:79]
	v_mfma_f32_16x16x32_bf16 v[72:75], v[158:161], v[216:219], v[72:75]
	s_setprio 0
	s_setprio 1
	v_mfma_f32_16x16x32_bf16 v[116:119], v[162:165], v[184:187], v[116:119]
	v_mfma_f32_16x16x32_bf16 v[112:115], v[174:177], v[184:187], v[112:115]
	v_mfma_f32_16x16x32_bf16 v[100:103], v[162:165], v[192:195], v[100:103]
	v_mfma_f32_16x16x32_bf16 v[96:99], v[174:177], v[192:195], v[96:99]
	v_mfma_f32_16x16x32_bf16 v[84:87], v[162:165], v[204:207], v[84:87]
	v_mfma_f32_16x16x32_bf16 v[80:83], v[174:177], v[204:207], v[80:83]
	v_mfma_f32_16x16x32_bf16 v[68:71], v[162:165], v[212:215], v[68:71]
	v_mfma_f32_16x16x32_bf16 v[64:67], v[174:177], v[212:215], v[64:67]
	v_mfma_f32_16x16x32_bf16 v[116:119], v[166:169], v[188:191], v[116:119]
	v_mfma_f32_16x16x32_bf16 v[112:115], v[180:183], v[188:191], v[112:115]
	v_mfma_f32_16x16x32_bf16 v[100:103], v[166:169], v[200:203], v[100:103]
	v_mfma_f32_16x16x32_bf16 v[96:99], v[180:183], v[200:203], v[96:99]
	v_mfma_f32_16x16x32_bf16 v[84:87], v[166:169], v[208:211], v[84:87]
	v_mfma_f32_16x16x32_bf16 v[80:83], v[180:183], v[208:211], v[80:83]
	v_mfma_f32_16x16x32_bf16 v[68:71], v[166:169], v[216:219], v[68:71]
	v_mfma_f32_16x16x32_bf16 v[64:67], v[180:183], v[216:219], v[64:67]
	s_setprio 0
	s_barrier
	s_add_i32 s34, s34, s40
	v_lshl_add_u64 v[140:141], s[18:19], 0, v[132:133]
	s_mov_b32 m0, s34
	ds_read_b128 v[184:187], v144 offset:16384
	ds_read_b128 v[188:191], v144 offset:17408
	ds_read_b128 v[192:195], v144 offset:18432
	ds_read_b128 v[200:203], v144 offset:19456
	ds_read_b128 v[204:207], v144 offset:20480
	ds_read_b128 v[208:211], v144 offset:21504
	ds_read_b128 v[212:215], v144 offset:22528
	ds_read_b128 v[216:219], v144 offset:23552
	global_load_lds_dwordx4 v132, s[18:19]
	s_add_i32 m0, s34, 0x2000
	s_add_u32 s34, s18, 0x40000
	v_lshl_add_u64 v[170:171], s[18:19], 0, v[128:129]
	s_addc_u32 s35, s19, 0
	s_add_i32 s52, s52, s40
	global_load_lds_dwordx4 v128, s[18:19]
	s_mov_b32 m0, s52
	v_lshl_add_u64 v[222:223], s[30:31], 0, v[130:131]
	global_load_lds_dwordx4 v132, s[34:35]
	s_add_i32 m0, s52, 0x2000
	s_nop 0
	global_load_lds_dwordx4 v128, s[34:35]
	v_lshl_add_u64 v[220:221], s[30:31], 0, v[134:135]
	s_mov_b32 m0, s41
	s_nop 0
	global_load_lds_dwordx4 v134, s[30:31]
	s_mov_b32 m0, s44
	s_nop 0
	global_load_lds_dwordx4 v130, s[30:31]
	s_waitcnt vmcnt(8)
	s_waitcnt lgkmcnt(0)
	s_barrier
; #define PG8_STAGE(bufoff, gbase, voff) do { _Pragma("unroll") for (int _i = 0; _i < 2; ++_i) \
;         __builtin_amdgcn_global_load_lds((const unsigned*)((const char*)(gbase) + (voff)[_i]), (PG8_LAS unsigned*)(lds + (bufoff) + ldsw + _i * 8192), 16, 0, 0); } while (0)
; #define PG8_LDA(dst, b, h) do { _Pragma("unroll") for (int m = 0; m < 4; ++m) _Pragma("unroll") for (int k = 0; k < 2; ++k) dst[m][k] = *(const PG8_LAS bf16x8*)(lds + PG8_SA(b, h) + aoff + m * 2048 + k * 1024); } while (0)
; #define PG8_LDB(dst, b, h) do { _Pragma("unroll") for (int n = 0; n < 2; ++n) _Pragma("unroll") for (int k = 0; k < 2; ++k) dst[n][k] = *(const PG8_LAS bf16x8*)(lds + PG8_SB(b, h) + boff + n * 2048 + k * 1024); } while (0)
; #define PG8_MMA(ai, bj, At, Bt) do { __builtin_amdgcn_s_setprio(1); _Pragma("unroll") for (int m = 0; m < 4; ++m) _Pragma("unroll") for (int n = 0; n < 2; ++n) _Pragma("unroll") for (int k = 0; k < 2; ++k) \
;         acc[ai][bj][m][n] = __builtin_amdgcn_mfma_f32_16x16x32_bf16(Bt[n][k], At[m][k], acc[ai][bj][m][n], 0, 0, 0); __builtin_amdgcn_s_setprio(0); } while (0)
; #define PG8_BAR __builtin_amdgcn_s_barrier()
; template <class Epi, class Sched, bool ALIGN_EPI = false, bool SP2 = false>
; __device__ __forceinline__ void gemm_phase(PG8_LAS unsigned char* lds, const Gemm g, const Sched& S, const Epi& E) {
;     ...
;             if constexpr (SP2) {
;             PG8_LDB(B0, 0, 0); PG8_LDB(B1, 0, 1); PG8_SCHED; PG8_LDA(At, 0, 0); PG8_STAGE(PG8_SA(1, 1), a1 + hA, voffA);
;             PG8_WAIT_V(8); PG8_WAIT_L(0); PG8_BAR; PG8_MMA(0, 0, At, B0); PG8_MMA(0, 1, At, B1); PG8_BAR; PG8_SCHED;
;             PG8_LDA(At, 0, 1); PG8_STAGE(PG8_SB(0, 0), b2, voffB); PG8_STAGE(PG8_SB(0, 1), b2 + hB, voffB); PG8_STAGE(PG8_SA(0, 0), a2, voffA);
;             PG8_WAIT_V(8); PG8_WAIT_L(0); PG8_BAR; PG8_MMA(1, 0, At, B0); PG8_MMA(1, 1, At, B1); PG8_BAR; PG8_SCHED;
;             PG8_LDB(B0, 1, 0); PG8_LDB(B1, 1, 1); PG8_SCHED; PG8_LDA(At, 1, 0); PG8_STAGE(PG8_SA(0, 1), a2 + hA, voffA);
;             PG8_WAIT_V(8); PG8_WAIT_L(0); PG8_BAR; PG8_MMA(0, 0, At, B0); PG8_MMA(0, 1, At, B1); PG8_BAR; PG8_SCHED;
;             PG8_LDA(At, 1, 1); PG8_STAGE(PG8_SB(1, 0), b3, voffB); PG8_STAGE(PG8_SB(1, 1), b3 + hB, voffB); PG8_STAGE(PG8_SA(1, 0), a3, voffA);
;             PG8_WAIT_V(8); PG8_WAIT_L(0); PG8_BAR; PG8_MMA(1, 0, At, B0); PG8_MMA(1, 1, At, B1); PG8_BAR; PG8_SCHED;
	s_setprio 1
	s_waitcnt lgkmcnt(0)
	v_mfma_f32_16x16x32_bf16 v[60:63], v[146:149], v[184:187], v[60:63]
	v_mfma_f32_16x16x32_bf16 v[56:59], v[154:157], v[184:187], v[56:59]
	v_mfma_f32_16x16x32_bf16 v[44:47], v[146:149], v[192:195], v[44:47]
	v_mfma_f32_16x16x32_bf16 v[40:43], v[154:157], v[192:195], v[40:43]
	v_mfma_f32_16x16x32_bf16 v[28:31], v[146:149], v[204:207], v[28:31]
	v_mfma_f32_16x16x32_bf16 v[24:27], v[154:157], v[204:207], v[24:27]
	v_mfma_f32_16x16x32_bf16 v[12:15], v[146:149], v[212:215], v[12:15]
	v_mfma_f32_16x16x32_bf16 v[8:11], v[154:157], v[212:215], v[8:11]
	v_mfma_f32_16x16x32_bf16 v[60:63], v[150:153], v[188:191], v[60:63]
	v_mfma_f32_16x16x32_bf16 v[56:59], v[158:161], v[188:191], v[56:59]
	v_mfma_f32_16x16x32_bf16 v[44:47], v[150:153], v[200:203], v[44:47]
	v_mfma_f32_16x16x32_bf16 v[40:43], v[158:161], v[200:203], v[40:43]
	v_mfma_f32_16x16x32_bf16 v[28:31], v[150:153], v[208:211], v[28:31]
	v_mfma_f32_16x16x32_bf16 v[24:27], v[158:161], v[208:211], v[24:27]
	v_mfma_f32_16x16x32_bf16 v[12:15], v[150:153], v[216:219], v[12:15]
	v_mfma_f32_16x16x32_bf16 v[8:11], v[158:161], v[216:219], v[8:11]
	s_setprio 0
	s_setprio 1
	v_mfma_f32_16x16x32_bf16 v[52:55], v[162:165], v[184:187], v[52:55]
	v_mfma_f32_16x16x32_bf16 v[48:51], v[174:177], v[184:187], v[48:51]
	v_mfma_f32_16x16x32_bf16 v[36:39], v[162:165], v[192:195], v[36:39]
	v_mfma_f32_16x16x32_bf16 v[32:35], v[174:177], v[192:195], v[32:35]
	v_mfma_f32_16x16x32_bf16 v[20:23], v[162:165], v[204:207], v[20:23]
	v_mfma_f32_16x16x32_bf16 v[16:19], v[174:177], v[204:207], v[16:19]
	v_mfma_f32_16x16x32_bf16 v[4:7], v[162:165], v[212:215], v[4:7]
	v_mfma_f32_16x16x32_bf16 v[0:3], v[174:177], v[212:215], v[0:3]
	v_mfma_f32_16x16x32_bf16 v[52:55], v[166:169], v[188:191], v[52:55]
	v_mfma_f32_16x16x32_bf16 v[48:51], v[180:183], v[188:191], v[48:51]
	v_mfma_f32_16x16x32_bf16 v[36:39], v[166:169], v[200:203], v[36:39]
	v_mfma_f32_16x16x32_bf16 v[32:35], v[180:183], v[200:203], v[32:35]
	v_mfma_f32_16x16x32_bf16 v[20:23], v[166:169], v[208:211], v[20:23]
	v_mfma_f32_16x16x32_bf16 v[16:19], v[180:183], v[208:211], v[16:19]
	v_mfma_f32_16x16x32_bf16 v[4:7], v[166:169], v[216:219], v[4:7]
	v_mfma_f32_16x16x32_bf16 v[0:3], v[180:183], v[216:219], v[0:3]
	s_setprio 0
	s_barrier
	s_add_i32 s34, 0, 0x18000
	v_add_u32_e32 v145, s34, v143
	s_add_i32 s35, 0, 0x1c000
	ds_read_b128 v[146:149], v145
	ds_read_b128 v[150:153], v145 offset:1024
	ds_read_b128 v[154:157], v145 offset:2048
	ds_read_b128 v[158:161], v145 offset:3072
	v_add_u32_e32 v145, s35, v143
	ds_read_b128 v[162:165], v145
	ds_read_b128 v[166:169], v145 offset:1024
	ds_read_b128 v[174:177], v145 offset:2048
	ds_read_b128 v[180:183], v145 offset:3072
	s_add_u32 s30, s30, 0x40000
	s_addc_u32 s31, s31, 0
	s_mov_b32 m0, s45
	ds_read_b128 v[184:187], v144 offset:32768
	ds_read_b128 v[188:191], v144 offset:33792
	ds_read_b128 v[192:195], v144 offset:34816
	ds_read_b128 v[200:203], v144 offset:35840
	ds_read_b128 v[204:207], v144 offset:36864
	ds_read_b128 v[208:211], v144 offset:37888
	ds_read_b128 v[212:215], v144 offset:38912
	ds_read_b128 v[216:219], v144 offset:39936
	global_load_lds_dwordx4 v134, s[30:31]
	s_mov_b32 m0, s46
	s_nop 0
	global_load_lds_dwordx4 v130, s[30:31]
	s_waitcnt vmcnt(8)
	s_waitcnt lgkmcnt(0)
	s_barrier
	s_setprio 1
	s_waitcnt lgkmcnt(0)
	v_mfma_f32_16x16x32_bf16 v[124:127], v[146:149], v[184:187], v[124:127]
	v_mfma_f32_16x16x32_bf16 v[120:123], v[154:157], v[184:187], v[120:123]
	v_mfma_f32_16x16x32_bf16 v[108:111], v[146:149], v[192:195], v[108:111]
	v_mfma_f32_16x16x32_bf16 v[104:107], v[154:157], v[192:195], v[104:107]
	v_mfma_f32_16x16x32_bf16 v[92:95], v[146:149], v[204:207], v[92:95]
	v_mfma_f32_16x16x32_bf16 v[88:91], v[154:157], v[204:207], v[88:91]
	v_mfma_f32_16x16x32_bf16 v[76:79], v[146:149], v[212:215], v[76:79]
	v_mfma_f32_16x16x32_bf16 v[72:75], v[154:157], v[212:215], v[72:75]
	v_mfma_f32_16x16x32_bf16 v[124:127], v[150:153], v[188:191], v[124:127]
	v_mfma_f32_16x16x32_bf16 v[120:123], v[158:161], v[188:191], v[120:123]
	v_mfma_f32_16x16x32_bf16 v[108:111], v[150:153], v[200:203], v[108:111]
	v_mfma_f32_16x16x32_bf16 v[104:107], v[158:161], v[200:203], v[104:107]
	v_mfma_f32_16x16x32_bf16 v[92:95], v[150:153], v[208:211], v[92:95]
	v_mfma_f32_16x16x32_bf16 v[88:91], v[158:161], v[208:211], v[88:91]
	v_mfma_f32_16x16x32_bf16 v[76:79], v[150:153], v[216:219], v[76:79]
	v_mfma_f32_16x16x32_bf16 v[72:75], v[158:161], v[216:219], v[72:75]
	s_setprio 0
	s_setprio 1
	v_mfma_f32_16x16x32_bf16 v[116:119], v[162:165], v[184:187], v[116:119]
	v_mfma_f32_16x16x32_bf16 v[112:115], v[174:177], v[184:187], v[112:115]
	v_mfma_f32_16x16x32_bf16 v[100:103], v[162:165], v[192:195], v[100:103]
	v_mfma_f32_16x16x32_bf16 v[96:99], v[174:177], v[192:195], v[96:99]
	v_mfma_f32_16x16x32_bf16 v[84:87], v[162:165], v[204:207], v[84:87]
	v_mfma_f32_16x16x32_bf16 v[80:83], v[174:177], v[204:207], v[80:83]
	v_mfma_f32_16x16x32_bf16 v[68:71], v[162:165], v[212:215], v[68:71]
	v_mfma_f32_16x16x32_bf16 v[64:67], v[174:177], v[212:215], v[64:67]
	v_mfma_f32_16x16x32_bf16 v[116:119], v[166:169], v[188:191], v[116:119]
	v_mfma_f32_16x16x32_bf16 v[112:115], v[180:183], v[188:191], v[112:115]
	v_mfma_f32_16x16x32_bf16 v[100:103], v[166:169], v[200:203], v[100:103]
	v_mfma_f32_16x16x32_bf16 v[96:99], v[180:183], v[200:203], v[96:99]
	v_mfma_f32_16x16x32_bf16 v[84:87], v[166:169], v[208:211], v[84:87]
	v_mfma_f32_16x16x32_bf16 v[80:83], v[180:183], v[208:211], v[80:83]
	v_mfma_f32_16x16x32_bf16 v[68:71], v[166:169], v[216:219], v[68:71]
	v_mfma_f32_16x16x32_bf16 v[64:67], v[180:183], v[216:219], v[64:67]
	s_setprio 0
	s_barrier
; #define PG8_STAGE(bufoff, gbase, voff) do { _Pragma("unroll") for (int _i = 0; _i < 2; ++_i) \
;         __builtin_amdgcn_global_load_lds((const unsigned*)((const char*)(gbase) + (voff)[_i]), (PG8_LAS unsigned*)(lds + (bufoff) + ldsw + _i * 8192), 16, 0, 0); } while (0)
; #define PG8_LDA(dst, b, h) do { _Pragma("unroll") for (int m = 0; m < 4; ++m) _Pragma("unroll") for (int k = 0; k < 2; ++k) dst[m][k] = *(const PG8_LAS bf16x8*)(lds + PG8_SA(b, h) + aoff + m * 2048 + k * 1024); } while (0)
; #define PG8_LDB(dst, b, h) do { _Pragma("unroll") for (int n = 0; n < 2; ++n) _Pragma("unroll") for (int k = 0; k < 2; ++k) dst[n][k] = *(const PG8_LAS bf16x8*)(lds + PG8_SB(b, h) + boff + n * 2048 + k * 1024); } while (0)
; #define PG8_MMA(ai, bj, At, Bt) do { __builtin_amdgcn_s_setprio(1); _Pragma("unroll") for (int m = 0; m < 4; ++m) _Pragma("unroll") for (int n = 0; n < 2; ++n) _Pragma("unroll") for (int k = 0; k < 2; ++k) \
;         acc[ai][bj][m][n] = __builtin_amdgcn_mfma_f32_16x16x32_bf16(Bt[n][k], At[m][k], acc[ai][bj][m][n], 0, 0, 0); __builtin_amdgcn_s_setprio(0); } while (0)
; #define PG8_BAR __builtin_amdgcn_s_barrier()
; template <class Epi, class Sched, bool ALIGN_EPI = false, bool SP2 = false>
; __device__ __forceinline__ void gemm_phase(PG8_LAS unsigned char* lds, const Gemm g, const Sched& S, const Epi& E) {
;     ...
;             if constexpr (SP2) {
;             PG8_LDB(B0, 0, 0); PG8_LDB(B1, 0, 1); PG8_SCHED; PG8_LDA(At, 0, 0); PG8_STAGE(PG8_SA(1, 1), a1 + hA, voffA);
;             PG8_WAIT_V(8); PG8_WAIT_L(0); PG8_BAR; PG8_MMA(0, 0, At, B0); PG8_MMA(0, 1, At, B1); PG8_BAR; PG8_SCHED;
;             PG8_LDA(At, 0, 1); PG8_STAGE(PG8_SB(0, 0), b2, voffB); PG8_STAGE(PG8_SB(0, 1), b2 + hB, voffB); PG8_STAGE(PG8_SA(0, 0), a2, voffA);
;             PG8_WAIT_V(8); PG8_WAIT_L(0); PG8_BAR; PG8_MMA(1, 0, At, B0); PG8_MMA(1, 1, At, B1); PG8_BAR; PG8_SCHED;
;             PG8_LDB(B0, 1, 0); PG8_LDB(B1, 1, 1); PG8_SCHED; PG8_LDA(At, 1, 0); PG8_STAGE(PG8_SA(0, 1), a2 + hA, voffA);
;             PG8_WAIT_V(8); PG8_WAIT_L(0); PG8_BAR; PG8_MMA(0, 0, At, B0); PG8_MMA(0, 1, At, B1); PG8_BAR; PG8_SCHED;
;             PG8_LDA(At, 1, 1); PG8_STAGE(PG8_SB(1, 0), b3, voffB); PG8_STAGE(PG8_SB(1, 1), b3 + hB, voffB); PG8_STAGE(PG8_SA(1, 0), a3, voffA);
;             PG8_WAIT_V(8); PG8_WAIT_L(0); PG8_BAR; PG8_MMA(1, 0, At, B0); PG8_MMA(1, 1, At, B1); PG8_BAR; PG8_SCHED;
	s_add_i32 s30, s34, s40
	v_lshl_add_u64 v[140:141], v[140:141], 0, s[76:77]
	s_mov_b32 m0, s30
	ds_read_b128 v[184:187], v144 offset:49152
	ds_read_b128 v[188:191], v144 offset:50176
	ds_read_b128 v[192:195], v144 offset:51200
	ds_read_b128 v[200:203], v144 offset:52224
	ds_read_b128 v[204:207], v144 offset:53248
	ds_read_b128 v[208:211], v144 offset:54272
	ds_read_b128 v[212:215], v144 offset:55296
	ds_read_b128 v[216:219], v144 offset:56320
	global_load_lds_dwordx4 v[140:141], off
	s_add_i32 m0, s30, 0x2000
	s_add_u32 s18, s18, 0x40080
	v_lshl_add_u64 v[140:141], v[170:171], 0, s[76:77]
	s_addc_u32 s19, s19, 0
	s_add_i32 s30, s35, s40
	global_load_lds_dwordx4 v[140:141], off
	s_mov_b32 m0, s30
	s_nop 0
	global_load_lds_dwordx4 v132, s[18:19]
	s_add_i32 m0, s30, 0x2000
	s_nop 0
	global_load_lds_dwordx4 v128, s[18:19]
	v_lshl_add_u64 v[140:141], v[220:221], 0, s[76:77]
	s_mov_b32 m0, s47
	s_nop 0
	global_load_lds_dwordx4 v[140:141], off
	v_lshl_add_u64 v[140:141], v[222:223], 0, s[76:77]
	s_mov_b32 m0, s48
	s_nop 0
	global_load_lds_dwordx4 v[140:141], off
	s_waitcnt vmcnt(8)
	s_waitcnt lgkmcnt(0)
	s_barrier
	s_setprio 1
	s_waitcnt lgkmcnt(0)
	v_mfma_f32_16x16x32_bf16 v[60:63], v[146:149], v[184:187], v[60:63]
	v_mfma_f32_16x16x32_bf16 v[56:59], v[154:157], v[184:187], v[56:59]
	v_mfma_f32_16x16x32_bf16 v[44:47], v[146:149], v[192:195], v[44:47]
	v_mfma_f32_16x16x32_bf16 v[40:43], v[154:157], v[192:195], v[40:43]
	v_mfma_f32_16x16x32_bf16 v[28:31], v[146:149], v[204:207], v[28:31]
	v_mfma_f32_16x16x32_bf16 v[24:27], v[154:157], v[204:207], v[24:27]
	v_mfma_f32_16x16x32_bf16 v[12:15], v[146:149], v[212:215], v[12:15]
	v_mfma_f32_16x16x32_bf16 v[8:11], v[154:157], v[212:215], v[8:11]
	v_mfma_f32_16x16x32_bf16 v[60:63], v[150:153], v[188:191], v[60:63]
	v_mfma_f32_16x16x32_bf16 v[56:59], v[158:161], v[188:191], v[56:59]
	v_mfma_f32_16x16x32_bf16 v[44:47], v[150:153], v[200:203], v[44:47]
	v_mfma_f32_16x16x32_bf16 v[40:43], v[158:161], v[200:203], v[40:43]
	v_mfma_f32_16x16x32_bf16 v[28:31], v[150:153], v[208:211], v[28:31]
	v_mfma_f32_16x16x32_bf16 v[24:27], v[158:161], v[208:211], v[24:27]
	v_mfma_f32_16x16x32_bf16 v[12:15], v[150:153], v[216:219], v[12:15]
	v_mfma_f32_16x16x32_bf16 v[8:11], v[158:161], v[216:219], v[8:11]
	s_setprio 0
	s_setprio 1
	v_mfma_f32_16x16x32_bf16 v[52:55], v[162:165], v[184:187], v[52:55]
	v_mfma_f32_16x16x32_bf16 v[48:51], v[174:177], v[184:187], v[48:51]
	v_mfma_f32_16x16x32_bf16 v[36:39], v[162:165], v[192:195], v[36:39]
	v_mfma_f32_16x16x32_bf16 v[32:35], v[174:177], v[192:195], v[32:35]
	v_mfma_f32_16x16x32_bf16 v[20:23], v[162:165], v[204:207], v[20:23]
	v_mfma_f32_16x16x32_bf16 v[16:19], v[174:177], v[204:207], v[16:19]
	v_mfma_f32_16x16x32_bf16 v[4:7], v[162:165], v[212:215], v[4:7]
	v_mfma_f32_16x16x32_bf16 v[0:3], v[174:177], v[212:215], v[0:3]
	v_mfma_f32_16x16x32_bf16 v[52:55], v[166:169], v[188:191], v[52:55]
	v_mfma_f32_16x16x32_bf16 v[48:51], v[180:183], v[188:191], v[48:51]
	v_mfma_f32_16x16x32_bf16 v[36:39], v[166:169], v[200:203], v[36:39]
	v_mfma_f32_16x16x32_bf16 v[32:35], v[180:183], v[200:203], v[32:35]
	v_mfma_f32_16x16x32_bf16 v[20:23], v[166:169], v[208:211], v[20:23]
	v_mfma_f32_16x16x32_bf16 v[16:19], v[180:183], v[208:211], v[16:19]
	v_mfma_f32_16x16x32_bf16 v[4:7], v[166:169], v[216:219], v[4:7]
	v_mfma_f32_16x16x32_bf16 v[0:3], v[180:183], v[216:219], v[0:3]
	s_setprio 0
	s_barrier
	s_add_i32 s79, s79, 2
	s_add_u32 s0, s0, 0x100
	s_addc_u32 s1, s1, 0
	s_add_u32 s74, s74, 0x100
	s_addc_u32 s75, s75, 0
	s_cmp_gt_u32 s79, 13
	s_cbranch_scc0 .LBB0_912
	v_readlane_b32 s58, v255, 19
	v_readlane_b32 s74, v255, 21
	s_and_b64 vcc, exec, s[8:9]
	v_readlane_b32 s59, v255, 20
	v_readlane_b32 s75, v255, 22
	v_readlane_b32 s79, v255, 23
	s_cbranch_vccz .LBB0_915
	s_barrier

; #define PG8_STAGE(bufoff, gbase, voff) do { _Pragma("unroll") for (int _i = 0; _i < 2; ++_i) \
;         __builtin_amdgcn_global_load_lds((const unsigned*)((const char*)(gbase) + (voff)[_i]), (PG8_LAS unsigned*)(lds + (bufoff) + ldsw + _i * 8192), 16, 0, 0); } while (0)
; #define PG8_WAIT_V(n) asm volatile("s_waitcnt vmcnt(" #n ")" ::: "memory")
; #define PG8_BAR __builtin_amdgcn_s_barrier()
; template <class Epi, class Sched, bool ALIGN_EPI = false, bool SP2 = false>
; __device__ __forceinline__ void gemm_phase(PG8_LAS unsigned char* lds, const Gemm g, const Sched& S, const Epi& E) {
;     ...
;         PG8_STAGE(PG8_SB(0, 0), cB, voffB); PG8_STAGE(PG8_SB(0, 1), cB + hB, voffB); PG8_STAGE(PG8_SA(0, 0), cA, voffA); PG8_STAGE(PG8_SA(0, 1), cA + hA, voffA);
;         if (wr == 1) PG8_BAR;
;         PG8_WAIT_V(2); PG8_BAR;
;         PG8_STAGE(PG8_SB(1, 0), cB + kstep, voffB); PG8_STAGE(PG8_SA(1, 0), cA + kstep, voffA); PG8_STAGE(PG8_SB(1, 1), cB + hB + kstep, voffB);
;         PG8_WAIT_V(6); PG8_BAR;
.LBB0_974:
	v_bfe_u32 v16, v6, 4, 2
	v_and_b32_e32 v7, 15, v6
	v_lshlrev_b32_e32 v17, 4, v16
	v_lshlrev_b32_e32 v6, 2, v6
	v_readlane_b32 s18, v253, 59
	v_lshl_or_b32 v131, s8, 6, v7
	v_lshl_or_b32 v7, v7, 6, v17
	s_lshl_b32 s8, s8, 13
	v_and_b32_e32 v6, 32, v6
	s_lshl_b32 s7, s7, 5
	v_readlane_b32 s19, v253, 60
	v_bitop3_b32 v17, v7, s8, v6 bitop3:0xde
	s_and_b32 s8, s7, 0x60
	v_lshl_add_u64 v[8:9], s[18:19], 0, v[172:173]
	v_mov_b32_e32 v129, v173
	v_readlane_b32 s16, v253, 55
	s_lshl_b32 s7, s8, 7
	v_lshl_add_u64 v[10:11], s[18:19], 0, v[128:129]
	v_readlane_b32 s17, v253, 56
	v_bitop3_b32 v140, v7, s7, v6 bitop3:0xde
	s_add_i32 m0, s43, 0x18000
	v_lshl_add_u64 v[6:7], v[8:9], 0, s[76:77]
	v_lshl_add_u64 v[12:13], s[16:17], 0, v[172:173]
	s_waitcnt vmcnt(2)
	s_barrier
	global_load_lds_dwordx4 v[6:7], off
	v_lshl_add_u64 v[6:7], v[10:11], 0, s[76:77]
	s_add_i32 m0, s43, 0x1a000
	s_add_i32 s47, s43, 0x8000
	v_lshl_add_u64 v[14:15], s[16:17], 0, v[128:129]
	global_load_lds_dwordx4 v[6:7], off
	v_lshl_add_u64 v[6:7], v[12:13], 0, s[76:77]
	s_mov_b32 m0, s47
	s_add_i32 s48, s43, 0xa000
	v_readlane_b32 s10, v253, 61
	global_load_lds_dwordx4 v[6:7], off
	v_lshl_add_u64 v[6:7], v[14:15], 0, s[76:77]
	s_mov_b32 m0, s48
	v_readlane_b32 s11, v253, 62
	global_load_lds_dwordx4 v[6:7], off
	s_add_i32 m0, s43, 0x1c000
	v_lshl_add_u64 v[6:7], s[10:11], 0, v[172:173]
	global_load_lds_dwordx4 v[6:7], off
	s_add_i32 m0, s43, 0x1e000
	s_cmpk_lt_u32 s6, 0x100
	global_load_lds_dwordx4 v128, s[10:11]
	v_lshlrev_b32_e32 v6, 16, v3
	v_and_b32_e32 v6, 0xfffe0000, v6
	v_lshl_add_u32 v4, v4, 13, v6
	v_and_b32_e32 v3, 1, v3
	v_lshl_or_b32 v3, v3, 6, v4
	v_lshl_add_u32 v132, v5, 1, v3
	v_lshlrev_b32_e32 v3, 16, v0
	v_and_b32_e32 v3, 0xfffe0000, v3
	s_waitcnt vmcnt(6)
	v_lshl_add_u32 v1, v1, 13, v3
	v_and_b32_e32 v0, 1, v0
	v_lshl_or_b32 v130, v16, 2, s8
	v_lshl_or_b32 v0, v0, 6, v1
	v_readlane_b32 s8, v254, 39
	s_cselect_b64 s[6:7], -1, 0
	v_mov_b32_e32 v133, v173
	v_lshl_add_u32 v134, v2, 1, v0
	v_mov_b32_e32 v135, v173
	s_mov_b32 s49, 0
	v_add_u32_e32 v141, 0, v17
	v_readlane_b32 s50, v253, 36
	s_mov_b32 s51, s8
	s_barrier
	v_readlane_b32 s9, v254, 40
	s_branch .LBB0_977

; #define PG8_STAGE(bufoff, gbase, voff) do { _Pragma("unroll") for (int _i = 0; _i < 2; ++_i) \
;         __builtin_amdgcn_global_load_lds((const unsigned*)((const char*)(gbase) + (voff)[_i]), (PG8_LAS unsigned*)(lds + (bufoff) + ldsw + _i * 8192), 16, 0, 0); } while (0)
; #define PG8_LDA(dst, b, h) do { _Pragma("unroll") for (int m = 0; m < 4; ++m) _Pragma("unroll") for (int k = 0; k < 2; ++k) dst[m][k] = *(const PG8_LAS bf16x8*)(lds + PG8_SA(b, h) + aoff + m * 2048 + k * 1024); } while (0)
; #define PG8_LDB(dst, b, h) do { _Pragma("unroll") for (int n = 0; n < 2; ++n) _Pragma("unroll") for (int k = 0; k < 2; ++k) dst[n][k] = *(const PG8_LAS bf16x8*)(lds + PG8_SB(b, h) + boff + n * 2048 + k * 1024); } while (0)
; #define PG8_MMA(ai, bj, At, Bt) do { __builtin_amdgcn_s_setprio(1); _Pragma("unroll") for (int m = 0; m < 4; ++m) _Pragma("unroll") for (int n = 0; n < 2; ++n) _Pragma("unroll") for (int k = 0; k < 2; ++k) \
;         acc[ai][bj][m][n] = __builtin_amdgcn_mfma_f32_16x16x32_bf16(Bt[n][k], At[m][k], acc[ai][bj][m][n], 0, 0, 0); __builtin_amdgcn_s_setprio(0); } while (0)
; #define PG8_BAR __builtin_amdgcn_s_barrier()
; template <class Epi, class Sched, bool ALIGN_EPI = false, bool SP2 = false>
; __device__ __forceinline__ void gemm_phase(PG8_LAS unsigned char* lds, const Gemm g, const Sched& S, const Epi& E) {
;     ...
;             if constexpr (SP2) {
;             PG8_LDB(B0, 0, 0); PG8_LDB(B1, 0, 1); PG8_SCHED; PG8_LDA(At, 0, 0); PG8_STAGE(PG8_SA(1, 1), a1 + hA, voffA);
;             PG8_WAIT_V(8); PG8_WAIT_L(0); PG8_BAR; PG8_MMA(0, 0, At, B0); PG8_MMA(0, 1, At, B1); PG8_BAR; PG8_SCHED;
;             PG8_LDA(At, 0, 1); PG8_STAGE(PG8_SB(0, 0), b2, voffB); PG8_STAGE(PG8_SB(0, 1), b2 + hB, voffB); PG8_STAGE(PG8_SA(0, 0), a2, voffA);
;             PG8_WAIT_V(8); PG8_WAIT_L(0); PG8_BAR; PG8_MMA(1, 0, At, B0); PG8_MMA(1, 1, At, B1); PG8_BAR; PG8_SCHED;
;             PG8_LDB(B0, 1, 0); PG8_LDB(B1, 1, 1); PG8_SCHED; PG8_LDA(At, 1, 0); PG8_STAGE(PG8_SA(0, 1), a2 + hA, voffA);
;             PG8_WAIT_V(8); PG8_WAIT_L(0); PG8_BAR; PG8_MMA(0, 0, At, B0); PG8_MMA(0, 1, At, B1); PG8_BAR; PG8_SCHED;
;             PG8_LDA(At, 1, 1); PG8_STAGE(PG8_SB(1, 0), b3, voffB); PG8_STAGE(PG8_SB(1, 1), b3 + hB, voffB); PG8_STAGE(PG8_SA(1, 0), a3, voffA);
;             PG8_WAIT_V(8); PG8_WAIT_L(0); PG8_BAR; PG8_MMA(1, 0, At, B0); PG8_MMA(1, 1, At, B1); PG8_BAR; PG8_SCHED;
.LBB0_984:
	s_add_u32 s18, s16, 0xfff00080
	s_addc_u32 s19, s17, -1
	s_add_i32 s34, 0, 0x10000
	s_cmp_eq_u32 s75, 60
	s_cselect_b32 s31, s11, s19
	s_cselect_b32 s30, s68, s18
	s_cselect_b32 s19, s9, s74
	s_cselect_b32 s18, s70, s71
	s_add_i32 s52, 0, 0x14000
	v_add_u32_e32 v150, s34, v140
	v_add_u32_e32 v166, s52, v140
	ds_read_b128 v[136:139], v150
	ds_read_b128 v[142:145], v150 offset:1024
	ds_read_b128 v[146:149], v150 offset:2048
	ds_read_b128 v[150:153], v150 offset:3072
	ds_read_b128 v[154:157], v166
	ds_read_b128 v[158:161], v166 offset:1024
	ds_read_b128 v[162:165], v166 offset:2048
	ds_read_b128 v[166:169], v166 offset:3072
	s_add_i32 m0, s43, 0xc000
	ds_read_b128 v[174:177], v141
	ds_read_b128 v[180:183], v141 offset:1024
	ds_read_b128 v[184:187], v141 offset:2048
	ds_read_b128 v[188:191], v141 offset:3072
	ds_read_b128 v[192:195], v141 offset:4096
	ds_read_b128 v[200:203], v141 offset:5120
	ds_read_b128 v[204:207], v141 offset:6144
	ds_read_b128 v[208:211], v141 offset:7168
	global_load_lds_dwordx4 v132, s[16:17]
	s_add_i32 m0, s43, 0xe000
	s_nop 0
	global_load_lds_dwordx4 v134, s[16:17]
	s_waitcnt vmcnt(8)
	s_waitcnt lgkmcnt(0)
	s_barrier
	s_setprio 1
	s_waitcnt lgkmcnt(0)
	v_mfma_f32_16x16x32_bf16 v[124:127], v[136:139], v[174:177], v[124:127]
	v_mfma_f32_16x16x32_bf16 v[120:123], v[146:149], v[174:177], v[120:123]
	v_mfma_f32_16x16x32_bf16 v[108:111], v[136:139], v[184:187], v[108:111]
	v_mfma_f32_16x16x32_bf16 v[104:107], v[146:149], v[184:187], v[104:107]
	v_mfma_f32_16x16x32_bf16 v[92:95], v[136:139], v[192:195], v[92:95]
	v_mfma_f32_16x16x32_bf16 v[88:91], v[146:149], v[192:195], v[88:91]
	v_mfma_f32_16x16x32_bf16 v[76:79], v[136:139], v[204:207], v[76:79]
	v_mfma_f32_16x16x32_bf16 v[72:75], v[146:149], v[204:207], v[72:75]
	v_mfma_f32_16x16x32_bf16 v[124:127], v[142:145], v[180:183], v[124:127]
	v_mfma_f32_16x16x32_bf16 v[120:123], v[150:153], v[180:183], v[120:123]
	v_mfma_f32_16x16x32_bf16 v[108:111], v[142:145], v[188:191], v[108:111]
	v_mfma_f32_16x16x32_bf16 v[104:107], v[150:153], v[188:191], v[104:107]
	v_mfma_f32_16x16x32_bf16 v[92:95], v[142:145], v[200:203], v[92:95]
	v_mfma_f32_16x16x32_bf16 v[88:91], v[150:153], v[200:203], v[88:91]
	v_mfma_f32_16x16x32_bf16 v[76:79], v[142:145], v[208:211], v[76:79]
	v_mfma_f32_16x16x32_bf16 v[72:75], v[150:153], v[208:211], v[72:75]
	s_setprio 0
	s_setprio 1
	v_mfma_f32_16x16x32_bf16 v[116:119], v[154:157], v[174:177], v[116:119]
	v_mfma_f32_16x16x32_bf16 v[112:115], v[162:165], v[174:177], v[112:115]
	v_mfma_f32_16x16x32_bf16 v[100:103], v[154:157], v[184:187], v[100:103]
	v_mfma_f32_16x16x32_bf16 v[96:99], v[162:165], v[184:187], v[96:99]
	v_mfma_f32_16x16x32_bf16 v[84:87], v[154:157], v[192:195], v[84:87]
	v_mfma_f32_16x16x32_bf16 v[80:83], v[162:165], v[192:195], v[80:83]
	v_mfma_f32_16x16x32_bf16 v[68:71], v[154:157], v[204:207], v[68:71]
	v_mfma_f32_16x16x32_bf16 v[64:67], v[162:165], v[204:207], v[64:67]
	v_mfma_f32_16x16x32_bf16 v[116:119], v[158:161], v[180:183], v[116:119]
	v_mfma_f32_16x16x32_bf16 v[112:115], v[166:169], v[180:183], v[112:115]
	v_mfma_f32_16x16x32_bf16 v[100:103], v[158:161], v[188:191], v[100:103]
	v_mfma_f32_16x16x32_bf16 v[96:99], v[166:169], v[188:191], v[96:99]
	v_mfma_f32_16x16x32_bf16 v[84:87], v[158:161], v[200:203], v[84:87]
	v_mfma_f32_16x16x32_bf16 v[80:83], v[166:169], v[200:203], v[80:83]
	v_mfma_f32_16x16x32_bf16 v[68:71], v[158:161], v[208:211], v[68:71]
	v_mfma_f32_16x16x32_bf16 v[64:67], v[166:169], v[208:211], v[64:67]
	s_setprio 0
	s_barrier
	s_add_i32 s34, s34, s42
	v_lshl_add_u64 v[170:171], s[18:19], 0, v[172:173]
	s_mov_b32 m0, s34
	ds_read_b128 v[174:177], v141 offset:16384
	ds_read_b128 v[180:183], v141 offset:17408
	ds_read_b128 v[184:187], v141 offset:18432
	ds_read_b128 v[188:191], v141 offset:19456
	ds_read_b128 v[192:195], v141 offset:20480
	ds_read_b128 v[200:203], v141 offset:21504
	ds_read_b128 v[204:207], v141 offset:22528
	ds_read_b128 v[208:211], v141 offset:23552
	global_load_lds_dwordx4 v[170:171], off
	s_add_i32 m0, s34, 0x2000
	s_add_u32 s34, s18, 0x100000
	v_lshl_add_u64 v[212:213], s[18:19], 0, v[128:129]
	s_addc_u32 s35, s19, 0
	s_add_i32 s52, s52, s42
	global_load_lds_dwordx4 v128, s[18:19]
	v_lshl_add_u64 v[214:215], s[34:35], 0, v[172:173]
	s_mov_b32 m0, s52
	v_lshl_add_u64 v[216:217], s[30:31], 0, v[128:129]
	global_load_lds_dwordx4 v[214:215], off
	s_add_i32 m0, s52, 0x2000
	s_nop 0
	global_load_lds_dwordx4 v128, s[34:35]
	v_lshl_add_u64 v[214:215], s[30:31], 0, v[172:173]
	s_mov_b32 m0, s43
	s_nop 0
	global_load_lds_dwordx4 v[214:215], off
	s_mov_b32 m0, s44
	s_nop 0
	global_load_lds_dwordx4 v128, s[30:31]
	s_waitcnt vmcnt(8)
	s_waitcnt lgkmcnt(0)
	s_barrier
; #define PG8_STAGE(bufoff, gbase, voff) do { _Pragma("unroll") for (int _i = 0; _i < 2; ++_i) \
;         __builtin_amdgcn_global_load_lds((const unsigned*)((const char*)(gbase) + (voff)[_i]), (PG8_LAS unsigned*)(lds + (bufoff) + ldsw + _i * 8192), 16, 0, 0); } while (0)
; #define PG8_LDA(dst, b, h) do { _Pragma("unroll") for (int m = 0; m < 4; ++m) _Pragma("unroll") for (int k = 0; k < 2; ++k) dst[m][k] = *(const PG8_LAS bf16x8*)(lds + PG8_SA(b, h) + aoff + m * 2048 + k * 1024); } while (0)
; #define PG8_LDB(dst, b, h) do { _Pragma("unroll") for (int n = 0; n < 2; ++n) _Pragma("unroll") for (int k = 0; k < 2; ++k) dst[n][k] = *(const PG8_LAS bf16x8*)(lds + PG8_SB(b, h) + boff + n * 2048 + k * 1024); } while (0)
; #define PG8_MMA(ai, bj, At, Bt) do { __builtin_amdgcn_s_setprio(1); _Pragma("unroll") for (int m = 0; m < 4; ++m) _Pragma("unroll") for (int n = 0; n < 2; ++n) _Pragma("unroll") for (int k = 0; k < 2; ++k) \
;         acc[ai][bj][m][n] = __builtin_amdgcn_mfma_f32_16x16x32_bf16(Bt[n][k], At[m][k], acc[ai][bj][m][n], 0, 0, 0); __builtin_amdgcn_s_setprio(0); } while (0)
; #define PG8_BAR __builtin_amdgcn_s_barrier()
; template <class Epi, class Sched, bool ALIGN_EPI = false, bool SP2 = false>
; __device__ __forceinline__ void gemm_phase(PG8_LAS unsigned char* lds, const Gemm g, const Sched& S, const Epi& E) {
;     ...
;             if constexpr (SP2) {
;             PG8_LDB(B0, 0, 0); PG8_LDB(B1, 0, 1); PG8_SCHED; PG8_LDA(At, 0, 0); PG8_STAGE(PG8_SA(1, 1), a1 + hA, voffA);
;             PG8_WAIT_V(8); PG8_WAIT_L(0); PG8_BAR; PG8_MMA(0, 0, At, B0); PG8_MMA(0, 1, At, B1); PG8_BAR; PG8_SCHED;
;             PG8_LDA(At, 0, 1); PG8_STAGE(PG8_SB(0, 0), b2, voffB); PG8_STAGE(PG8_SB(0, 1), b2 + hB, voffB); PG8_STAGE(PG8_SA(0, 0), a2, voffA);
;             PG8_WAIT_V(8); PG8_WAIT_L(0); PG8_BAR; PG8_MMA(1, 0, At, B0); PG8_MMA(1, 1, At, B1); PG8_BAR; PG8_SCHED;
;             PG8_LDB(B0, 1, 0); PG8_LDB(B1, 1, 1); PG8_SCHED; PG8_LDA(At, 1, 0); PG8_STAGE(PG8_SA(0, 1), a2 + hA, voffA);
;             PG8_WAIT_V(8); PG8_WAIT_L(0); PG8_BAR; PG8_MMA(0, 0, At, B0); PG8_MMA(0, 1, At, B1); PG8_BAR; PG8_SCHED;
;             PG8_LDA(At, 1, 1); PG8_STAGE(PG8_SB(1, 0), b3, voffB); PG8_STAGE(PG8_SB(1, 1), b3 + hB, voffB); PG8_STAGE(PG8_SA(1, 0), a3, voffA);
;             PG8_WAIT_V(8); PG8_WAIT_L(0); PG8_BAR; PG8_MMA(1, 0, At, B0); PG8_MMA(1, 1, At, B1); PG8_BAR; PG8_SCHED;
	s_setprio 1
	s_waitcnt lgkmcnt(0)
	v_mfma_f32_16x16x32_bf16 v[60:63], v[136:139], v[174:177], v[60:63]
	v_mfma_f32_16x16x32_bf16 v[56:59], v[146:149], v[174:177], v[56:59]
	v_mfma_f32_16x16x32_bf16 v[44:47], v[136:139], v[184:187], v[44:47]
	v_mfma_f32_16x16x32_bf16 v[40:43], v[146:149], v[184:187], v[40:43]
	v_mfma_f32_16x16x32_bf16 v[28:31], v[136:139], v[192:195], v[28:31]
	v_mfma_f32_16x16x32_bf16 v[24:27], v[146:149], v[192:195], v[24:27]
	v_mfma_f32_16x16x32_bf16 v[12:15], v[136:139], v[204:207], v[12:15]
	v_mfma_f32_16x16x32_bf16 v[8:11], v[146:149], v[204:207], v[8:11]
	v_mfma_f32_16x16x32_bf16 v[60:63], v[142:145], v[180:183], v[60:63]
	v_mfma_f32_16x16x32_bf16 v[56:59], v[150:153], v[180:183], v[56:59]
	v_mfma_f32_16x16x32_bf16 v[44:47], v[142:145], v[188:191], v[44:47]
	v_mfma_f32_16x16x32_bf16 v[40:43], v[150:153], v[188:191], v[40:43]
	v_mfma_f32_16x16x32_bf16 v[28:31], v[142:145], v[200:203], v[28:31]
	v_mfma_f32_16x16x32_bf16 v[24:27], v[150:153], v[200:203], v[24:27]
	v_mfma_f32_16x16x32_bf16 v[12:15], v[142:145], v[208:211], v[12:15]
	v_mfma_f32_16x16x32_bf16 v[8:11], v[150:153], v[208:211], v[8:11]
	s_setprio 0
	s_setprio 1
	v_mfma_f32_16x16x32_bf16 v[52:55], v[154:157], v[174:177], v[52:55]
	v_mfma_f32_16x16x32_bf16 v[48:51], v[162:165], v[174:177], v[48:51]
	v_mfma_f32_16x16x32_bf16 v[36:39], v[154:157], v[184:187], v[36:39]
	v_mfma_f32_16x16x32_bf16 v[32:35], v[162:165], v[184:187], v[32:35]
	v_mfma_f32_16x16x32_bf16 v[20:23], v[154:157], v[192:195], v[20:23]
	v_mfma_f32_16x16x32_bf16 v[16:19], v[162:165], v[192:195], v[16:19]
	v_mfma_f32_16x16x32_bf16 v[4:7], v[154:157], v[204:207], v[4:7]
	v_mfma_f32_16x16x32_bf16 v[0:3], v[162:165], v[204:207], v[0:3]
	v_mfma_f32_16x16x32_bf16 v[52:55], v[158:161], v[180:183], v[52:55]
	v_mfma_f32_16x16x32_bf16 v[48:51], v[166:169], v[180:183], v[48:51]
	v_mfma_f32_16x16x32_bf16 v[36:39], v[158:161], v[188:191], v[36:39]
	v_mfma_f32_16x16x32_bf16 v[32:35], v[166:169], v[188:191], v[32:35]
	v_mfma_f32_16x16x32_bf16 v[20:23], v[158:161], v[200:203], v[20:23]
	v_mfma_f32_16x16x32_bf16 v[16:19], v[166:169], v[200:203], v[16:19]
	v_mfma_f32_16x16x32_bf16 v[4:7], v[158:161], v[208:211], v[4:7]
	v_mfma_f32_16x16x32_bf16 v[0:3], v[166:169], v[208:211], v[0:3]
	s_setprio 0
	s_barrier
	s_add_i32 s34, 0, 0x18000
	s_add_i32 s35, 0, 0x1c000
	v_add_u32_e32 v150, s34, v140
	v_add_u32_e32 v166, s35, v140
	ds_read_b128 v[136:139], v150
	ds_read_b128 v[142:145], v150 offset:1024
	ds_read_b128 v[146:149], v150 offset:2048
	ds_read_b128 v[150:153], v150 offset:3072
	ds_read_b128 v[154:157], v166
	ds_read_b128 v[158:161], v166 offset:1024
	ds_read_b128 v[162:165], v166 offset:2048
	ds_read_b128 v[166:169], v166 offset:3072
	s_add_u32 s30, s30, 0x100000
	s_addc_u32 s31, s31, 0
	s_mov_b32 m0, s45
	v_lshl_add_u64 v[218:219], s[30:31], 0, v[172:173]
	ds_read_b128 v[174:177], v141 offset:32768
	ds_read_b128 v[180:183], v141 offset:33792
	ds_read_b128 v[184:187], v141 offset:34816
	ds_read_b128 v[188:191], v141 offset:35840
	ds_read_b128 v[192:195], v141 offset:36864
	ds_read_b128 v[200:203], v141 offset:37888
	ds_read_b128 v[204:207], v141 offset:38912
	ds_read_b128 v[208:211], v141 offset:39936
	global_load_lds_dwordx4 v[218:219], off
	s_mov_b32 m0, s46
	s_nop 0
	global_load_lds_dwordx4 v128, s[30:31]
	s_waitcnt vmcnt(8)
	s_waitcnt lgkmcnt(0)
	s_barrier
	s_setprio 1
	s_waitcnt lgkmcnt(0)
	v_mfma_f32_16x16x32_bf16 v[124:127], v[136:139], v[174:177], v[124:127]
	v_mfma_f32_16x16x32_bf16 v[120:123], v[146:149], v[174:177], v[120:123]
	v_mfma_f32_16x16x32_bf16 v[108:111], v[136:139], v[184:187], v[108:111]
	v_mfma_f32_16x16x32_bf16 v[104:107], v[146:149], v[184:187], v[104:107]
	v_mfma_f32_16x16x32_bf16 v[92:95], v[136:139], v[192:195], v[92:95]
	v_mfma_f32_16x16x32_bf16 v[88:91], v[146:149], v[192:195], v[88:91]
	v_mfma_f32_16x16x32_bf16 v[76:79], v[136:139], v[204:207], v[76:79]
	v_mfma_f32_16x16x32_bf16 v[72:75], v[146:149], v[204:207], v[72:75]
	v_mfma_f32_16x16x32_bf16 v[124:127], v[142:145], v[180:183], v[124:127]
	v_mfma_f32_16x16x32_bf16 v[120:123], v[150:153], v[180:183], v[120:123]
	v_mfma_f32_16x16x32_bf16 v[108:111], v[142:145], v[188:191], v[108:111]
	v_mfma_f32_16x16x32_bf16 v[104:107], v[150:153], v[188:191], v[104:107]
	v_mfma_f32_16x16x32_bf16 v[92:95], v[142:145], v[200:203], v[92:95]
	v_mfma_f32_16x16x32_bf16 v[88:91], v[150:153], v[200:203], v[88:91]
	v_mfma_f32_16x16x32_bf16 v[76:79], v[142:145], v[208:211], v[76:79]
	v_mfma_f32_16x16x32_bf16 v[72:75], v[150:153], v[208:211], v[72:75]
	s_setprio 0
	s_setprio 1
	v_mfma_f32_16x16x32_bf16 v[116:119], v[154:157], v[174:177], v[116:119]
	v_mfma_f32_16x16x32_bf16 v[112:115], v[162:165], v[174:177], v[112:115]
	v_mfma_f32_16x16x32_bf16 v[100:103], v[154:157], v[184:187], v[100:103]
	v_mfma_f32_16x16x32_bf16 v[96:99], v[162:165], v[184:187], v[96:99]
	v_mfma_f32_16x16x32_bf16 v[84:87], v[154:157], v[192:195], v[84:87]
	v_mfma_f32_16x16x32_bf16 v[80:83], v[162:165], v[192:195], v[80:83]
	v_mfma_f32_16x16x32_bf16 v[68:71], v[154:157], v[204:207], v[68:71]
	v_mfma_f32_16x16x32_bf16 v[64:67], v[162:165], v[204:207], v[64:67]
	v_mfma_f32_16x16x32_bf16 v[116:119], v[158:161], v[180:183], v[116:119]
	v_mfma_f32_16x16x32_bf16 v[112:115], v[166:169], v[180:183], v[112:115]
	v_mfma_f32_16x16x32_bf16 v[100:103], v[158:161], v[188:191], v[100:103]
	v_mfma_f32_16x16x32_bf16 v[96:99], v[166:169], v[188:191], v[96:99]
	v_mfma_f32_16x16x32_bf16 v[84:87], v[158:161], v[200:203], v[84:87]
	v_mfma_f32_16x16x32_bf16 v[80:83], v[166:169], v[200:203], v[80:83]
	v_mfma_f32_16x16x32_bf16 v[68:71], v[158:161], v[208:211], v[68:71]
	v_mfma_f32_16x16x32_bf16 v[64:67], v[166:169], v[208:211], v[64:67]
	s_setprio 0
	s_barrier
; #define PG8_STAGE(bufoff, gbase, voff) do { _Pragma("unroll") for (int _i = 0; _i < 2; ++_i) \
;         __builtin_amdgcn_global_load_lds((const unsigned*)((const char*)(gbase) + (voff)[_i]), (PG8_LAS unsigned*)(lds + (bufoff) + ldsw + _i * 8192), 16, 0, 0); } while (0)
; #define PG8_LDA(dst, b, h) do { _Pragma("unroll") for (int m = 0; m < 4; ++m) _Pragma("unroll") for (int k = 0; k < 2; ++k) dst[m][k] = *(const PG8_LAS bf16x8*)(lds + PG8_SA(b, h) + aoff + m * 2048 + k * 1024); } while (0)
; #define PG8_LDB(dst, b, h) do { _Pragma("unroll") for (int n = 0; n < 2; ++n) _Pragma("unroll") for (int k = 0; k < 2; ++k) dst[n][k] = *(const PG8_LAS bf16x8*)(lds + PG8_SB(b, h) + boff + n * 2048 + k * 1024); } while (0)
; #define PG8_MMA(ai, bj, At, Bt) do { __builtin_amdgcn_s_setprio(1); _Pragma("unroll") for (int m = 0; m < 4; ++m) _Pragma("unroll") for (int n = 0; n < 2; ++n) _Pragma("unroll") for (int k = 0; k < 2; ++k) \
;         acc[ai][bj][m][n] = __builtin_amdgcn_mfma_f32_16x16x32_bf16(Bt[n][k], At[m][k], acc[ai][bj][m][n], 0, 0, 0); __builtin_amdgcn_s_setprio(0); } while (0)
; #define PG8_BAR __builtin_amdgcn_s_barrier()
; template <class Epi, class Sched, bool ALIGN_EPI = false, bool SP2 = false>
; __device__ __forceinline__ void gemm_phase(PG8_LAS unsigned char* lds, const Gemm g, const Sched& S, const Epi& E) {
;     ...
;             if constexpr (SP2) {
;             PG8_LDB(B0, 0, 0); PG8_LDB(B1, 0, 1); PG8_SCHED; PG8_LDA(At, 0, 0); PG8_STAGE(PG8_SA(1, 1), a1 + hA, voffA);
;             PG8_WAIT_V(8); PG8_WAIT_L(0); PG8_BAR; PG8_MMA(0, 0, At, B0); PG8_MMA(0, 1, At, B1); PG8_BAR; PG8_SCHED;
;             PG8_LDA(At, 0, 1); PG8_STAGE(PG8_SB(0, 0), b2, voffB); PG8_STAGE(PG8_SB(0, 1), b2 + hB, voffB); PG8_STAGE(PG8_SA(0, 0), a2, voffA);
;             PG8_WAIT_V(8); PG8_WAIT_L(0); PG8_BAR; PG8_MMA(1, 0, At, B0); PG8_MMA(1, 1, At, B1); PG8_BAR; PG8_SCHED;
;             PG8_LDB(B0, 1, 0); PG8_LDB(B1, 1, 1); PG8_SCHED; PG8_LDA(At, 1, 0); PG8_STAGE(PG8_SA(0, 1), a2 + hA, voffA);
;             PG8_WAIT_V(8); PG8_WAIT_L(0); PG8_BAR; PG8_MMA(0, 0, At, B0); PG8_MMA(0, 1, At, B1); PG8_BAR; PG8_SCHED;
;             PG8_LDA(At, 1, 1); PG8_STAGE(PG8_SB(1, 0), b3, voffB); PG8_STAGE(PG8_SB(1, 1), b3 + hB, voffB); PG8_STAGE(PG8_SA(1, 0), a3, voffA);
;             PG8_WAIT_V(8); PG8_WAIT_L(0); PG8_BAR; PG8_MMA(1, 0, At, B0); PG8_MMA(1, 1, At, B1); PG8_BAR; PG8_SCHED;
	s_add_i32 s30, s34, s42
	v_lshl_add_u64 v[170:171], v[170:171], 0, s[76:77]
	s_mov_b32 m0, s30
	ds_read_b128 v[174:177], v141 offset:49152
	ds_read_b128 v[180:183], v141 offset:50176
	ds_read_b128 v[184:187], v141 offset:51200
	ds_read_b128 v[188:191], v141 offset:52224
	ds_read_b128 v[192:195], v141 offset:53248
	ds_read_b128 v[200:203], v141 offset:54272
	ds_read_b128 v[204:207], v141 offset:55296
	ds_read_b128 v[208:211], v141 offset:56320
	global_load_lds_dwordx4 v[170:171], off
	s_add_i32 m0, s30, 0x2000
	s_add_u32 s18, s18, 0x100080
	v_lshl_add_u64 v[170:171], v[212:213], 0, s[76:77]
	s_addc_u32 s19, s19, 0
	s_add_i32 s30, s35, s42
	global_load_lds_dwordx4 v[170:171], off
	v_lshl_add_u64 v[170:171], s[18:19], 0, v[172:173]
	s_mov_b32 m0, s30
	s_nop 0
	global_load_lds_dwordx4 v[170:171], off
	s_add_i32 m0, s30, 0x2000
	s_nop 0
	global_load_lds_dwordx4 v128, s[18:19]
	v_lshl_add_u64 v[170:171], v[214:215], 0, s[76:77]
	s_mov_b32 m0, s47
	s_nop 0
	global_load_lds_dwordx4 v[170:171], off
	v_lshl_add_u64 v[170:171], v[216:217], 0, s[76:77]
	s_mov_b32 m0, s48
	s_nop 0
	global_load_lds_dwordx4 v[170:171], off
	s_waitcnt vmcnt(8)
	s_waitcnt lgkmcnt(0)
	s_barrier
	s_setprio 1
	s_waitcnt lgkmcnt(0)
	v_mfma_f32_16x16x32_bf16 v[60:63], v[136:139], v[174:177], v[60:63]
	v_mfma_f32_16x16x32_bf16 v[56:59], v[146:149], v[174:177], v[56:59]
	v_mfma_f32_16x16x32_bf16 v[44:47], v[136:139], v[184:187], v[44:47]
	v_mfma_f32_16x16x32_bf16 v[40:43], v[146:149], v[184:187], v[40:43]
	v_mfma_f32_16x16x32_bf16 v[28:31], v[136:139], v[192:195], v[28:31]
	v_mfma_f32_16x16x32_bf16 v[24:27], v[146:149], v[192:195], v[24:27]
	v_mfma_f32_16x16x32_bf16 v[12:15], v[136:139], v[204:207], v[12:15]
	v_mfma_f32_16x16x32_bf16 v[8:11], v[146:149], v[204:207], v[8:11]
	v_mfma_f32_16x16x32_bf16 v[60:63], v[142:145], v[180:183], v[60:63]
	v_mfma_f32_16x16x32_bf16 v[56:59], v[150:153], v[180:183], v[56:59]
	v_mfma_f32_16x16x32_bf16 v[44:47], v[142:145], v[188:191], v[44:47]
	v_mfma_f32_16x16x32_bf16 v[40:43], v[150:153], v[188:191], v[40:43]
	v_mfma_f32_16x16x32_bf16 v[28:31], v[142:145], v[200:203], v[28:31]
	v_mfma_f32_16x16x32_bf16 v[24:27], v[150:153], v[200:203], v[24:27]
	v_mfma_f32_16x16x32_bf16 v[12:15], v[142:145], v[208:211], v[12:15]
	v_mfma_f32_16x16x32_bf16 v[8:11], v[150:153], v[208:211], v[8:11]
	s_setprio 0
	s_setprio 1
	v_mfma_f32_16x16x32_bf16 v[52:55], v[154:157], v[174:177], v[52:55]
	v_mfma_f32_16x16x32_bf16 v[48:51], v[162:165], v[174:177], v[48:51]
	v_mfma_f32_16x16x32_bf16 v[36:39], v[154:157], v[184:187], v[36:39]
	v_mfma_f32_16x16x32_bf16 v[32:35], v[162:165], v[184:187], v[32:35]
	v_mfma_f32_16x16x32_bf16 v[20:23], v[154:157], v[192:195], v[20:23]
	v_mfma_f32_16x16x32_bf16 v[16:19], v[162:165], v[192:195], v[16:19]
	v_mfma_f32_16x16x32_bf16 v[4:7], v[154:157], v[204:207], v[4:7]
	v_mfma_f32_16x16x32_bf16 v[0:3], v[162:165], v[204:207], v[0:3]
	v_mfma_f32_16x16x32_bf16 v[52:55], v[158:161], v[180:183], v[52:55]
	v_mfma_f32_16x16x32_bf16 v[48:51], v[166:169], v[180:183], v[48:51]
	v_mfma_f32_16x16x32_bf16 v[36:39], v[158:161], v[188:191], v[36:39]
	v_mfma_f32_16x16x32_bf16 v[32:35], v[166:169], v[188:191], v[32:35]
	v_mfma_f32_16x16x32_bf16 v[20:23], v[158:161], v[200:203], v[20:23]
	v_mfma_f32_16x16x32_bf16 v[16:19], v[166:169], v[200:203], v[16:19]
	v_mfma_f32_16x16x32_bf16 v[4:7], v[158:161], v[208:211], v[4:7]
	v_mfma_f32_16x16x32_bf16 v[0:3], v[166:169], v[208:211], v[0:3]
	s_setprio 0
	s_barrier
	s_add_i32 s75, s75, 2
	s_add_u32 s16, s16, 0x100
	s_addc_u32 s17, s17, 0
	s_add_u32 s71, s71, 0x100
	s_addc_u32 s74, s74, 0
	s_cmp_gt_u32 s75, 61
	s_cbranch_scc0 .LBB0_984
	v_readlane_b32 s58, v255, 19
	v_readlane_b32 s74, v255, 21
	s_and_b64 vcc, exec, s[6:7]
	v_readlane_b32 s59, v255, 20
	v_readlane_b32 s75, v255, 22
	s_cbranch_vccz .LBB0_987
	s_barrier
